# code placement: every K-loop MFMA run starts on an 8-byte boundary (s_nop 0 ahead of the opening barrier where needed)
# baseline (speedup 1.0000x reference)
; #define PG8_STAGE(bufoff, gbase, voff) do { _Pragma("unroll") for (int _i = 0; _i < 2; ++_i) { \
;         const unsigned _m0 = ldsb + (unsigned)((bufoff) + _i * 8192); const char* _gb = (const char*)(gbase); \
;         asm volatile("s_mov_b32 m0, %0\n\ts_nop 0\n\tglobal_load_lds_dwordx4 %1, %2" :: "s"(_m0), "v"((voff)[_i]), "s"(_gb) : "m0", "memory"); } } while (0)
; #define PG8_LDA(dst, b, h) do { _Pragma("unroll") for (int m = 0; m < 4; ++m) _Pragma("unroll") for (int k = 0; k < 2; ++k) dst[m][k] = *(const LAS bf16x8*)(lds + PG8_SA(b, h) + aoff + m * 2048 + k * 1024); } while (0)
; #define PG8_LDB(dst, b, h) do { _Pragma("unroll") for (int n = 0; n < 2; ++n) _Pragma("unroll") for (int k = 0; k < 2; ++k) dst[n][k] = *(const LAS bf16x8*)(lds + PG8_SB(b, h) + boff + n * 2048 + k * 1024); } while (0)
; #define PG8_MMA(ai, bj, At, Bt) do { __builtin_amdgcn_s_setprio(1); _Pragma("unroll") for (int m = 0; m < 4; ++m) _Pragma("unroll") for (int n = 0; n < 2; ++n) _Pragma("unroll") for (int k = 0; k < 2; ++k) \
;         acc[ai][bj][m][n] = __builtin_amdgcn_mfma_f32_16x16x32_bf16(Bt[n][k], At[m][k], acc[ai][bj][m][n], 0, 0, 0); __builtin_amdgcn_s_setprio(0); } while (0)
; #define PG8_WAIT_V(n) asm volatile("s_waitcnt vmcnt(" #n ")" ::: "memory")
; #define PG8_WAIT_L(n) asm volatile("s_waitcnt lgkmcnt(" #n ")" ::: "memory")
; template <class Epi, bool ALIGN_EPI>
; __device__ __forceinline__ void gemm_phase(LAS unsigned char* lds, const Gemm g, const StaticOrder& S, const Epi& E) {
;     ...
;         for (int t = 0; t < nt; t += 2) {
;             const bool last = (t == nt - 2);
;             const char* a1 = cA + (size_t)(t + 1) * kstep;
;             const char* a2 = last ? nA : cA + (size_t)(t + 2) * kstep; const char* b2 = last ? nB : cB + (size_t)(t + 2) * kstep;
;             const char* a3 = a2 + kstep; const char* b3 = b2 + kstep;
;             PG8_LDB(B0, 0, 0); PG8_LDB(B1, 0, 1); PG8_SCHED; PG8_LDA(At, 0, 0); PG8_STAGE(PG8_SA(1, 1), a1 + hstepA, voffA);
;             PG8_WAIT_V(8); PG8_WAIT_L(0); PG8_BAR; PG8_MMA(0, 0, At, B0); PG8_MMA(0, 1, At, B1); PG8_BAR; PG8_SCHED;
;             PG8_LDA(At, 0, 1); PG8_STAGE(PG8_SB(0, 0), b2, voffB); PG8_STAGE(PG8_SB(0, 1), b2 + hstepB, voffB); PG8_STAGE(PG8_SA(0, 0), a2, voffA);
;             PG8_WAIT_V(8); PG8_WAIT_L(0); PG8_BAR; PG8_MMA(1, 0, At, B0); PG8_MMA(1, 1, At, B1); PG8_BAR; PG8_SCHED;
.LBB0_150:
	s_add_u32 s4, s48, 0x100
	s_addc_u32 s5, s49, 0
	s_add_u32 s37, s54, 0x100
	s_addc_u32 s44, s55, 0
	s_mov_b32 s45, 0
	s_waitcnt lgkmcnt(0)
	s_add_i32 s51, s45, 2
	s_cmp_eq_u32 s67, s45
	s_cselect_b32 s56, s0, s37
	s_cselect_b32 s57, s1, s44
	s_cselect_b32 s54, s94, s4
	s_cselect_b32 s55, s95, s5
	s_add_u32 s48, s56, 0x80
	s_addc_u32 s49, s57, 0
	s_add_u32 s45, s37, s15
	s_addc_u32 s59, s44, 0
	s_add_u32 s58, s45, 0xffffff80
	s_addc_u32 s59, s59, -1
	s_mov_b32 m0, s68
	s_nop 0
	global_load_lds_dwordx4 v0, s[58:59]
	s_nop 0
	s_mov_b32 m0, s85
	s_nop 0
	global_load_lds_dwordx4 v240, s[58:59]
	s_waitcnt vmcnt(8)
	s_waitcnt lgkmcnt(0)
	s_barrier
	s_setprio 1
	s_waitcnt lgkmcnt(0)
	v_mfma_f32_16x16x32_bf16 v[172:175], v[108:111], v[156:159], 0
	v_mfma_f32_16x16x32_bf16 v[172:175], v[120:123], v[160:163], v[172:175]
	v_mfma_f32_16x16x32_bf16 v[168:171], v[128:131], v[156:159], 0
	v_mfma_f32_16x16x32_bf16 v[168:171], v[132:135], v[160:163], v[168:171]
	v_mfma_f32_16x16x32_bf16 v[140:143], v[136:139], v[156:159], 0
	v_mfma_f32_16x16x32_bf16 v[140:143], v[144:147], v[160:163], v[140:143]
	v_mfma_f32_16x16x32_bf16 v[124:127], v[148:151], v[156:159], 0
	v_mfma_f32_16x16x32_bf16 v[124:127], v[152:155], v[160:163], v[124:127]
	v_mfma_f32_16x16x32_bf16 v[100:103], v[148:151], v[164:167], 0
	v_mfma_f32_16x16x32_bf16 v[100:103], v[152:155], v[176:179], v[100:103]
	v_mfma_f32_16x16x32_bf16 v[104:107], v[136:139], v[164:167], 0
	v_mfma_f32_16x16x32_bf16 v[104:107], v[144:147], v[176:179], v[104:107]
	v_mfma_f32_16x16x32_bf16 v[112:115], v[128:131], v[164:167], 0
	v_mfma_f32_16x16x32_bf16 v[112:115], v[132:135], v[176:179], v[112:115]
	v_mfma_f32_16x16x32_bf16 v[116:119], v[108:111], v[164:167], 0
	v_mfma_f32_16x16x32_bf16 v[116:119], v[120:123], v[176:179], v[116:119]
	v_mfma_f32_16x16x32_bf16 v[96:99], v[108:111], v[180:183], 0
	v_mfma_f32_16x16x32_bf16 v[96:99], v[120:123], v[184:187], v[96:99]
	v_mfma_f32_16x16x32_bf16 v[92:95], v[128:131], v[180:183], 0
	v_mfma_f32_16x16x32_bf16 v[92:95], v[132:135], v[184:187], v[92:95]
	v_mfma_f32_16x16x32_bf16 v[88:91], v[136:139], v[180:183], 0
	v_mfma_f32_16x16x32_bf16 v[88:91], v[144:147], v[184:187], v[88:91]
	v_mfma_f32_16x16x32_bf16 v[84:87], v[148:151], v[180:183], 0
	v_mfma_f32_16x16x32_bf16 v[84:87], v[152:155], v[184:187], v[84:87]
	v_mfma_f32_16x16x32_bf16 v[68:71], v[148:151], v[188:191], 0
	v_mfma_f32_16x16x32_bf16 v[68:71], v[152:155], v[202:205], v[68:71]
	v_mfma_f32_16x16x32_bf16 v[72:75], v[136:139], v[188:191], 0
	v_mfma_f32_16x16x32_bf16 v[72:75], v[144:147], v[202:205], v[72:75]
	v_mfma_f32_16x16x32_bf16 v[76:79], v[128:131], v[188:191], 0
	v_mfma_f32_16x16x32_bf16 v[76:79], v[132:135], v[202:205], v[76:79]
	v_mfma_f32_16x16x32_bf16 v[80:83], v[108:111], v[188:191], 0
	v_mfma_f32_16x16x32_bf16 v[80:83], v[120:123], v[202:205], v[80:83]
	s_setprio 0
	s_barrier
	ds_read_b128 v[156:159], v245 offset:16384
	ds_read_b128 v[160:163], v245 offset:17408
	ds_read_b128 v[164:167], v245 offset:18432
	ds_read_b128 v[176:179], v245 offset:19456
	ds_read_b128 v[180:183], v245 offset:20480
	ds_read_b128 v[184:187], v245 offset:21504
	ds_read_b128 v[188:191], v245 offset:22528
	ds_read_b128 v[202:205], v245 offset:23552
	s_mov_b32 m0, s27
	s_nop 0
	global_load_lds_dwordx4 v195, s[54:55]
	s_add_u32 s58, s54, s15
	s_mov_b32 m0, s28
	s_nop 0
	global_load_lds_dwordx4 v241, s[54:55]
	s_addc_u32 s59, s55, 0
	s_mov_b32 m0, s29
	s_nop 0
	global_load_lds_dwordx4 v195, s[58:59]
	s_nop 0
	s_mov_b32 m0, s30
	s_nop 0
	global_load_lds_dwordx4 v241, s[58:59]
	s_nop 0
	s_mov_b32 m0, s26
	s_nop 0
	global_load_lds_dwordx4 v0, s[56:57]
	s_nop 0
	s_mov_b32 m0, s31
	s_nop 0
	global_load_lds_dwordx4 v240, s[56:57]
	s_waitcnt vmcnt(8)
	s_waitcnt lgkmcnt(0)
	s_barrier
	s_setprio 1
	s_waitcnt lgkmcnt(0)
	v_mfma_f32_16x16x32_bf16 v[64:67], v[108:111], v[156:159], 0
	v_mfma_f32_16x16x32_bf16 v[64:67], v[120:123], v[160:163], v[64:67]
	v_mfma_f32_16x16x32_bf16 v[60:63], v[128:131], v[156:159], 0
	v_mfma_f32_16x16x32_bf16 v[60:63], v[132:135], v[160:163], v[60:63]
	v_mfma_f32_16x16x32_bf16 v[56:59], v[136:139], v[156:159], 0
	v_mfma_f32_16x16x32_bf16 v[56:59], v[144:147], v[160:163], v[56:59]
	v_mfma_f32_16x16x32_bf16 v[52:55], v[148:151], v[156:159], 0
	v_mfma_f32_16x16x32_bf16 v[52:55], v[152:155], v[160:163], v[52:55]
	v_mfma_f32_16x16x32_bf16 v[36:39], v[148:151], v[164:167], 0
	v_mfma_f32_16x16x32_bf16 v[36:39], v[152:155], v[176:179], v[36:39]
	v_mfma_f32_16x16x32_bf16 v[40:43], v[136:139], v[164:167], 0
	v_mfma_f32_16x16x32_bf16 v[40:43], v[144:147], v[176:179], v[40:43]
	v_mfma_f32_16x16x32_bf16 v[44:47], v[128:131], v[164:167], 0
	v_mfma_f32_16x16x32_bf16 v[44:47], v[132:135], v[176:179], v[44:47]
	v_mfma_f32_16x16x32_bf16 v[48:51], v[108:111], v[164:167], 0
	v_mfma_f32_16x16x32_bf16 v[48:51], v[120:123], v[176:179], v[48:51]
	v_mfma_f32_16x16x32_bf16 v[32:35], v[108:111], v[180:183], 0
	v_mfma_f32_16x16x32_bf16 v[32:35], v[120:123], v[184:187], v[32:35]
	v_mfma_f32_16x16x32_bf16 v[28:31], v[128:131], v[180:183], 0
	v_mfma_f32_16x16x32_bf16 v[28:31], v[132:135], v[184:187], v[28:31]
	v_mfma_f32_16x16x32_bf16 v[24:27], v[136:139], v[180:183], 0
	v_mfma_f32_16x16x32_bf16 v[24:27], v[144:147], v[184:187], v[24:27]
	v_mfma_f32_16x16x32_bf16 v[20:23], v[148:151], v[180:183], 0
	v_mfma_f32_16x16x32_bf16 v[20:23], v[152:155], v[184:187], v[20:23]
	v_mfma_f32_16x16x32_bf16 v[4:7], v[148:151], v[188:191], 0
	v_mfma_f32_16x16x32_bf16 v[4:7], v[152:155], v[202:205], v[4:7]
	v_mfma_f32_16x16x32_bf16 v[8:11], v[136:139], v[188:191], 0
	v_mfma_f32_16x16x32_bf16 v[8:11], v[144:147], v[202:205], v[8:11]
	v_mfma_f32_16x16x32_bf16 v[12:15], v[128:131], v[188:191], 0
	v_mfma_f32_16x16x32_bf16 v[12:15], v[132:135], v[202:205], v[12:15]
	v_mfma_f32_16x16x32_bf16 v[16:19], v[108:111], v[188:191], 0
	v_mfma_f32_16x16x32_bf16 v[16:19], v[120:123], v[202:205], v[16:19]
	s_setprio 0
	s_barrier
; #define PG8_STAGE(bufoff, gbase, voff) do { _Pragma("unroll") for (int _i = 0; _i < 2; ++_i) { \
;         const unsigned _m0 = ldsb + (unsigned)((bufoff) + _i * 8192); const char* _gb = (const char*)(gbase); \
;         asm volatile("s_mov_b32 m0, %0\n\ts_nop 0\n\tglobal_load_lds_dwordx4 %1, %2" :: "s"(_m0), "v"((voff)[_i]), "s"(_gb) : "m0", "memory"); } } while (0)
; #define PG8_LDA(dst, b, h) do { _Pragma("unroll") for (int m = 0; m < 4; ++m) _Pragma("unroll") for (int k = 0; k < 2; ++k) dst[m][k] = *(const LAS bf16x8*)(lds + PG8_SA(b, h) + aoff + m * 2048 + k * 1024); } while (0)
; #define PG8_LDB(dst, b, h) do { _Pragma("unroll") for (int n = 0; n < 2; ++n) _Pragma("unroll") for (int k = 0; k < 2; ++k) dst[n][k] = *(const LAS bf16x8*)(lds + PG8_SB(b, h) + boff + n * 2048 + k * 1024); } while (0)
; #define PG8_MMA(ai, bj, At, Bt) do { __builtin_amdgcn_s_setprio(1); _Pragma("unroll") for (int m = 0; m < 4; ++m) _Pragma("unroll") for (int n = 0; n < 2; ++n) _Pragma("unroll") for (int k = 0; k < 2; ++k) \
;         acc[ai][bj][m][n] = __builtin_amdgcn_mfma_f32_16x16x32_bf16(Bt[n][k], At[m][k], acc[ai][bj][m][n], 0, 0, 0); __builtin_amdgcn_s_setprio(0); } while (0)
; #define PG8_WAIT_V(n) asm volatile("s_waitcnt vmcnt(" #n ")" ::: "memory")
; #define PG8_WAIT_L(n) asm volatile("s_waitcnt lgkmcnt(" #n ")" ::: "memory")
; #define PG8_BAR __builtin_amdgcn_s_barrier()
; #define PG8_SCHED __builtin_amdgcn_sched_barrier(0)
; template <class Epi, bool ALIGN_EPI>
; __device__ __forceinline__ void gemm_phase(LAS unsigned char* lds, const Gemm g, const StaticOrder& S, const Epi& E) {
;     ...
;             PG8_LDB(B0, 1, 0); PG8_LDB(B1, 1, 1); PG8_SCHED; PG8_LDA(At, 1, 0); PG8_STAGE(PG8_SA(0, 1), a2 + hstepA, voffA);
;             PG8_WAIT_V(8); PG8_WAIT_L(0); PG8_BAR; PG8_MMA(0, 0, At, B0); PG8_MMA(0, 1, At, B1); PG8_BAR; PG8_SCHED;
;             PG8_LDA(At, 1, 1); PG8_STAGE(PG8_SB(1, 0), b3, voffB); PG8_STAGE(PG8_SB(1, 1), b3 + hstepB, voffB); PG8_STAGE(PG8_SA(1, 0), a3, voffA);
;             PG8_WAIT_V(8); PG8_WAIT_L(0); PG8_BAR; PG8_MMA(1, 0, At, B0); PG8_MMA(1, 1, At, B1); PG8_BAR; PG8_SCHED;
	v_add_u32_e32 v132, 0x18000, v244
	v_add_u32_e32 v152, 0x1c000, v244
	ds_read_b128 v[108:111], v132
	ds_read_b128 v[120:123], v132 offset:1024
	ds_read_b128 v[128:131], v132 offset:2048
	ds_read_b128 v[132:135], v132 offset:3072
	ds_read_b128 v[136:139], v152
	ds_read_b128 v[144:147], v152 offset:1024
	ds_read_b128 v[148:151], v152 offset:2048
	ds_read_b128 v[152:155], v152 offset:3072
	ds_read_b128 v[156:159], v245 offset:32768
	ds_read_b128 v[160:163], v245 offset:33792
	ds_read_b128 v[164:167], v245 offset:34816
	ds_read_b128 v[176:179], v245 offset:35840
	ds_read_b128 v[180:183], v245 offset:36864
	ds_read_b128 v[184:187], v245 offset:37888
	ds_read_b128 v[188:191], v245 offset:38912
	ds_read_b128 v[202:205], v245 offset:39936
	s_add_u32 s56, s56, s15
	s_addc_u32 s57, s57, 0
	s_mov_b32 m0, s41
	s_nop 0
	global_load_lds_dwordx4 v0, s[56:57]
	s_nop 0
	s_mov_b32 m0, s42
	s_nop 0
	global_load_lds_dwordx4 v240, s[56:57]
	s_waitcnt vmcnt(8)
	s_waitcnt lgkmcnt(0)
	s_barrier
	s_setprio 1
	s_waitcnt lgkmcnt(0)
	v_mfma_f32_16x16x32_bf16 v[172:175], v[108:111], v[156:159], v[172:175]
	v_mfma_f32_16x16x32_bf16 v[172:175], v[120:123], v[160:163], v[172:175]
	v_mfma_f32_16x16x32_bf16 v[168:171], v[128:131], v[156:159], v[168:171]
	v_mfma_f32_16x16x32_bf16 v[168:171], v[132:135], v[160:163], v[168:171]
	v_mfma_f32_16x16x32_bf16 v[140:143], v[136:139], v[156:159], v[140:143]
	v_mfma_f32_16x16x32_bf16 v[140:143], v[144:147], v[160:163], v[140:143]
	v_mfma_f32_16x16x32_bf16 v[124:127], v[148:151], v[156:159], v[124:127]
	v_mfma_f32_16x16x32_bf16 v[124:127], v[152:155], v[160:163], v[124:127]
	v_mfma_f32_16x16x32_bf16 v[100:103], v[148:151], v[164:167], v[100:103]
	v_mfma_f32_16x16x32_bf16 v[100:103], v[152:155], v[176:179], v[100:103]
	v_mfma_f32_16x16x32_bf16 v[104:107], v[136:139], v[164:167], v[104:107]
	v_mfma_f32_16x16x32_bf16 v[104:107], v[144:147], v[176:179], v[104:107]
	v_mfma_f32_16x16x32_bf16 v[112:115], v[128:131], v[164:167], v[112:115]
	v_mfma_f32_16x16x32_bf16 v[112:115], v[132:135], v[176:179], v[112:115]
	v_mfma_f32_16x16x32_bf16 v[116:119], v[108:111], v[164:167], v[116:119]
	v_mfma_f32_16x16x32_bf16 v[116:119], v[120:123], v[176:179], v[116:119]
	v_mfma_f32_16x16x32_bf16 v[96:99], v[108:111], v[180:183], v[96:99]
	v_mfma_f32_16x16x32_bf16 v[96:99], v[120:123], v[184:187], v[96:99]
	v_mfma_f32_16x16x32_bf16 v[92:95], v[128:131], v[180:183], v[92:95]
	v_mfma_f32_16x16x32_bf16 v[92:95], v[132:135], v[184:187], v[92:95]
	v_mfma_f32_16x16x32_bf16 v[88:91], v[136:139], v[180:183], v[88:91]
	v_mfma_f32_16x16x32_bf16 v[88:91], v[144:147], v[184:187], v[88:91]
	v_mfma_f32_16x16x32_bf16 v[84:87], v[148:151], v[180:183], v[84:87]
	v_mfma_f32_16x16x32_bf16 v[84:87], v[152:155], v[184:187], v[84:87]
	v_mfma_f32_16x16x32_bf16 v[68:71], v[148:151], v[188:191], v[68:71]
	v_mfma_f32_16x16x32_bf16 v[68:71], v[152:155], v[202:205], v[68:71]
	v_mfma_f32_16x16x32_bf16 v[72:75], v[136:139], v[188:191], v[72:75]
	v_mfma_f32_16x16x32_bf16 v[72:75], v[144:147], v[202:205], v[72:75]
	v_mfma_f32_16x16x32_bf16 v[76:79], v[128:131], v[188:191], v[76:79]
	v_mfma_f32_16x16x32_bf16 v[76:79], v[132:135], v[202:205], v[76:79]
	v_mfma_f32_16x16x32_bf16 v[80:83], v[108:111], v[188:191], v[80:83]
	v_mfma_f32_16x16x32_bf16 v[80:83], v[120:123], v[202:205], v[80:83]
	s_setprio 0
	s_barrier
	ds_read_b128 v[156:159], v245 offset:49152
	ds_read_b128 v[160:163], v245 offset:50176
	ds_read_b128 v[164:167], v245 offset:51200
	ds_read_b128 v[176:179], v245 offset:52224
	ds_read_b128 v[180:183], v245 offset:53248
	ds_read_b128 v[184:187], v245 offset:54272
	ds_read_b128 v[188:191], v245 offset:55296
	ds_read_b128 v[202:205], v245 offset:56320
	s_add_u32 s54, s54, 0x80
	s_addc_u32 s55, s55, 0
	s_mov_b32 m0, s46
	s_nop 0
	global_load_lds_dwordx4 v195, s[54:55]
	s_nop 0
	s_mov_b32 m0, s50
	s_nop 0
	global_load_lds_dwordx4 v241, s[54:55]
	s_add_u32 s54, s58, 0x80
	s_addc_u32 s55, s59, 0
	s_mov_b32 m0, s61
	s_nop 0
	global_load_lds_dwordx4 v195, s[54:55]
	s_nop 0
	s_mov_b32 m0, s65
	s_nop 0
	global_load_lds_dwordx4 v241, s[54:55]
	s_nop 0
	s_mov_b32 m0, s53
	s_nop 0
	global_load_lds_dwordx4 v0, s[48:49]
	s_nop 0
	s_mov_b32 m0, s60
	s_nop 0
	global_load_lds_dwordx4 v240, s[48:49]
	s_waitcnt vmcnt(8)
	s_waitcnt lgkmcnt(0)
	s_nop 0
	s_barrier
	s_setprio 1
	s_waitcnt lgkmcnt(0)
	v_mfma_f32_16x16x32_bf16 v[64:67], v[108:111], v[156:159], v[64:67]
	v_mfma_f32_16x16x32_bf16 v[64:67], v[120:123], v[160:163], v[64:67]
	v_mfma_f32_16x16x32_bf16 v[60:63], v[128:131], v[156:159], v[60:63]
	v_mfma_f32_16x16x32_bf16 v[60:63], v[132:135], v[160:163], v[60:63]
	v_mfma_f32_16x16x32_bf16 v[56:59], v[136:139], v[156:159], v[56:59]
	v_mfma_f32_16x16x32_bf16 v[56:59], v[144:147], v[160:163], v[56:59]
	v_mfma_f32_16x16x32_bf16 v[52:55], v[148:151], v[156:159], v[52:55]
	v_mfma_f32_16x16x32_bf16 v[52:55], v[152:155], v[160:163], v[52:55]
	v_mfma_f32_16x16x32_bf16 v[36:39], v[148:151], v[164:167], v[36:39]
	v_mfma_f32_16x16x32_bf16 v[36:39], v[152:155], v[176:179], v[36:39]
	v_mfma_f32_16x16x32_bf16 v[40:43], v[136:139], v[164:167], v[40:43]
	v_mfma_f32_16x16x32_bf16 v[40:43], v[144:147], v[176:179], v[40:43]
	v_mfma_f32_16x16x32_bf16 v[44:47], v[128:131], v[164:167], v[44:47]
	v_mfma_f32_16x16x32_bf16 v[44:47], v[132:135], v[176:179], v[44:47]
	v_mfma_f32_16x16x32_bf16 v[48:51], v[108:111], v[164:167], v[48:51]
	v_mfma_f32_16x16x32_bf16 v[48:51], v[120:123], v[176:179], v[48:51]
	v_mfma_f32_16x16x32_bf16 v[32:35], v[108:111], v[180:183], v[32:35]
	v_mfma_f32_16x16x32_bf16 v[32:35], v[120:123], v[184:187], v[32:35]
	v_mfma_f32_16x16x32_bf16 v[28:31], v[128:131], v[180:183], v[28:31]
	v_mfma_f32_16x16x32_bf16 v[28:31], v[132:135], v[184:187], v[28:31]
	v_mfma_f32_16x16x32_bf16 v[24:27], v[136:139], v[180:183], v[24:27]
	v_mfma_f32_16x16x32_bf16 v[24:27], v[144:147], v[184:187], v[24:27]
	v_mfma_f32_16x16x32_bf16 v[20:23], v[148:151], v[180:183], v[20:23]
	v_mfma_f32_16x16x32_bf16 v[20:23], v[152:155], v[184:187], v[20:23]
	v_mfma_f32_16x16x32_bf16 v[4:7], v[148:151], v[188:191], v[4:7]
	v_mfma_f32_16x16x32_bf16 v[4:7], v[152:155], v[202:205], v[4:7]
	v_mfma_f32_16x16x32_bf16 v[8:11], v[136:139], v[188:191], v[8:11]
	v_mfma_f32_16x16x32_bf16 v[8:11], v[144:147], v[202:205], v[8:11]
	v_mfma_f32_16x16x32_bf16 v[12:15], v[128:131], v[188:191], v[12:15]
	v_mfma_f32_16x16x32_bf16 v[12:15], v[132:135], v[202:205], v[12:15]
	v_mfma_f32_16x16x32_bf16 v[16:19], v[108:111], v[188:191], v[16:19]
	v_mfma_f32_16x16x32_bf16 v[16:19], v[120:123], v[202:205], v[16:19]
	s_setprio 0
	s_barrier
	s_add_u32 s4, s4, 0x100
	s_addc_u32 s5, s5, 0
	s_add_u32 s37, s37, 0x100
	s_addc_u32 s44, s44, 0
	s_cmp_ge_u32 s51, s43
	s_mov_b32 s45, s51
; #define PG8_STAGE(bufoff, gbase, voff) do { _Pragma("unroll") for (int _i = 0; _i < 2; ++_i) { \
;         const unsigned _m0 = ldsb + (unsigned)((bufoff) + _i * 8192); const char* _gb = (const char*)(gbase); \
;         asm volatile("s_mov_b32 m0, %0\n\ts_nop 0\n\tglobal_load_lds_dwordx4 %1, %2" :: "s"(_m0), "v"((voff)[_i]), "s"(_gb) : "m0", "memory"); } } while (0)
; #define PG8_LDA(dst, b, h) do { _Pragma("unroll") for (int m = 0; m < 4; ++m) _Pragma("unroll") for (int k = 0; k < 2; ++k) dst[m][k] = *(const LAS bf16x8*)(lds + PG8_SA(b, h) + aoff + m * 2048 + k * 1024); } while (0)
; #define PG8_LDB(dst, b, h) do { _Pragma("unroll") for (int n = 0; n < 2; ++n) _Pragma("unroll") for (int k = 0; k < 2; ++k) dst[n][k] = *(const LAS bf16x8*)(lds + PG8_SB(b, h) + boff + n * 2048 + k * 1024); } while (0)
; #define PG8_MMA(ai, bj, At, Bt) do { __builtin_amdgcn_s_setprio(1); _Pragma("unroll") for (int m = 0; m < 4; ++m) _Pragma("unroll") for (int n = 0; n < 2; ++n) _Pragma("unroll") for (int k = 0; k < 2; ++k) \
;         acc[ai][bj][m][n] = __builtin_amdgcn_mfma_f32_16x16x32_bf16(Bt[n][k], At[m][k], acc[ai][bj][m][n], 0, 0, 0); __builtin_amdgcn_s_setprio(0); } while (0)
; #define PG8_WAIT_V(n) asm volatile("s_waitcnt vmcnt(" #n ")" ::: "memory")
; #define PG8_WAIT_L(n) asm volatile("s_waitcnt lgkmcnt(" #n ")" ::: "memory")
; template <class Epi, bool ALIGN_EPI>
; __device__ __forceinline__ void gemm_phase(LAS unsigned char* lds, const Gemm g, const StaticOrder& S, const Epi& E) {
;     ...
;         for (int t = 0; t < nt; t += 2) {
;             const bool last = (t == nt - 2);
;             const char* a1 = cA + (size_t)(t + 1) * kstep;
;             const char* a2 = last ? nA : cA + (size_t)(t + 2) * kstep; const char* b2 = last ? nB : cB + (size_t)(t + 2) * kstep;
;             const char* a3 = a2 + kstep; const char* b3 = b2 + kstep;
;             PG8_LDB(B0, 0, 0); PG8_LDB(B1, 0, 1); PG8_SCHED; PG8_LDA(At, 0, 0); PG8_STAGE(PG8_SA(1, 1), a1 + hstepA, voffA);
;             PG8_WAIT_V(8); PG8_WAIT_L(0); PG8_BAR; PG8_MMA(0, 0, At, B0); PG8_MMA(0, 1, At, B1); PG8_BAR; PG8_SCHED;
;             PG8_LDA(At, 0, 1); PG8_STAGE(PG8_SB(0, 0), b2, voffB); PG8_STAGE(PG8_SB(0, 1), b2 + hstepB, voffB); PG8_STAGE(PG8_SA(0, 0), a2, voffA);
;             PG8_WAIT_V(8); PG8_WAIT_L(0); PG8_BAR; PG8_MMA(1, 0, At, B0); PG8_MMA(1, 1, At, B1); PG8_BAR; PG8_SCHED;
.LBB0_151:
	v_add_u32_e32 v132, 0x10000, v244
	v_add_u32_e32 v152, 0x14000, v244
	ds_read_b128 v[108:111], v132
	ds_read_b128 v[120:123], v132 offset:1024
	ds_read_b128 v[128:131], v132 offset:2048
	ds_read_b128 v[132:135], v132 offset:3072
	ds_read_b128 v[136:139], v152
	ds_read_b128 v[144:147], v152 offset:1024
	ds_read_b128 v[148:151], v152 offset:2048
	ds_read_b128 v[152:155], v152 offset:3072
	s_add_i32 s51, s45, 2
	s_cmp_eq_u32 s67, s45
	s_cselect_b32 s56, s0, s37
	s_cselect_b32 s57, s1, s44
	s_cselect_b32 s54, s94, s4
	s_cselect_b32 s55, s95, s5
	s_add_u32 s48, s56, 0x80
	s_addc_u32 s49, s57, 0
	ds_read_b128 v[156:159], v245
	ds_read_b128 v[160:163], v245 offset:1024
	ds_read_b128 v[164:167], v245 offset:2048
	ds_read_b128 v[176:179], v245 offset:3072
	ds_read_b128 v[180:183], v245 offset:4096
	ds_read_b128 v[184:187], v245 offset:5120
	ds_read_b128 v[188:191], v245 offset:6144
	ds_read_b128 v[202:205], v245 offset:7168
	s_add_u32 s45, s37, s15
	s_addc_u32 s59, s44, 0
	s_add_u32 s58, s45, 0xffffff80
	s_addc_u32 s59, s59, -1
	s_mov_b32 m0, s68
	s_nop 0
	global_load_lds_dwordx4 v0, s[58:59]
	s_nop 0
	s_mov_b32 m0, s85
	s_nop 0
	global_load_lds_dwordx4 v240, s[58:59]
	s_waitcnt vmcnt(8)
	s_waitcnt lgkmcnt(0)
	s_barrier
	s_setprio 1
	s_waitcnt lgkmcnt(0)
	v_mfma_f32_16x16x32_bf16 v[172:175], v[108:111], v[156:159], v[172:175]
	v_mfma_f32_16x16x32_bf16 v[172:175], v[120:123], v[160:163], v[172:175]
	v_mfma_f32_16x16x32_bf16 v[168:171], v[128:131], v[156:159], v[168:171]
	v_mfma_f32_16x16x32_bf16 v[168:171], v[132:135], v[160:163], v[168:171]
	v_mfma_f32_16x16x32_bf16 v[140:143], v[136:139], v[156:159], v[140:143]
	v_mfma_f32_16x16x32_bf16 v[140:143], v[144:147], v[160:163], v[140:143]
	v_mfma_f32_16x16x32_bf16 v[124:127], v[148:151], v[156:159], v[124:127]
	v_mfma_f32_16x16x32_bf16 v[124:127], v[152:155], v[160:163], v[124:127]
	v_mfma_f32_16x16x32_bf16 v[100:103], v[148:151], v[164:167], v[100:103]
	v_mfma_f32_16x16x32_bf16 v[100:103], v[152:155], v[176:179], v[100:103]
	v_mfma_f32_16x16x32_bf16 v[104:107], v[136:139], v[164:167], v[104:107]
	v_mfma_f32_16x16x32_bf16 v[104:107], v[144:147], v[176:179], v[104:107]
	v_mfma_f32_16x16x32_bf16 v[112:115], v[128:131], v[164:167], v[112:115]
	v_mfma_f32_16x16x32_bf16 v[112:115], v[132:135], v[176:179], v[112:115]
	v_mfma_f32_16x16x32_bf16 v[116:119], v[108:111], v[164:167], v[116:119]
	v_mfma_f32_16x16x32_bf16 v[116:119], v[120:123], v[176:179], v[116:119]
	v_mfma_f32_16x16x32_bf16 v[96:99], v[108:111], v[180:183], v[96:99]
	v_mfma_f32_16x16x32_bf16 v[96:99], v[120:123], v[184:187], v[96:99]
	v_mfma_f32_16x16x32_bf16 v[92:95], v[128:131], v[180:183], v[92:95]
	v_mfma_f32_16x16x32_bf16 v[92:95], v[132:135], v[184:187], v[92:95]
	v_mfma_f32_16x16x32_bf16 v[88:91], v[136:139], v[180:183], v[88:91]
	v_mfma_f32_16x16x32_bf16 v[88:91], v[144:147], v[184:187], v[88:91]
	v_mfma_f32_16x16x32_bf16 v[84:87], v[148:151], v[180:183], v[84:87]
	v_mfma_f32_16x16x32_bf16 v[84:87], v[152:155], v[184:187], v[84:87]
	v_mfma_f32_16x16x32_bf16 v[68:71], v[148:151], v[188:191], v[68:71]
	v_mfma_f32_16x16x32_bf16 v[68:71], v[152:155], v[202:205], v[68:71]
	v_mfma_f32_16x16x32_bf16 v[72:75], v[136:139], v[188:191], v[72:75]
	v_mfma_f32_16x16x32_bf16 v[72:75], v[144:147], v[202:205], v[72:75]
	v_mfma_f32_16x16x32_bf16 v[76:79], v[128:131], v[188:191], v[76:79]
	v_mfma_f32_16x16x32_bf16 v[76:79], v[132:135], v[202:205], v[76:79]
	v_mfma_f32_16x16x32_bf16 v[80:83], v[108:111], v[188:191], v[80:83]
	v_mfma_f32_16x16x32_bf16 v[80:83], v[120:123], v[202:205], v[80:83]
	s_setprio 0
	s_barrier
	ds_read_b128 v[156:159], v245 offset:16384
	ds_read_b128 v[160:163], v245 offset:17408
	ds_read_b128 v[164:167], v245 offset:18432
	ds_read_b128 v[176:179], v245 offset:19456
	ds_read_b128 v[180:183], v245 offset:20480
	ds_read_b128 v[184:187], v245 offset:21504
	ds_read_b128 v[188:191], v245 offset:22528
	ds_read_b128 v[202:205], v245 offset:23552
	s_mov_b32 m0, s27
	s_nop 0
	global_load_lds_dwordx4 v195, s[54:55]
	s_add_u32 s58, s54, s15
	s_mov_b32 m0, s28
	s_nop 0
	global_load_lds_dwordx4 v241, s[54:55]
	s_addc_u32 s59, s55, 0
	s_mov_b32 m0, s29
	s_nop 0
	global_load_lds_dwordx4 v195, s[58:59]
	s_nop 0
	s_mov_b32 m0, s30
	s_nop 0
	global_load_lds_dwordx4 v241, s[58:59]
	s_nop 0
	s_mov_b32 m0, s26
	s_nop 0
	global_load_lds_dwordx4 v0, s[56:57]
	s_nop 0
	s_mov_b32 m0, s31
	s_nop 0
	global_load_lds_dwordx4 v240, s[56:57]
	s_waitcnt vmcnt(8)
	s_waitcnt lgkmcnt(0)
	s_barrier
	s_setprio 1
	s_waitcnt lgkmcnt(0)
	v_mfma_f32_16x16x32_bf16 v[64:67], v[108:111], v[156:159], v[64:67]
	v_mfma_f32_16x16x32_bf16 v[64:67], v[120:123], v[160:163], v[64:67]
	v_mfma_f32_16x16x32_bf16 v[60:63], v[128:131], v[156:159], v[60:63]
	v_mfma_f32_16x16x32_bf16 v[60:63], v[132:135], v[160:163], v[60:63]
	v_mfma_f32_16x16x32_bf16 v[56:59], v[136:139], v[156:159], v[56:59]
	v_mfma_f32_16x16x32_bf16 v[56:59], v[144:147], v[160:163], v[56:59]
	v_mfma_f32_16x16x32_bf16 v[52:55], v[148:151], v[156:159], v[52:55]
	v_mfma_f32_16x16x32_bf16 v[52:55], v[152:155], v[160:163], v[52:55]
	v_mfma_f32_16x16x32_bf16 v[36:39], v[148:151], v[164:167], v[36:39]
	v_mfma_f32_16x16x32_bf16 v[36:39], v[152:155], v[176:179], v[36:39]
	v_mfma_f32_16x16x32_bf16 v[40:43], v[136:139], v[164:167], v[40:43]
	v_mfma_f32_16x16x32_bf16 v[40:43], v[144:147], v[176:179], v[40:43]
	v_mfma_f32_16x16x32_bf16 v[44:47], v[128:131], v[164:167], v[44:47]
	v_mfma_f32_16x16x32_bf16 v[44:47], v[132:135], v[176:179], v[44:47]
	v_mfma_f32_16x16x32_bf16 v[48:51], v[108:111], v[164:167], v[48:51]
	v_mfma_f32_16x16x32_bf16 v[48:51], v[120:123], v[176:179], v[48:51]
	v_mfma_f32_16x16x32_bf16 v[32:35], v[108:111], v[180:183], v[32:35]
	v_mfma_f32_16x16x32_bf16 v[32:35], v[120:123], v[184:187], v[32:35]
	v_mfma_f32_16x16x32_bf16 v[28:31], v[128:131], v[180:183], v[28:31]
	v_mfma_f32_16x16x32_bf16 v[28:31], v[132:135], v[184:187], v[28:31]
	v_mfma_f32_16x16x32_bf16 v[24:27], v[136:139], v[180:183], v[24:27]
	v_mfma_f32_16x16x32_bf16 v[24:27], v[144:147], v[184:187], v[24:27]
	v_mfma_f32_16x16x32_bf16 v[20:23], v[148:151], v[180:183], v[20:23]
	v_mfma_f32_16x16x32_bf16 v[20:23], v[152:155], v[184:187], v[20:23]
	v_mfma_f32_16x16x32_bf16 v[4:7], v[148:151], v[188:191], v[4:7]
	v_mfma_f32_16x16x32_bf16 v[4:7], v[152:155], v[202:205], v[4:7]
	v_mfma_f32_16x16x32_bf16 v[8:11], v[136:139], v[188:191], v[8:11]
	v_mfma_f32_16x16x32_bf16 v[8:11], v[144:147], v[202:205], v[8:11]
	v_mfma_f32_16x16x32_bf16 v[12:15], v[128:131], v[188:191], v[12:15]
	v_mfma_f32_16x16x32_bf16 v[12:15], v[132:135], v[202:205], v[12:15]
	v_mfma_f32_16x16x32_bf16 v[16:19], v[108:111], v[188:191], v[16:19]
	v_mfma_f32_16x16x32_bf16 v[16:19], v[120:123], v[202:205], v[16:19]
	s_setprio 0
	s_barrier
; #define PG8_STAGE(bufoff, gbase, voff) do { _Pragma("unroll") for (int _i = 0; _i < 2; ++_i) { \
;         const unsigned _m0 = ldsb + (unsigned)((bufoff) + _i * 8192); const char* _gb = (const char*)(gbase); \
;         asm volatile("s_mov_b32 m0, %0\n\ts_nop 0\n\tglobal_load_lds_dwordx4 %1, %2" :: "s"(_m0), "v"((voff)[_i]), "s"(_gb) : "m0", "memory"); } } while (0)
; #define PG8_LDA(dst, b, h) do { _Pragma("unroll") for (int m = 0; m < 4; ++m) _Pragma("unroll") for (int k = 0; k < 2; ++k) dst[m][k] = *(const LAS bf16x8*)(lds + PG8_SA(b, h) + aoff + m * 2048 + k * 1024); } while (0)
; #define PG8_LDB(dst, b, h) do { _Pragma("unroll") for (int n = 0; n < 2; ++n) _Pragma("unroll") for (int k = 0; k < 2; ++k) dst[n][k] = *(const LAS bf16x8*)(lds + PG8_SB(b, h) + boff + n * 2048 + k * 1024); } while (0)
; #define PG8_MMA(ai, bj, At, Bt) do { __builtin_amdgcn_s_setprio(1); _Pragma("unroll") for (int m = 0; m < 4; ++m) _Pragma("unroll") for (int n = 0; n < 2; ++n) _Pragma("unroll") for (int k = 0; k < 2; ++k) \
;         acc[ai][bj][m][n] = __builtin_amdgcn_mfma_f32_16x16x32_bf16(Bt[n][k], At[m][k], acc[ai][bj][m][n], 0, 0, 0); __builtin_amdgcn_s_setprio(0); } while (0)
; #define PG8_WAIT_V(n) asm volatile("s_waitcnt vmcnt(" #n ")" ::: "memory")
; #define PG8_WAIT_L(n) asm volatile("s_waitcnt lgkmcnt(" #n ")" ::: "memory")
; #define PG8_BAR __builtin_amdgcn_s_barrier()
; #define PG8_SCHED __builtin_amdgcn_sched_barrier(0)
; template <class Epi, bool ALIGN_EPI>
; __device__ __forceinline__ void gemm_phase(LAS unsigned char* lds, const Gemm g, const StaticOrder& S, const Epi& E) {
;     ...
;             PG8_LDB(B0, 1, 0); PG8_LDB(B1, 1, 1); PG8_SCHED; PG8_LDA(At, 1, 0); PG8_STAGE(PG8_SA(0, 1), a2 + hstepA, voffA);
;             PG8_WAIT_V(8); PG8_WAIT_L(0); PG8_BAR; PG8_MMA(0, 0, At, B0); PG8_MMA(0, 1, At, B1); PG8_BAR; PG8_SCHED;
;             PG8_LDA(At, 1, 1); PG8_STAGE(PG8_SB(1, 0), b3, voffB); PG8_STAGE(PG8_SB(1, 1), b3 + hstepB, voffB); PG8_STAGE(PG8_SA(1, 0), a3, voffA);
;             PG8_WAIT_V(8); PG8_WAIT_L(0); PG8_BAR; PG8_MMA(1, 0, At, B0); PG8_MMA(1, 1, At, B1); PG8_BAR; PG8_SCHED;
;         }
;         if constexpr (ALIGN_EPI) { if (wr == 0) PG8_BAR; }
	v_add_u32_e32 v132, 0x18000, v244
	v_add_u32_e32 v152, 0x1c000, v244
	ds_read_b128 v[108:111], v132
	ds_read_b128 v[120:123], v132 offset:1024
	ds_read_b128 v[128:131], v132 offset:2048
	ds_read_b128 v[132:135], v132 offset:3072
	ds_read_b128 v[136:139], v152
	ds_read_b128 v[144:147], v152 offset:1024
	ds_read_b128 v[148:151], v152 offset:2048
	ds_read_b128 v[152:155], v152 offset:3072
	ds_read_b128 v[156:159], v245 offset:32768
	ds_read_b128 v[160:163], v245 offset:33792
	ds_read_b128 v[164:167], v245 offset:34816
	ds_read_b128 v[176:179], v245 offset:35840
	ds_read_b128 v[180:183], v245 offset:36864
	ds_read_b128 v[184:187], v245 offset:37888
	ds_read_b128 v[188:191], v245 offset:38912
	ds_read_b128 v[202:205], v245 offset:39936
	s_add_u32 s56, s56, s15
	s_addc_u32 s57, s57, 0
	s_mov_b32 m0, s41
	s_nop 0
	global_load_lds_dwordx4 v0, s[56:57]
	s_nop 0
	s_mov_b32 m0, s42
	s_nop 0
	global_load_lds_dwordx4 v240, s[56:57]
	s_waitcnt vmcnt(8)
	s_waitcnt lgkmcnt(0)
	s_barrier
	s_setprio 1
	s_waitcnt lgkmcnt(0)
	v_mfma_f32_16x16x32_bf16 v[172:175], v[108:111], v[156:159], v[172:175]
	v_mfma_f32_16x16x32_bf16 v[172:175], v[120:123], v[160:163], v[172:175]
	v_mfma_f32_16x16x32_bf16 v[168:171], v[128:131], v[156:159], v[168:171]
	v_mfma_f32_16x16x32_bf16 v[168:171], v[132:135], v[160:163], v[168:171]
	v_mfma_f32_16x16x32_bf16 v[140:143], v[136:139], v[156:159], v[140:143]
	v_mfma_f32_16x16x32_bf16 v[140:143], v[144:147], v[160:163], v[140:143]
	v_mfma_f32_16x16x32_bf16 v[124:127], v[148:151], v[156:159], v[124:127]
	v_mfma_f32_16x16x32_bf16 v[124:127], v[152:155], v[160:163], v[124:127]
	v_mfma_f32_16x16x32_bf16 v[100:103], v[148:151], v[164:167], v[100:103]
	v_mfma_f32_16x16x32_bf16 v[100:103], v[152:155], v[176:179], v[100:103]
	v_mfma_f32_16x16x32_bf16 v[104:107], v[136:139], v[164:167], v[104:107]
	v_mfma_f32_16x16x32_bf16 v[104:107], v[144:147], v[176:179], v[104:107]
	v_mfma_f32_16x16x32_bf16 v[112:115], v[128:131], v[164:167], v[112:115]
	v_mfma_f32_16x16x32_bf16 v[112:115], v[132:135], v[176:179], v[112:115]
	v_mfma_f32_16x16x32_bf16 v[116:119], v[108:111], v[164:167], v[116:119]
	v_mfma_f32_16x16x32_bf16 v[116:119], v[120:123], v[176:179], v[116:119]
	v_mfma_f32_16x16x32_bf16 v[96:99], v[108:111], v[180:183], v[96:99]
	v_mfma_f32_16x16x32_bf16 v[96:99], v[120:123], v[184:187], v[96:99]
	v_mfma_f32_16x16x32_bf16 v[92:95], v[128:131], v[180:183], v[92:95]
	v_mfma_f32_16x16x32_bf16 v[92:95], v[132:135], v[184:187], v[92:95]
	v_mfma_f32_16x16x32_bf16 v[88:91], v[136:139], v[180:183], v[88:91]
	v_mfma_f32_16x16x32_bf16 v[88:91], v[144:147], v[184:187], v[88:91]
	v_mfma_f32_16x16x32_bf16 v[84:87], v[148:151], v[180:183], v[84:87]
	v_mfma_f32_16x16x32_bf16 v[84:87], v[152:155], v[184:187], v[84:87]
	v_mfma_f32_16x16x32_bf16 v[68:71], v[148:151], v[188:191], v[68:71]
	v_mfma_f32_16x16x32_bf16 v[68:71], v[152:155], v[202:205], v[68:71]
	v_mfma_f32_16x16x32_bf16 v[72:75], v[136:139], v[188:191], v[72:75]
	v_mfma_f32_16x16x32_bf16 v[72:75], v[144:147], v[202:205], v[72:75]
	v_mfma_f32_16x16x32_bf16 v[76:79], v[128:131], v[188:191], v[76:79]
	v_mfma_f32_16x16x32_bf16 v[76:79], v[132:135], v[202:205], v[76:79]
	v_mfma_f32_16x16x32_bf16 v[80:83], v[108:111], v[188:191], v[80:83]
	v_mfma_f32_16x16x32_bf16 v[80:83], v[120:123], v[202:205], v[80:83]
	s_setprio 0
	s_barrier
	ds_read_b128 v[156:159], v245 offset:49152
	ds_read_b128 v[160:163], v245 offset:50176
	ds_read_b128 v[164:167], v245 offset:51200
	ds_read_b128 v[176:179], v245 offset:52224
	ds_read_b128 v[180:183], v245 offset:53248
	ds_read_b128 v[184:187], v245 offset:54272
	ds_read_b128 v[188:191], v245 offset:55296
	ds_read_b128 v[202:205], v245 offset:56320
	s_add_u32 s54, s54, 0x80
	s_addc_u32 s55, s55, 0
	s_mov_b32 m0, s46
	s_nop 0
	global_load_lds_dwordx4 v195, s[54:55]
	s_nop 0
	s_mov_b32 m0, s50
	s_nop 0
	global_load_lds_dwordx4 v241, s[54:55]
	s_add_u32 s54, s58, 0x80
	s_addc_u32 s55, s59, 0
	s_mov_b32 m0, s61
	s_nop 0
	global_load_lds_dwordx4 v195, s[54:55]
	s_nop 0
	s_mov_b32 m0, s65
	s_nop 0
	global_load_lds_dwordx4 v241, s[54:55]
	s_nop 0
	s_mov_b32 m0, s53
	s_nop 0
	global_load_lds_dwordx4 v0, s[48:49]
	s_nop 0
	s_mov_b32 m0, s60
	s_nop 0
	global_load_lds_dwordx4 v240, s[48:49]
	s_waitcnt vmcnt(8)
	s_waitcnt lgkmcnt(0)
	s_nop 0
	s_barrier
	s_setprio 1
	s_waitcnt lgkmcnt(0)
	v_mfma_f32_16x16x32_bf16 v[64:67], v[108:111], v[156:159], v[64:67]
	v_mfma_f32_16x16x32_bf16 v[64:67], v[120:123], v[160:163], v[64:67]
	v_mfma_f32_16x16x32_bf16 v[60:63], v[128:131], v[156:159], v[60:63]
	v_mfma_f32_16x16x32_bf16 v[60:63], v[132:135], v[160:163], v[60:63]
	v_mfma_f32_16x16x32_bf16 v[56:59], v[136:139], v[156:159], v[56:59]
	v_mfma_f32_16x16x32_bf16 v[56:59], v[144:147], v[160:163], v[56:59]
	v_mfma_f32_16x16x32_bf16 v[52:55], v[148:151], v[156:159], v[52:55]
	v_mfma_f32_16x16x32_bf16 v[52:55], v[152:155], v[160:163], v[52:55]
	v_mfma_f32_16x16x32_bf16 v[36:39], v[148:151], v[164:167], v[36:39]
	v_mfma_f32_16x16x32_bf16 v[36:39], v[152:155], v[176:179], v[36:39]
	v_mfma_f32_16x16x32_bf16 v[40:43], v[136:139], v[164:167], v[40:43]
	v_mfma_f32_16x16x32_bf16 v[40:43], v[144:147], v[176:179], v[40:43]
	v_mfma_f32_16x16x32_bf16 v[44:47], v[128:131], v[164:167], v[44:47]
	v_mfma_f32_16x16x32_bf16 v[44:47], v[132:135], v[176:179], v[44:47]
	v_mfma_f32_16x16x32_bf16 v[48:51], v[108:111], v[164:167], v[48:51]
	v_mfma_f32_16x16x32_bf16 v[48:51], v[120:123], v[176:179], v[48:51]
	v_mfma_f32_16x16x32_bf16 v[32:35], v[108:111], v[180:183], v[32:35]
	v_mfma_f32_16x16x32_bf16 v[32:35], v[120:123], v[184:187], v[32:35]
	v_mfma_f32_16x16x32_bf16 v[28:31], v[128:131], v[180:183], v[28:31]
	v_mfma_f32_16x16x32_bf16 v[28:31], v[132:135], v[184:187], v[28:31]
	v_mfma_f32_16x16x32_bf16 v[24:27], v[136:139], v[180:183], v[24:27]
	v_mfma_f32_16x16x32_bf16 v[24:27], v[144:147], v[184:187], v[24:27]
	v_mfma_f32_16x16x32_bf16 v[20:23], v[148:151], v[180:183], v[20:23]
	v_mfma_f32_16x16x32_bf16 v[20:23], v[152:155], v[184:187], v[20:23]
	v_mfma_f32_16x16x32_bf16 v[4:7], v[148:151], v[188:191], v[4:7]
	v_mfma_f32_16x16x32_bf16 v[4:7], v[152:155], v[202:205], v[4:7]
	v_mfma_f32_16x16x32_bf16 v[8:11], v[136:139], v[188:191], v[8:11]
	v_mfma_f32_16x16x32_bf16 v[8:11], v[144:147], v[202:205], v[8:11]
	v_mfma_f32_16x16x32_bf16 v[12:15], v[128:131], v[188:191], v[12:15]
	v_mfma_f32_16x16x32_bf16 v[12:15], v[132:135], v[202:205], v[12:15]
	v_mfma_f32_16x16x32_bf16 v[16:19], v[108:111], v[188:191], v[16:19]
	v_mfma_f32_16x16x32_bf16 v[16:19], v[120:123], v[202:205], v[16:19]
	s_setprio 0
	s_barrier
	s_add_u32 s4, s4, 0x100
	s_addc_u32 s5, s5, 0
	s_add_u32 s37, s37, 0x100
	s_addc_u32 s44, s44, 0
	s_cmp_ge_u32 s51, s43
	s_mov_b32 s45, s51
	s_cbranch_scc0 .LBB0_151
	s_and_b64 vcc, exec, s[92:93]
	s_cbranch_vccz .LBB0_154
	s_barrier

; #define PG8_STAGE(bufoff, gbase, voff) do { _Pragma("unroll") for (int _i = 0; _i < 2; ++_i) { \
;         const unsigned _m0 = ldsb + (unsigned)((bufoff) + _i * 8192); const char* _gb = (const char*)(gbase); \
;         asm volatile("s_mov_b32 m0, %0\n\ts_nop 0\n\tglobal_load_lds_dwordx4 %1, %2" :: "s"(_m0), "v"((voff)[_i]), "s"(_gb) : "m0", "memory"); } } while (0)
; #define PG8_LDA(dst, b, h) do { _Pragma("unroll") for (int m = 0; m < 4; ++m) _Pragma("unroll") for (int k = 0; k < 2; ++k) dst[m][k] = *(const LAS bf16x8*)(lds + PG8_SA(b, h) + aoff + m * 2048 + k * 1024); } while (0)
; #define PG8_LDB(dst, b, h) do { _Pragma("unroll") for (int n = 0; n < 2; ++n) _Pragma("unroll") for (int k = 0; k < 2; ++k) dst[n][k] = *(const LAS bf16x8*)(lds + PG8_SB(b, h) + boff + n * 2048 + k * 1024); } while (0)
; #define PG8_MMA(ai, bj, At, Bt) do { __builtin_amdgcn_s_setprio(1); _Pragma("unroll") for (int m = 0; m < 4; ++m) _Pragma("unroll") for (int n = 0; n < 2; ++n) _Pragma("unroll") for (int k = 0; k < 2; ++k) \
;         acc[ai][bj][m][n] = __builtin_amdgcn_mfma_f32_16x16x32_bf16(Bt[n][k], At[m][k], acc[ai][bj][m][n], 0, 0, 0); __builtin_amdgcn_s_setprio(0); } while (0)
; #define PG8_WAIT_V(n) asm volatile("s_waitcnt vmcnt(" #n ")" ::: "memory")
; #define PG8_WAIT_L(n) asm volatile("s_waitcnt lgkmcnt(" #n ")" ::: "memory")
; template <class Epi, bool ALIGN_EPI>
; __device__ __forceinline__ void gemm_phase(LAS unsigned char* lds, const Gemm g, const StaticOrder& S, const Epi& E) {
;     ...
;         for (int t = 0; t < nt; t += 2) {
;             const bool last = (t == nt - 2);
;             const char* a1 = cA + (size_t)(t + 1) * kstep;
;             const char* a2 = last ? nA : cA + (size_t)(t + 2) * kstep; const char* b2 = last ? nB : cB + (size_t)(t + 2) * kstep;
;             const char* a3 = a2 + kstep; const char* b3 = b2 + kstep;
;             PG8_LDB(B0, 0, 0); PG8_LDB(B1, 0, 1); PG8_SCHED; PG8_LDA(At, 0, 0); PG8_STAGE(PG8_SA(1, 1), a1 + hstepA, voffA);
;             PG8_WAIT_V(8); PG8_WAIT_L(0); PG8_BAR; PG8_MMA(0, 0, At, B0); PG8_MMA(0, 1, At, B1); PG8_BAR; PG8_SCHED;
;             PG8_LDA(At, 0, 1); PG8_STAGE(PG8_SB(0, 0), b2, voffB); PG8_STAGE(PG8_SB(0, 1), b2 + hstepB, voffB); PG8_STAGE(PG8_SA(0, 0), a2, voffA);
;             PG8_WAIT_V(8); PG8_WAIT_L(0); PG8_BAR; PG8_MMA(1, 0, At, B0); PG8_MMA(1, 1, At, B1); PG8_BAR; PG8_SCHED;
.LBB0_200:
	s_add_u32 s4, s48, 0x100
	s_addc_u32 s5, s49, 0
	s_add_u32 s15, s54, 0x100
	s_addc_u32 s42, s55, 0
	s_mov_b32 s43, 0
	s_add_i32 s44, s43, 2
	s_cmp_eq_u32 s68, s43
	s_cselect_b32 s56, s0, s15
	s_cselect_b32 s57, s1, s42
	s_cselect_b32 s54, s94, s4
	s_cselect_b32 s55, s95, s5
	s_add_u32 s48, s56, 0x80
	s_addc_u32 s49, s57, 0
	s_add_u32 s43, s15, s38
	s_addc_u32 s45, s42, 0
	s_add_u32 s58, s43, 0xffffff80
	s_addc_u32 s59, s45, -1
	s_mov_b32 m0, s37
	s_nop 0
	global_load_lds_dwordx4 v0, s[58:59]
	s_nop 0
	s_mov_b32 m0, s41
	s_nop 0
	global_load_lds_dwordx4 v206, s[58:59]
	s_waitcnt vmcnt(8)
	s_waitcnt lgkmcnt(0)
	s_barrier
	s_setprio 1
	s_waitcnt lgkmcnt(0)
	v_mfma_f32_16x16x32_bf16 v[126:129], v[130:133], v[162:165], 0
	v_mfma_f32_16x16x32_bf16 v[126:129], v[134:137], v[166:169], v[126:129]
	v_mfma_f32_16x16x32_bf16 v[122:125], v[138:141], v[162:165], 0
	v_mfma_f32_16x16x32_bf16 v[122:125], v[142:145], v[166:169], v[122:125]
	v_mfma_f32_16x16x32_bf16 v[118:121], v[146:149], v[162:165], 0
	v_mfma_f32_16x16x32_bf16 v[118:121], v[150:153], v[166:169], v[118:121]
	v_mfma_f32_16x16x32_bf16 v[114:117], v[154:157], v[162:165], 0
	v_mfma_f32_16x16x32_bf16 v[114:117], v[158:161], v[166:169], v[114:117]
	v_mfma_f32_16x16x32_bf16 v[98:101], v[154:157], v[170:173], 0
	v_mfma_f32_16x16x32_bf16 v[98:101], v[158:161], v[174:177], v[98:101]
	v_mfma_f32_16x16x32_bf16 v[102:105], v[146:149], v[170:173], 0
	v_mfma_f32_16x16x32_bf16 v[102:105], v[150:153], v[174:177], v[102:105]
	v_mfma_f32_16x16x32_bf16 v[106:109], v[138:141], v[170:173], 0
	v_mfma_f32_16x16x32_bf16 v[106:109], v[142:145], v[174:177], v[106:109]
	v_mfma_f32_16x16x32_bf16 v[110:113], v[130:133], v[170:173], 0
	v_mfma_f32_16x16x32_bf16 v[110:113], v[134:137], v[174:177], v[110:113]
	v_mfma_f32_16x16x32_bf16 v[94:97], v[130:133], v[178:181], 0
	v_mfma_f32_16x16x32_bf16 v[94:97], v[134:137], v[182:185], v[94:97]
	v_mfma_f32_16x16x32_bf16 v[90:93], v[138:141], v[178:181], 0
	v_mfma_f32_16x16x32_bf16 v[90:93], v[142:145], v[182:185], v[90:93]
	v_mfma_f32_16x16x32_bf16 v[86:89], v[146:149], v[178:181], 0
	v_mfma_f32_16x16x32_bf16 v[86:89], v[150:153], v[182:185], v[86:89]
	v_mfma_f32_16x16x32_bf16 v[82:85], v[154:157], v[178:181], 0
	v_mfma_f32_16x16x32_bf16 v[82:85], v[158:161], v[182:185], v[82:85]
	v_mfma_f32_16x16x32_bf16 v[66:69], v[154:157], v[186:189], 0
	v_mfma_f32_16x16x32_bf16 v[66:69], v[158:161], v[190:193], v[66:69]
	v_mfma_f32_16x16x32_bf16 v[70:73], v[146:149], v[186:189], 0
	v_mfma_f32_16x16x32_bf16 v[70:73], v[150:153], v[190:193], v[70:73]
	v_mfma_f32_16x16x32_bf16 v[74:77], v[138:141], v[186:189], 0
	v_mfma_f32_16x16x32_bf16 v[74:77], v[142:145], v[190:193], v[74:77]
	v_mfma_f32_16x16x32_bf16 v[78:81], v[130:133], v[186:189], 0
	v_mfma_f32_16x16x32_bf16 v[78:81], v[134:137], v[190:193], v[78:81]
	s_setprio 0
	s_barrier
	ds_read_b128 v[162:165], v246 offset:16384
	ds_read_b128 v[166:169], v246 offset:17408
	ds_read_b128 v[170:173], v246 offset:18432
	ds_read_b128 v[174:177], v246 offset:19456
	ds_read_b128 v[178:181], v246 offset:20480
	ds_read_b128 v[182:185], v246 offset:21504
	ds_read_b128 v[186:189], v246 offset:22528
	ds_read_b128 v[190:193], v246 offset:23552
	s_mov_b32 m0, s46
	s_nop 0
	global_load_lds_dwordx4 v195, s[54:55]
	s_add_u32 s58, s54, s38
	s_mov_b32 m0, s26
	s_nop 0
	global_load_lds_dwordx4 v207, s[54:55]
	s_addc_u32 s59, s55, 0
	s_mov_b32 m0, s27
	s_nop 0
	global_load_lds_dwordx4 v195, s[58:59]
	s_nop 0
	s_mov_b32 m0, s30
	s_nop 0
	global_load_lds_dwordx4 v207, s[58:59]
	s_nop 0
	s_mov_b32 m0, s29
	s_nop 0
	global_load_lds_dwordx4 v0, s[56:57]
	s_nop 0
	s_mov_b32 m0, s17
	s_nop 0
	global_load_lds_dwordx4 v206, s[56:57]
	s_waitcnt vmcnt(8)
	s_waitcnt lgkmcnt(0)
	s_barrier
	s_setprio 1
	s_waitcnt lgkmcnt(0)
	v_mfma_f32_16x16x32_bf16 v[62:65], v[130:133], v[162:165], 0
	v_mfma_f32_16x16x32_bf16 v[62:65], v[134:137], v[166:169], v[62:65]
	v_mfma_f32_16x16x32_bf16 v[58:61], v[138:141], v[162:165], 0
	v_mfma_f32_16x16x32_bf16 v[58:61], v[142:145], v[166:169], v[58:61]
	v_mfma_f32_16x16x32_bf16 v[54:57], v[146:149], v[162:165], 0
	v_mfma_f32_16x16x32_bf16 v[54:57], v[150:153], v[166:169], v[54:57]
	v_mfma_f32_16x16x32_bf16 v[50:53], v[154:157], v[162:165], 0
	v_mfma_f32_16x16x32_bf16 v[50:53], v[158:161], v[166:169], v[50:53]
	v_mfma_f32_16x16x32_bf16 v[34:37], v[154:157], v[170:173], 0
	v_mfma_f32_16x16x32_bf16 v[34:37], v[158:161], v[174:177], v[34:37]
	v_mfma_f32_16x16x32_bf16 v[38:41], v[146:149], v[170:173], 0
	v_mfma_f32_16x16x32_bf16 v[38:41], v[150:153], v[174:177], v[38:41]
	v_mfma_f32_16x16x32_bf16 v[42:45], v[138:141], v[170:173], 0
	v_mfma_f32_16x16x32_bf16 v[42:45], v[142:145], v[174:177], v[42:45]
	v_mfma_f32_16x16x32_bf16 v[46:49], v[130:133], v[170:173], 0
	v_mfma_f32_16x16x32_bf16 v[46:49], v[134:137], v[174:177], v[46:49]
	v_mfma_f32_16x16x32_bf16 v[30:33], v[130:133], v[178:181], 0
	v_mfma_f32_16x16x32_bf16 v[30:33], v[134:137], v[182:185], v[30:33]
	v_mfma_f32_16x16x32_bf16 v[26:29], v[138:141], v[178:181], 0
	v_mfma_f32_16x16x32_bf16 v[26:29], v[142:145], v[182:185], v[26:29]
	v_mfma_f32_16x16x32_bf16 v[22:25], v[146:149], v[178:181], 0
	v_mfma_f32_16x16x32_bf16 v[22:25], v[150:153], v[182:185], v[22:25]
	v_mfma_f32_16x16x32_bf16 v[18:21], v[154:157], v[178:181], 0
	v_mfma_f32_16x16x32_bf16 v[18:21], v[158:161], v[182:185], v[18:21]
	v_mfma_f32_16x16x32_bf16 v[2:5], v[154:157], v[186:189], 0
	v_mfma_f32_16x16x32_bf16 v[2:5], v[158:161], v[190:193], v[2:5]
	v_mfma_f32_16x16x32_bf16 v[6:9], v[146:149], v[186:189], 0
	v_mfma_f32_16x16x32_bf16 v[6:9], v[150:153], v[190:193], v[6:9]
	v_mfma_f32_16x16x32_bf16 v[10:13], v[138:141], v[186:189], 0
	v_mfma_f32_16x16x32_bf16 v[10:13], v[142:145], v[190:193], v[10:13]
	v_mfma_f32_16x16x32_bf16 v[14:17], v[130:133], v[186:189], 0
	v_mfma_f32_16x16x32_bf16 v[14:17], v[134:137], v[190:193], v[14:17]
	s_setprio 0
	s_barrier
; #define PG8_STAGE(bufoff, gbase, voff) do { _Pragma("unroll") for (int _i = 0; _i < 2; ++_i) { \
;         const unsigned _m0 = ldsb + (unsigned)((bufoff) + _i * 8192); const char* _gb = (const char*)(gbase); \
;         asm volatile("s_mov_b32 m0, %0\n\ts_nop 0\n\tglobal_load_lds_dwordx4 %1, %2" :: "s"(_m0), "v"((voff)[_i]), "s"(_gb) : "m0", "memory"); } } while (0)
; #define PG8_LDA(dst, b, h) do { _Pragma("unroll") for (int m = 0; m < 4; ++m) _Pragma("unroll") for (int k = 0; k < 2; ++k) dst[m][k] = *(const LAS bf16x8*)(lds + PG8_SA(b, h) + aoff + m * 2048 + k * 1024); } while (0)
; #define PG8_LDB(dst, b, h) do { _Pragma("unroll") for (int n = 0; n < 2; ++n) _Pragma("unroll") for (int k = 0; k < 2; ++k) dst[n][k] = *(const LAS bf16x8*)(lds + PG8_SB(b, h) + boff + n * 2048 + k * 1024); } while (0)
; #define PG8_MMA(ai, bj, At, Bt) do { __builtin_amdgcn_s_setprio(1); _Pragma("unroll") for (int m = 0; m < 4; ++m) _Pragma("unroll") for (int n = 0; n < 2; ++n) _Pragma("unroll") for (int k = 0; k < 2; ++k) \
;         acc[ai][bj][m][n] = __builtin_amdgcn_mfma_f32_16x16x32_bf16(Bt[n][k], At[m][k], acc[ai][bj][m][n], 0, 0, 0); __builtin_amdgcn_s_setprio(0); } while (0)
; #define PG8_WAIT_V(n) asm volatile("s_waitcnt vmcnt(" #n ")" ::: "memory")
; #define PG8_WAIT_L(n) asm volatile("s_waitcnt lgkmcnt(" #n ")" ::: "memory")
; #define PG8_BAR __builtin_amdgcn_s_barrier()
; #define PG8_SCHED __builtin_amdgcn_sched_barrier(0)
; template <class Epi, bool ALIGN_EPI>
; __device__ __forceinline__ void gemm_phase(LAS unsigned char* lds, const Gemm g, const StaticOrder& S, const Epi& E) {
;     ...
;             PG8_LDB(B0, 1, 0); PG8_LDB(B1, 1, 1); PG8_SCHED; PG8_LDA(At, 1, 0); PG8_STAGE(PG8_SA(0, 1), a2 + hstepA, voffA);
;             PG8_WAIT_V(8); PG8_WAIT_L(0); PG8_BAR; PG8_MMA(0, 0, At, B0); PG8_MMA(0, 1, At, B1); PG8_BAR; PG8_SCHED;
;             PG8_LDA(At, 1, 1); PG8_STAGE(PG8_SB(1, 0), b3, voffB); PG8_STAGE(PG8_SB(1, 1), b3 + hstepB, voffB); PG8_STAGE(PG8_SA(1, 0), a3, voffA);
;             PG8_WAIT_V(8); PG8_WAIT_L(0); PG8_BAR; PG8_MMA(1, 0, At, B0); PG8_MMA(1, 1, At, B1); PG8_BAR; PG8_SCHED;
	v_add_u32_e32 v142, 0x18000, v245
	v_add_u32_e32 v158, 0x1c000, v245
	ds_read_b128 v[130:133], v142
	ds_read_b128 v[134:137], v142 offset:1024
	ds_read_b128 v[138:141], v142 offset:2048
	ds_read_b128 v[142:145], v142 offset:3072
	ds_read_b128 v[146:149], v158
	ds_read_b128 v[150:153], v158 offset:1024
	ds_read_b128 v[154:157], v158 offset:2048
	ds_read_b128 v[158:161], v158 offset:3072
	ds_read_b128 v[162:165], v246 offset:32768
	ds_read_b128 v[166:169], v246 offset:33792
	ds_read_b128 v[170:173], v246 offset:34816
	ds_read_b128 v[174:177], v246 offset:35840
	ds_read_b128 v[178:181], v246 offset:36864
	ds_read_b128 v[182:185], v246 offset:37888
	ds_read_b128 v[186:189], v246 offset:38912
	ds_read_b128 v[190:193], v246 offset:39936
	s_add_u32 s56, s56, s38
	s_addc_u32 s57, s57, 0
	s_mov_b32 m0, s31
	s_nop 0
	global_load_lds_dwordx4 v0, s[56:57]
	s_nop 0
	s_mov_b32 m0, s53
	s_nop 0
	global_load_lds_dwordx4 v206, s[56:57]
	s_waitcnt vmcnt(8)
	s_waitcnt lgkmcnt(0)
	s_barrier
	s_setprio 1
	s_waitcnt lgkmcnt(0)
	v_mfma_f32_16x16x32_bf16 v[126:129], v[130:133], v[162:165], v[126:129]
	v_mfma_f32_16x16x32_bf16 v[126:129], v[134:137], v[166:169], v[126:129]
	v_mfma_f32_16x16x32_bf16 v[122:125], v[138:141], v[162:165], v[122:125]
	v_mfma_f32_16x16x32_bf16 v[122:125], v[142:145], v[166:169], v[122:125]
	v_mfma_f32_16x16x32_bf16 v[118:121], v[146:149], v[162:165], v[118:121]
	v_mfma_f32_16x16x32_bf16 v[118:121], v[150:153], v[166:169], v[118:121]
	v_mfma_f32_16x16x32_bf16 v[114:117], v[154:157], v[162:165], v[114:117]
	v_mfma_f32_16x16x32_bf16 v[114:117], v[158:161], v[166:169], v[114:117]
	v_mfma_f32_16x16x32_bf16 v[98:101], v[154:157], v[170:173], v[98:101]
	v_mfma_f32_16x16x32_bf16 v[98:101], v[158:161], v[174:177], v[98:101]
	v_mfma_f32_16x16x32_bf16 v[102:105], v[146:149], v[170:173], v[102:105]
	v_mfma_f32_16x16x32_bf16 v[102:105], v[150:153], v[174:177], v[102:105]
	v_mfma_f32_16x16x32_bf16 v[106:109], v[138:141], v[170:173], v[106:109]
	v_mfma_f32_16x16x32_bf16 v[106:109], v[142:145], v[174:177], v[106:109]
	v_mfma_f32_16x16x32_bf16 v[110:113], v[130:133], v[170:173], v[110:113]
	v_mfma_f32_16x16x32_bf16 v[110:113], v[134:137], v[174:177], v[110:113]
	v_mfma_f32_16x16x32_bf16 v[94:97], v[130:133], v[178:181], v[94:97]
	v_mfma_f32_16x16x32_bf16 v[94:97], v[134:137], v[182:185], v[94:97]
	v_mfma_f32_16x16x32_bf16 v[90:93], v[138:141], v[178:181], v[90:93]
	v_mfma_f32_16x16x32_bf16 v[90:93], v[142:145], v[182:185], v[90:93]
	v_mfma_f32_16x16x32_bf16 v[86:89], v[146:149], v[178:181], v[86:89]
	v_mfma_f32_16x16x32_bf16 v[86:89], v[150:153], v[182:185], v[86:89]
	v_mfma_f32_16x16x32_bf16 v[82:85], v[154:157], v[178:181], v[82:85]
	v_mfma_f32_16x16x32_bf16 v[82:85], v[158:161], v[182:185], v[82:85]
	v_mfma_f32_16x16x32_bf16 v[66:69], v[154:157], v[186:189], v[66:69]
	v_mfma_f32_16x16x32_bf16 v[66:69], v[158:161], v[190:193], v[66:69]
	v_mfma_f32_16x16x32_bf16 v[70:73], v[146:149], v[186:189], v[70:73]
	v_mfma_f32_16x16x32_bf16 v[70:73], v[150:153], v[190:193], v[70:73]
	v_mfma_f32_16x16x32_bf16 v[74:77], v[138:141], v[186:189], v[74:77]
	v_mfma_f32_16x16x32_bf16 v[74:77], v[142:145], v[190:193], v[74:77]
	v_mfma_f32_16x16x32_bf16 v[78:81], v[130:133], v[186:189], v[78:81]
	v_mfma_f32_16x16x32_bf16 v[78:81], v[134:137], v[190:193], v[78:81]
	s_setprio 0
	s_barrier
	ds_read_b128 v[162:165], v246 offset:49152
	ds_read_b128 v[166:169], v246 offset:50176
	ds_read_b128 v[170:173], v246 offset:51200
	ds_read_b128 v[174:177], v246 offset:52224
	ds_read_b128 v[178:181], v246 offset:53248
	ds_read_b128 v[182:185], v246 offset:54272
	ds_read_b128 v[186:189], v246 offset:55296
	ds_read_b128 v[190:193], v246 offset:56320
	s_add_u32 s54, s54, 0x80
	s_addc_u32 s55, s55, 0
	s_mov_b32 m0, s85
	s_nop 0
	global_load_lds_dwordx4 v195, s[54:55]
	s_nop 0
	s_mov_b32 m0, s65
	s_nop 0
	global_load_lds_dwordx4 v207, s[54:55]
	s_add_u32 s54, s58, 0x80
	s_addc_u32 s55, s59, 0
	s_mov_b32 m0, s93
	s_nop 0
	global_load_lds_dwordx4 v195, s[54:55]
	s_nop 0
	s_mov_b32 m0, s28
	s_nop 0
	global_load_lds_dwordx4 v207, s[54:55]
	s_nop 0
	s_mov_b32 m0, s67
	s_nop 0
	global_load_lds_dwordx4 v0, s[48:49]
	s_nop 0
	s_mov_b32 m0, s92
	s_nop 0
	global_load_lds_dwordx4 v206, s[48:49]
	s_waitcnt vmcnt(8)
	s_waitcnt lgkmcnt(0)
	s_nop 0
	s_barrier
	s_setprio 1
	s_waitcnt lgkmcnt(0)
	v_mfma_f32_16x16x32_bf16 v[62:65], v[130:133], v[162:165], v[62:65]
	v_mfma_f32_16x16x32_bf16 v[62:65], v[134:137], v[166:169], v[62:65]
	v_mfma_f32_16x16x32_bf16 v[58:61], v[138:141], v[162:165], v[58:61]
	v_mfma_f32_16x16x32_bf16 v[58:61], v[142:145], v[166:169], v[58:61]
	v_mfma_f32_16x16x32_bf16 v[54:57], v[146:149], v[162:165], v[54:57]
	v_mfma_f32_16x16x32_bf16 v[54:57], v[150:153], v[166:169], v[54:57]
	v_mfma_f32_16x16x32_bf16 v[50:53], v[154:157], v[162:165], v[50:53]
	v_mfma_f32_16x16x32_bf16 v[50:53], v[158:161], v[166:169], v[50:53]
	v_mfma_f32_16x16x32_bf16 v[34:37], v[154:157], v[170:173], v[34:37]
	v_mfma_f32_16x16x32_bf16 v[34:37], v[158:161], v[174:177], v[34:37]
	v_mfma_f32_16x16x32_bf16 v[38:41], v[146:149], v[170:173], v[38:41]
	v_mfma_f32_16x16x32_bf16 v[38:41], v[150:153], v[174:177], v[38:41]
	v_mfma_f32_16x16x32_bf16 v[42:45], v[138:141], v[170:173], v[42:45]
	v_mfma_f32_16x16x32_bf16 v[42:45], v[142:145], v[174:177], v[42:45]
	v_mfma_f32_16x16x32_bf16 v[46:49], v[130:133], v[170:173], v[46:49]
	v_mfma_f32_16x16x32_bf16 v[46:49], v[134:137], v[174:177], v[46:49]
	v_mfma_f32_16x16x32_bf16 v[30:33], v[130:133], v[178:181], v[30:33]
	v_mfma_f32_16x16x32_bf16 v[30:33], v[134:137], v[182:185], v[30:33]
	v_mfma_f32_16x16x32_bf16 v[26:29], v[138:141], v[178:181], v[26:29]
	v_mfma_f32_16x16x32_bf16 v[26:29], v[142:145], v[182:185], v[26:29]
	v_mfma_f32_16x16x32_bf16 v[22:25], v[146:149], v[178:181], v[22:25]
	v_mfma_f32_16x16x32_bf16 v[22:25], v[150:153], v[182:185], v[22:25]
	v_mfma_f32_16x16x32_bf16 v[18:21], v[154:157], v[178:181], v[18:21]
	v_mfma_f32_16x16x32_bf16 v[18:21], v[158:161], v[182:185], v[18:21]
	v_mfma_f32_16x16x32_bf16 v[2:5], v[154:157], v[186:189], v[2:5]
	v_mfma_f32_16x16x32_bf16 v[2:5], v[158:161], v[190:193], v[2:5]
	v_mfma_f32_16x16x32_bf16 v[6:9], v[146:149], v[186:189], v[6:9]
	v_mfma_f32_16x16x32_bf16 v[6:9], v[150:153], v[190:193], v[6:9]
	v_mfma_f32_16x16x32_bf16 v[10:13], v[138:141], v[186:189], v[10:13]
	v_mfma_f32_16x16x32_bf16 v[10:13], v[142:145], v[190:193], v[10:13]
	v_mfma_f32_16x16x32_bf16 v[14:17], v[130:133], v[186:189], v[14:17]
	v_mfma_f32_16x16x32_bf16 v[14:17], v[134:137], v[190:193], v[14:17]
	s_setprio 0
	s_barrier
	s_add_u32 s4, s4, 0x100
	s_addc_u32 s5, s5, 0
	s_add_u32 s15, s15, 0x100
	s_addc_u32 s42, s42, 0
	s_cmp_ge_u32 s44, s36
	s_mov_b32 s43, s44
; #define PG8_STAGE(bufoff, gbase, voff) do { _Pragma("unroll") for (int _i = 0; _i < 2; ++_i) { \
;         const unsigned _m0 = ldsb + (unsigned)((bufoff) + _i * 8192); const char* _gb = (const char*)(gbase); \
;         asm volatile("s_mov_b32 m0, %0\n\ts_nop 0\n\tglobal_load_lds_dwordx4 %1, %2" :: "s"(_m0), "v"((voff)[_i]), "s"(_gb) : "m0", "memory"); } } while (0)
; #define PG8_LDA(dst, b, h) do { _Pragma("unroll") for (int m = 0; m < 4; ++m) _Pragma("unroll") for (int k = 0; k < 2; ++k) dst[m][k] = *(const LAS bf16x8*)(lds + PG8_SA(b, h) + aoff + m * 2048 + k * 1024); } while (0)
; #define PG8_LDB(dst, b, h) do { _Pragma("unroll") for (int n = 0; n < 2; ++n) _Pragma("unroll") for (int k = 0; k < 2; ++k) dst[n][k] = *(const LAS bf16x8*)(lds + PG8_SB(b, h) + boff + n * 2048 + k * 1024); } while (0)
; #define PG8_MMA(ai, bj, At, Bt) do { __builtin_amdgcn_s_setprio(1); _Pragma("unroll") for (int m = 0; m < 4; ++m) _Pragma("unroll") for (int n = 0; n < 2; ++n) _Pragma("unroll") for (int k = 0; k < 2; ++k) \
;         acc[ai][bj][m][n] = __builtin_amdgcn_mfma_f32_16x16x32_bf16(Bt[n][k], At[m][k], acc[ai][bj][m][n], 0, 0, 0); __builtin_amdgcn_s_setprio(0); } while (0)
; #define PG8_WAIT_V(n) asm volatile("s_waitcnt vmcnt(" #n ")" ::: "memory")
; #define PG8_WAIT_L(n) asm volatile("s_waitcnt lgkmcnt(" #n ")" ::: "memory")
; template <class Epi, bool ALIGN_EPI>
; __device__ __forceinline__ void gemm_phase(LAS unsigned char* lds, const Gemm g, const StaticOrder& S, const Epi& E) {
;     ...
;         for (int t = 0; t < nt; t += 2) {
;             const bool last = (t == nt - 2);
;             const char* a1 = cA + (size_t)(t + 1) * kstep;
;             const char* a2 = last ? nA : cA + (size_t)(t + 2) * kstep; const char* b2 = last ? nB : cB + (size_t)(t + 2) * kstep;
;             const char* a3 = a2 + kstep; const char* b3 = b2 + kstep;
;             PG8_LDB(B0, 0, 0); PG8_LDB(B1, 0, 1); PG8_SCHED; PG8_LDA(At, 0, 0); PG8_STAGE(PG8_SA(1, 1), a1 + hstepA, voffA);
;             PG8_WAIT_V(8); PG8_WAIT_L(0); PG8_BAR; PG8_MMA(0, 0, At, B0); PG8_MMA(0, 1, At, B1); PG8_BAR; PG8_SCHED;
;             PG8_LDA(At, 0, 1); PG8_STAGE(PG8_SB(0, 0), b2, voffB); PG8_STAGE(PG8_SB(0, 1), b2 + hstepB, voffB); PG8_STAGE(PG8_SA(0, 0), a2, voffA);
;             PG8_WAIT_V(8); PG8_WAIT_L(0); PG8_BAR; PG8_MMA(1, 0, At, B0); PG8_MMA(1, 1, At, B1); PG8_BAR; PG8_SCHED;
.LBB0_201:
	v_add_u32_e32 v142, 0x10000, v245
	v_add_u32_e32 v158, 0x14000, v245
	ds_read_b128 v[130:133], v142
	ds_read_b128 v[134:137], v142 offset:1024
	ds_read_b128 v[138:141], v142 offset:2048
	ds_read_b128 v[142:145], v142 offset:3072
	ds_read_b128 v[146:149], v158
	ds_read_b128 v[150:153], v158 offset:1024
	ds_read_b128 v[154:157], v158 offset:2048
	ds_read_b128 v[158:161], v158 offset:3072
	s_add_i32 s44, s43, 2
	s_cmp_eq_u32 s68, s43
	s_cselect_b32 s56, s0, s15
	s_cselect_b32 s57, s1, s42
	s_cselect_b32 s54, s94, s4
	s_cselect_b32 s55, s95, s5
	s_add_u32 s48, s56, 0x80
	s_addc_u32 s49, s57, 0
	ds_read_b128 v[162:165], v246
	ds_read_b128 v[166:169], v246 offset:1024
	ds_read_b128 v[170:173], v246 offset:2048
	ds_read_b128 v[174:177], v246 offset:3072
	ds_read_b128 v[178:181], v246 offset:4096
	ds_read_b128 v[182:185], v246 offset:5120
	ds_read_b128 v[186:189], v246 offset:6144
	ds_read_b128 v[190:193], v246 offset:7168
	s_add_u32 s43, s15, s38
	s_addc_u32 s45, s42, 0
	s_add_u32 s58, s43, 0xffffff80
	s_addc_u32 s59, s45, -1
	s_mov_b32 m0, s37
	s_nop 0
	global_load_lds_dwordx4 v0, s[58:59]
	s_nop 0
	s_mov_b32 m0, s41
	s_nop 0
	global_load_lds_dwordx4 v206, s[58:59]
	s_waitcnt vmcnt(8)
	s_waitcnt lgkmcnt(0)
	s_barrier
	s_setprio 1
	s_waitcnt lgkmcnt(0)
	v_mfma_f32_16x16x32_bf16 v[126:129], v[130:133], v[162:165], v[126:129]
	v_mfma_f32_16x16x32_bf16 v[126:129], v[134:137], v[166:169], v[126:129]
	v_mfma_f32_16x16x32_bf16 v[122:125], v[138:141], v[162:165], v[122:125]
	v_mfma_f32_16x16x32_bf16 v[122:125], v[142:145], v[166:169], v[122:125]
	v_mfma_f32_16x16x32_bf16 v[118:121], v[146:149], v[162:165], v[118:121]
	v_mfma_f32_16x16x32_bf16 v[118:121], v[150:153], v[166:169], v[118:121]
	v_mfma_f32_16x16x32_bf16 v[114:117], v[154:157], v[162:165], v[114:117]
	v_mfma_f32_16x16x32_bf16 v[114:117], v[158:161], v[166:169], v[114:117]
	v_mfma_f32_16x16x32_bf16 v[98:101], v[154:157], v[170:173], v[98:101]
	v_mfma_f32_16x16x32_bf16 v[98:101], v[158:161], v[174:177], v[98:101]
	v_mfma_f32_16x16x32_bf16 v[102:105], v[146:149], v[170:173], v[102:105]
	v_mfma_f32_16x16x32_bf16 v[102:105], v[150:153], v[174:177], v[102:105]
	v_mfma_f32_16x16x32_bf16 v[106:109], v[138:141], v[170:173], v[106:109]
	v_mfma_f32_16x16x32_bf16 v[106:109], v[142:145], v[174:177], v[106:109]
	v_mfma_f32_16x16x32_bf16 v[110:113], v[130:133], v[170:173], v[110:113]
	v_mfma_f32_16x16x32_bf16 v[110:113], v[134:137], v[174:177], v[110:113]
	v_mfma_f32_16x16x32_bf16 v[94:97], v[130:133], v[178:181], v[94:97]
	v_mfma_f32_16x16x32_bf16 v[94:97], v[134:137], v[182:185], v[94:97]
	v_mfma_f32_16x16x32_bf16 v[90:93], v[138:141], v[178:181], v[90:93]
	v_mfma_f32_16x16x32_bf16 v[90:93], v[142:145], v[182:185], v[90:93]
	v_mfma_f32_16x16x32_bf16 v[86:89], v[146:149], v[178:181], v[86:89]
	v_mfma_f32_16x16x32_bf16 v[86:89], v[150:153], v[182:185], v[86:89]
	v_mfma_f32_16x16x32_bf16 v[82:85], v[154:157], v[178:181], v[82:85]
	v_mfma_f32_16x16x32_bf16 v[82:85], v[158:161], v[182:185], v[82:85]
	v_mfma_f32_16x16x32_bf16 v[66:69], v[154:157], v[186:189], v[66:69]
	v_mfma_f32_16x16x32_bf16 v[66:69], v[158:161], v[190:193], v[66:69]
	v_mfma_f32_16x16x32_bf16 v[70:73], v[146:149], v[186:189], v[70:73]
	v_mfma_f32_16x16x32_bf16 v[70:73], v[150:153], v[190:193], v[70:73]
	v_mfma_f32_16x16x32_bf16 v[74:77], v[138:141], v[186:189], v[74:77]
	v_mfma_f32_16x16x32_bf16 v[74:77], v[142:145], v[190:193], v[74:77]
	v_mfma_f32_16x16x32_bf16 v[78:81], v[130:133], v[186:189], v[78:81]
	v_mfma_f32_16x16x32_bf16 v[78:81], v[134:137], v[190:193], v[78:81]
	s_setprio 0
	s_barrier
	ds_read_b128 v[162:165], v246 offset:16384
	ds_read_b128 v[166:169], v246 offset:17408
	ds_read_b128 v[170:173], v246 offset:18432
	ds_read_b128 v[174:177], v246 offset:19456
	ds_read_b128 v[178:181], v246 offset:20480
	ds_read_b128 v[182:185], v246 offset:21504
	ds_read_b128 v[186:189], v246 offset:22528
	ds_read_b128 v[190:193], v246 offset:23552
	s_mov_b32 m0, s46
	s_nop 0
	global_load_lds_dwordx4 v195, s[54:55]
	s_add_u32 s58, s54, s38
	s_mov_b32 m0, s26
	s_nop 0
	global_load_lds_dwordx4 v207, s[54:55]
	s_addc_u32 s59, s55, 0
	s_mov_b32 m0, s27
	s_nop 0
	global_load_lds_dwordx4 v195, s[58:59]
	s_nop 0
	s_mov_b32 m0, s30
	s_nop 0
	global_load_lds_dwordx4 v207, s[58:59]
	s_nop 0
	s_mov_b32 m0, s29
	s_nop 0
	global_load_lds_dwordx4 v0, s[56:57]
	s_nop 0
	s_mov_b32 m0, s17
	s_nop 0
	global_load_lds_dwordx4 v206, s[56:57]
	s_waitcnt vmcnt(8)
	s_waitcnt lgkmcnt(0)
	s_barrier
	s_setprio 1
	s_waitcnt lgkmcnt(0)
	v_mfma_f32_16x16x32_bf16 v[62:65], v[130:133], v[162:165], v[62:65]
	v_mfma_f32_16x16x32_bf16 v[62:65], v[134:137], v[166:169], v[62:65]
	v_mfma_f32_16x16x32_bf16 v[58:61], v[138:141], v[162:165], v[58:61]
	v_mfma_f32_16x16x32_bf16 v[58:61], v[142:145], v[166:169], v[58:61]
	v_mfma_f32_16x16x32_bf16 v[54:57], v[146:149], v[162:165], v[54:57]
	v_mfma_f32_16x16x32_bf16 v[54:57], v[150:153], v[166:169], v[54:57]
	v_mfma_f32_16x16x32_bf16 v[50:53], v[154:157], v[162:165], v[50:53]
	v_mfma_f32_16x16x32_bf16 v[50:53], v[158:161], v[166:169], v[50:53]
	v_mfma_f32_16x16x32_bf16 v[34:37], v[154:157], v[170:173], v[34:37]
	v_mfma_f32_16x16x32_bf16 v[34:37], v[158:161], v[174:177], v[34:37]
	v_mfma_f32_16x16x32_bf16 v[38:41], v[146:149], v[170:173], v[38:41]
	v_mfma_f32_16x16x32_bf16 v[38:41], v[150:153], v[174:177], v[38:41]
	v_mfma_f32_16x16x32_bf16 v[42:45], v[138:141], v[170:173], v[42:45]
	v_mfma_f32_16x16x32_bf16 v[42:45], v[142:145], v[174:177], v[42:45]
	v_mfma_f32_16x16x32_bf16 v[46:49], v[130:133], v[170:173], v[46:49]
	v_mfma_f32_16x16x32_bf16 v[46:49], v[134:137], v[174:177], v[46:49]
	v_mfma_f32_16x16x32_bf16 v[30:33], v[130:133], v[178:181], v[30:33]
	v_mfma_f32_16x16x32_bf16 v[30:33], v[134:137], v[182:185], v[30:33]
	v_mfma_f32_16x16x32_bf16 v[26:29], v[138:141], v[178:181], v[26:29]
	v_mfma_f32_16x16x32_bf16 v[26:29], v[142:145], v[182:185], v[26:29]
	v_mfma_f32_16x16x32_bf16 v[22:25], v[146:149], v[178:181], v[22:25]
	v_mfma_f32_16x16x32_bf16 v[22:25], v[150:153], v[182:185], v[22:25]
	v_mfma_f32_16x16x32_bf16 v[18:21], v[154:157], v[178:181], v[18:21]
	v_mfma_f32_16x16x32_bf16 v[18:21], v[158:161], v[182:185], v[18:21]
	v_mfma_f32_16x16x32_bf16 v[2:5], v[154:157], v[186:189], v[2:5]
	v_mfma_f32_16x16x32_bf16 v[2:5], v[158:161], v[190:193], v[2:5]
	v_mfma_f32_16x16x32_bf16 v[6:9], v[146:149], v[186:189], v[6:9]
	v_mfma_f32_16x16x32_bf16 v[6:9], v[150:153], v[190:193], v[6:9]
	v_mfma_f32_16x16x32_bf16 v[10:13], v[138:141], v[186:189], v[10:13]
	v_mfma_f32_16x16x32_bf16 v[10:13], v[142:145], v[190:193], v[10:13]
	v_mfma_f32_16x16x32_bf16 v[14:17], v[130:133], v[186:189], v[14:17]
	v_mfma_f32_16x16x32_bf16 v[14:17], v[134:137], v[190:193], v[14:17]
	s_setprio 0
	s_barrier
; #define PG8_STAGE(bufoff, gbase, voff) do { _Pragma("unroll") for (int _i = 0; _i < 2; ++_i) { \
;         const unsigned _m0 = ldsb + (unsigned)((bufoff) + _i * 8192); const char* _gb = (const char*)(gbase); \
;         asm volatile("s_mov_b32 m0, %0\n\ts_nop 0\n\tglobal_load_lds_dwordx4 %1, %2" :: "s"(_m0), "v"((voff)[_i]), "s"(_gb) : "m0", "memory"); } } while (0)
; #define PG8_LDA(dst, b, h) do { _Pragma("unroll") for (int m = 0; m < 4; ++m) _Pragma("unroll") for (int k = 0; k < 2; ++k) dst[m][k] = *(const LAS bf16x8*)(lds + PG8_SA(b, h) + aoff + m * 2048 + k * 1024); } while (0)
; #define PG8_LDB(dst, b, h) do { _Pragma("unroll") for (int n = 0; n < 2; ++n) _Pragma("unroll") for (int k = 0; k < 2; ++k) dst[n][k] = *(const LAS bf16x8*)(lds + PG8_SB(b, h) + boff + n * 2048 + k * 1024); } while (0)
; #define PG8_MMA(ai, bj, At, Bt) do { __builtin_amdgcn_s_setprio(1); _Pragma("unroll") for (int m = 0; m < 4; ++m) _Pragma("unroll") for (int n = 0; n < 2; ++n) _Pragma("unroll") for (int k = 0; k < 2; ++k) \
;         acc[ai][bj][m][n] = __builtin_amdgcn_mfma_f32_16x16x32_bf16(Bt[n][k], At[m][k], acc[ai][bj][m][n], 0, 0, 0); __builtin_amdgcn_s_setprio(0); } while (0)
; #define PG8_WAIT_V(n) asm volatile("s_waitcnt vmcnt(" #n ")" ::: "memory")
; #define PG8_WAIT_L(n) asm volatile("s_waitcnt lgkmcnt(" #n ")" ::: "memory")
; #define PG8_BAR __builtin_amdgcn_s_barrier()
; #define PG8_SCHED __builtin_amdgcn_sched_barrier(0)
; template <class Epi, bool ALIGN_EPI>
; __device__ __forceinline__ void gemm_phase(LAS unsigned char* lds, const Gemm g, const StaticOrder& S, const Epi& E) {
;     ...
;             PG8_LDB(B0, 1, 0); PG8_LDB(B1, 1, 1); PG8_SCHED; PG8_LDA(At, 1, 0); PG8_STAGE(PG8_SA(0, 1), a2 + hstepA, voffA);
;             PG8_WAIT_V(8); PG8_WAIT_L(0); PG8_BAR; PG8_MMA(0, 0, At, B0); PG8_MMA(0, 1, At, B1); PG8_BAR; PG8_SCHED;
;             PG8_LDA(At, 1, 1); PG8_STAGE(PG8_SB(1, 0), b3, voffB); PG8_STAGE(PG8_SB(1, 1), b3 + hstepB, voffB); PG8_STAGE(PG8_SA(1, 0), a3, voffA);
;             PG8_WAIT_V(8); PG8_WAIT_L(0); PG8_BAR; PG8_MMA(1, 0, At, B0); PG8_MMA(1, 1, At, B1); PG8_BAR; PG8_SCHED;
;         }
;         if constexpr (ALIGN_EPI) { if (wr == 0) PG8_BAR; }
	v_add_u32_e32 v142, 0x18000, v245
	v_add_u32_e32 v158, 0x1c000, v245
	ds_read_b128 v[130:133], v142
	ds_read_b128 v[134:137], v142 offset:1024
	ds_read_b128 v[138:141], v142 offset:2048
	ds_read_b128 v[142:145], v142 offset:3072
	ds_read_b128 v[146:149], v158
	ds_read_b128 v[150:153], v158 offset:1024
	ds_read_b128 v[154:157], v158 offset:2048
	ds_read_b128 v[158:161], v158 offset:3072
	ds_read_b128 v[162:165], v246 offset:32768
	ds_read_b128 v[166:169], v246 offset:33792
	ds_read_b128 v[170:173], v246 offset:34816
	ds_read_b128 v[174:177], v246 offset:35840
	ds_read_b128 v[178:181], v246 offset:36864
	ds_read_b128 v[182:185], v246 offset:37888
	ds_read_b128 v[186:189], v246 offset:38912
	ds_read_b128 v[190:193], v246 offset:39936
	s_add_u32 s56, s56, s38
	s_addc_u32 s57, s57, 0
	s_mov_b32 m0, s31
	s_nop 0
	global_load_lds_dwordx4 v0, s[56:57]
	s_nop 0
	s_mov_b32 m0, s53
	s_nop 0
	global_load_lds_dwordx4 v206, s[56:57]
	s_waitcnt vmcnt(8)
	s_waitcnt lgkmcnt(0)
	s_barrier
	s_setprio 1
	s_waitcnt lgkmcnt(0)
	v_mfma_f32_16x16x32_bf16 v[126:129], v[130:133], v[162:165], v[126:129]
	v_mfma_f32_16x16x32_bf16 v[126:129], v[134:137], v[166:169], v[126:129]
	v_mfma_f32_16x16x32_bf16 v[122:125], v[138:141], v[162:165], v[122:125]
	v_mfma_f32_16x16x32_bf16 v[122:125], v[142:145], v[166:169], v[122:125]
	v_mfma_f32_16x16x32_bf16 v[118:121], v[146:149], v[162:165], v[118:121]
	v_mfma_f32_16x16x32_bf16 v[118:121], v[150:153], v[166:169], v[118:121]
	v_mfma_f32_16x16x32_bf16 v[114:117], v[154:157], v[162:165], v[114:117]
	v_mfma_f32_16x16x32_bf16 v[114:117], v[158:161], v[166:169], v[114:117]
	v_mfma_f32_16x16x32_bf16 v[98:101], v[154:157], v[170:173], v[98:101]
	v_mfma_f32_16x16x32_bf16 v[98:101], v[158:161], v[174:177], v[98:101]
	v_mfma_f32_16x16x32_bf16 v[102:105], v[146:149], v[170:173], v[102:105]
	v_mfma_f32_16x16x32_bf16 v[102:105], v[150:153], v[174:177], v[102:105]
	v_mfma_f32_16x16x32_bf16 v[106:109], v[138:141], v[170:173], v[106:109]
	v_mfma_f32_16x16x32_bf16 v[106:109], v[142:145], v[174:177], v[106:109]
	v_mfma_f32_16x16x32_bf16 v[110:113], v[130:133], v[170:173], v[110:113]
	v_mfma_f32_16x16x32_bf16 v[110:113], v[134:137], v[174:177], v[110:113]
	v_mfma_f32_16x16x32_bf16 v[94:97], v[130:133], v[178:181], v[94:97]
	v_mfma_f32_16x16x32_bf16 v[94:97], v[134:137], v[182:185], v[94:97]
	v_mfma_f32_16x16x32_bf16 v[90:93], v[138:141], v[178:181], v[90:93]
	v_mfma_f32_16x16x32_bf16 v[90:93], v[142:145], v[182:185], v[90:93]
	v_mfma_f32_16x16x32_bf16 v[86:89], v[146:149], v[178:181], v[86:89]
	v_mfma_f32_16x16x32_bf16 v[86:89], v[150:153], v[182:185], v[86:89]
	v_mfma_f32_16x16x32_bf16 v[82:85], v[154:157], v[178:181], v[82:85]
	v_mfma_f32_16x16x32_bf16 v[82:85], v[158:161], v[182:185], v[82:85]
	v_mfma_f32_16x16x32_bf16 v[66:69], v[154:157], v[186:189], v[66:69]
	v_mfma_f32_16x16x32_bf16 v[66:69], v[158:161], v[190:193], v[66:69]
	v_mfma_f32_16x16x32_bf16 v[70:73], v[146:149], v[186:189], v[70:73]
	v_mfma_f32_16x16x32_bf16 v[70:73], v[150:153], v[190:193], v[70:73]
	v_mfma_f32_16x16x32_bf16 v[74:77], v[138:141], v[186:189], v[74:77]
	v_mfma_f32_16x16x32_bf16 v[74:77], v[142:145], v[190:193], v[74:77]
	v_mfma_f32_16x16x32_bf16 v[78:81], v[130:133], v[186:189], v[78:81]
	v_mfma_f32_16x16x32_bf16 v[78:81], v[134:137], v[190:193], v[78:81]
	s_setprio 0
	s_barrier
	ds_read_b128 v[162:165], v246 offset:49152
	ds_read_b128 v[166:169], v246 offset:50176
	ds_read_b128 v[170:173], v246 offset:51200
	ds_read_b128 v[174:177], v246 offset:52224
	ds_read_b128 v[178:181], v246 offset:53248
	ds_read_b128 v[182:185], v246 offset:54272
	ds_read_b128 v[186:189], v246 offset:55296
	ds_read_b128 v[190:193], v246 offset:56320
	s_add_u32 s54, s54, 0x80
	s_addc_u32 s55, s55, 0
	s_mov_b32 m0, s85
	s_nop 0
	global_load_lds_dwordx4 v195, s[54:55]
	s_nop 0
	s_mov_b32 m0, s65
	s_nop 0
	global_load_lds_dwordx4 v207, s[54:55]
	s_add_u32 s54, s58, 0x80
	s_addc_u32 s55, s59, 0
	s_mov_b32 m0, s93
	s_nop 0
	global_load_lds_dwordx4 v195, s[54:55]
	s_nop 0
	s_mov_b32 m0, s28
	s_nop 0
	global_load_lds_dwordx4 v207, s[54:55]
	s_nop 0
	s_mov_b32 m0, s67
	s_nop 0
	global_load_lds_dwordx4 v0, s[48:49]
	s_nop 0
	s_mov_b32 m0, s92
	s_nop 0
	global_load_lds_dwordx4 v206, s[48:49]
	s_waitcnt vmcnt(8)
	s_waitcnt lgkmcnt(0)
	s_nop 0
	s_barrier
	s_setprio 1
	s_waitcnt lgkmcnt(0)
	v_mfma_f32_16x16x32_bf16 v[62:65], v[130:133], v[162:165], v[62:65]
	v_mfma_f32_16x16x32_bf16 v[62:65], v[134:137], v[166:169], v[62:65]
	v_mfma_f32_16x16x32_bf16 v[58:61], v[138:141], v[162:165], v[58:61]
	v_mfma_f32_16x16x32_bf16 v[58:61], v[142:145], v[166:169], v[58:61]
	v_mfma_f32_16x16x32_bf16 v[54:57], v[146:149], v[162:165], v[54:57]
	v_mfma_f32_16x16x32_bf16 v[54:57], v[150:153], v[166:169], v[54:57]
	v_mfma_f32_16x16x32_bf16 v[50:53], v[154:157], v[162:165], v[50:53]
	v_mfma_f32_16x16x32_bf16 v[50:53], v[158:161], v[166:169], v[50:53]
	v_mfma_f32_16x16x32_bf16 v[34:37], v[154:157], v[170:173], v[34:37]
	v_mfma_f32_16x16x32_bf16 v[34:37], v[158:161], v[174:177], v[34:37]
	v_mfma_f32_16x16x32_bf16 v[38:41], v[146:149], v[170:173], v[38:41]
	v_mfma_f32_16x16x32_bf16 v[38:41], v[150:153], v[174:177], v[38:41]
	v_mfma_f32_16x16x32_bf16 v[42:45], v[138:141], v[170:173], v[42:45]
	v_mfma_f32_16x16x32_bf16 v[42:45], v[142:145], v[174:177], v[42:45]
	v_mfma_f32_16x16x32_bf16 v[46:49], v[130:133], v[170:173], v[46:49]
	v_mfma_f32_16x16x32_bf16 v[46:49], v[134:137], v[174:177], v[46:49]
	v_mfma_f32_16x16x32_bf16 v[30:33], v[130:133], v[178:181], v[30:33]
	v_mfma_f32_16x16x32_bf16 v[30:33], v[134:137], v[182:185], v[30:33]
	v_mfma_f32_16x16x32_bf16 v[26:29], v[138:141], v[178:181], v[26:29]
	v_mfma_f32_16x16x32_bf16 v[26:29], v[142:145], v[182:185], v[26:29]
	v_mfma_f32_16x16x32_bf16 v[22:25], v[146:149], v[178:181], v[22:25]
	v_mfma_f32_16x16x32_bf16 v[22:25], v[150:153], v[182:185], v[22:25]
	v_mfma_f32_16x16x32_bf16 v[18:21], v[154:157], v[178:181], v[18:21]
	v_mfma_f32_16x16x32_bf16 v[18:21], v[158:161], v[182:185], v[18:21]
	v_mfma_f32_16x16x32_bf16 v[2:5], v[154:157], v[186:189], v[2:5]
	v_mfma_f32_16x16x32_bf16 v[2:5], v[158:161], v[190:193], v[2:5]
	v_mfma_f32_16x16x32_bf16 v[6:9], v[146:149], v[186:189], v[6:9]
	v_mfma_f32_16x16x32_bf16 v[6:9], v[150:153], v[190:193], v[6:9]
	v_mfma_f32_16x16x32_bf16 v[10:13], v[138:141], v[186:189], v[10:13]
	v_mfma_f32_16x16x32_bf16 v[10:13], v[142:145], v[190:193], v[10:13]
	v_mfma_f32_16x16x32_bf16 v[14:17], v[130:133], v[186:189], v[14:17]
	v_mfma_f32_16x16x32_bf16 v[14:17], v[134:137], v[190:193], v[14:17]
	s_setprio 0
	s_barrier
	s_add_u32 s4, s4, 0x100
	s_addc_u32 s5, s5, 0
	s_add_u32 s15, s15, 0x100
	s_addc_u32 s42, s42, 0
	s_cmp_ge_u32 s44, s36
	s_mov_b32 s43, s44
	s_cbranch_scc0 .LBB0_201
	v_readlane_b32 s4, v255, 6
	v_readlane_b32 s5, v255, 7
	s_and_b64 vcc, exec, s[4:5]
	s_cbranch_vccz .LBB0_204
	s_barrier

; #define PG8_STAGE(bufoff, gbase, voff) do { _Pragma("unroll") for (int _i = 0; _i < 2; ++_i) { \
;         const unsigned _m0 = ldsb + (unsigned)((bufoff) + _i * 8192); const char* _gb = (const char*)(gbase); \
;         asm volatile("s_mov_b32 m0, %0\n\ts_nop 0\n\tglobal_load_lds_dwordx4 %1, %2" :: "s"(_m0), "v"((voff)[_i]), "s"(_gb) : "m0", "memory"); } } while (0)
; #define PG8_LDA(dst, b, h) do { _Pragma("unroll") for (int m = 0; m < 4; ++m) _Pragma("unroll") for (int k = 0; k < 2; ++k) dst[m][k] = *(const LAS bf16x8*)(lds + PG8_SA(b, h) + aoff + m * 2048 + k * 1024); } while (0)
; #define PG8_LDB(dst, b, h) do { _Pragma("unroll") for (int n = 0; n < 2; ++n) _Pragma("unroll") for (int k = 0; k < 2; ++k) dst[n][k] = *(const LAS bf16x8*)(lds + PG8_SB(b, h) + boff + n * 2048 + k * 1024); } while (0)
; #define PG8_MMA(ai, bj, At, Bt) do { __builtin_amdgcn_s_setprio(1); _Pragma("unroll") for (int m = 0; m < 4; ++m) _Pragma("unroll") for (int n = 0; n < 2; ++n) _Pragma("unroll") for (int k = 0; k < 2; ++k) \
;         acc[ai][bj][m][n] = __builtin_amdgcn_mfma_f32_16x16x32_bf16(Bt[n][k], At[m][k], acc[ai][bj][m][n], 0, 0, 0); __builtin_amdgcn_s_setprio(0); } while (0)
; #define PG8_WAIT_V(n) asm volatile("s_waitcnt vmcnt(" #n ")" ::: "memory")
; #define PG8_WAIT_L(n) asm volatile("s_waitcnt lgkmcnt(" #n ")" ::: "memory")
; template <class Epi, bool ALIGN_EPI>
; __device__ __forceinline__ void gemm_phase(LAS unsigned char* lds, const Gemm g, const StaticOrder& S, const Epi& E) {
;     ...
;         for (int t = 0; t < nt; t += 2) {
;             const bool last = (t == nt - 2);
;             const char* a1 = cA + (size_t)(t + 1) * kstep;
;             const char* a2 = last ? nA : cA + (size_t)(t + 2) * kstep; const char* b2 = last ? nB : cB + (size_t)(t + 2) * kstep;
;             const char* a3 = a2 + kstep; const char* b3 = b2 + kstep;
;             PG8_LDB(B0, 0, 0); PG8_LDB(B1, 0, 1); PG8_SCHED; PG8_LDA(At, 0, 0); PG8_STAGE(PG8_SA(1, 1), a1 + hstepA, voffA);
;             PG8_WAIT_V(8); PG8_WAIT_L(0); PG8_BAR; PG8_MMA(0, 0, At, B0); PG8_MMA(0, 1, At, B1); PG8_BAR; PG8_SCHED;
;             PG8_LDA(At, 0, 1); PG8_STAGE(PG8_SB(0, 0), b2, voffB); PG8_STAGE(PG8_SB(0, 1), b2 + hstepB, voffB); PG8_STAGE(PG8_SA(0, 0), a2, voffA);
;             PG8_WAIT_V(8); PG8_WAIT_L(0); PG8_BAR; PG8_MMA(1, 0, At, B0); PG8_MMA(1, 1, At, B1); PG8_BAR; PG8_SCHED;
.LBB0_270:
	s_add_u32 s4, s56, 0x100
	s_addc_u32 s5, s57, 0
	s_add_u32 s0, s58, 0x40080
	s_addc_u32 s1, s59, 0
	s_mov_b32 s44, 0
	s_add_i32 s55, s44, 2
	s_add_u32 s45, s0, 0xfffc0080
	s_addc_u32 s56, s1, -1
	s_cmp_eq_u32 s68, s44
	s_cselect_b32 s60, s96, s45
	s_cselect_b32 s61, s97, s56
	s_cselect_b32 s58, s48, s4
	s_cselect_b32 s59, s49, s5
	s_add_u32 s56, s60, 0x80
	s_addc_u32 s57, s61, 0
	s_mov_b32 m0, s41
	s_nop 0
	global_load_lds_dwordx4 v165, s[0:1]
	s_nop 0
	s_mov_b32 m0, s30
	s_nop 0
	global_load_lds_dwordx4 v171, s[0:1]
	s_waitcnt vmcnt(8)
	s_waitcnt lgkmcnt(0)
	s_barrier
	s_setprio 1
	s_waitcnt lgkmcnt(0)
	v_mfma_f32_16x16x32_bf16 v[126:129], v[130:133], v[182:185], 0
	v_mfma_f32_16x16x32_bf16 v[126:129], v[134:137], v[186:189], v[126:129]
	v_mfma_f32_16x16x32_bf16 v[122:125], v[138:141], v[182:185], 0
	v_mfma_f32_16x16x32_bf16 v[122:125], v[142:145], v[186:189], v[122:125]
	v_mfma_f32_16x16x32_bf16 v[118:121], v[146:149], v[182:185], 0
	v_mfma_f32_16x16x32_bf16 v[118:121], v[150:153], v[186:189], v[118:121]
	v_mfma_f32_16x16x32_bf16 v[110:113], v[154:157], v[182:185], 0
	v_mfma_f32_16x16x32_bf16 v[110:113], v[158:161], v[186:189], v[110:113]
	v_mfma_f32_16x16x32_bf16 v[94:97], v[154:157], v[190:193], 0
	v_mfma_f32_16x16x32_bf16 v[94:97], v[158:161], v[202:205], v[94:97]
	v_mfma_f32_16x16x32_bf16 v[102:105], v[146:149], v[190:193], 0
	v_mfma_f32_16x16x32_bf16 v[102:105], v[150:153], v[202:205], v[102:105]
	v_mfma_f32_16x16x32_bf16 v[106:109], v[138:141], v[190:193], 0
	v_mfma_f32_16x16x32_bf16 v[106:109], v[142:145], v[202:205], v[106:109]
	v_mfma_f32_16x16x32_bf16 v[114:117], v[130:133], v[190:193], 0
	v_mfma_f32_16x16x32_bf16 v[114:117], v[134:137], v[202:205], v[114:117]
	v_mfma_f32_16x16x32_bf16 v[98:101], v[130:133], v[206:209], 0
	v_mfma_f32_16x16x32_bf16 v[98:101], v[134:137], v[210:213], v[98:101]
	v_mfma_f32_16x16x32_bf16 v[90:93], v[138:141], v[206:209], 0
	v_mfma_f32_16x16x32_bf16 v[90:93], v[142:145], v[210:213], v[90:93]
	v_mfma_f32_16x16x32_bf16 v[86:89], v[146:149], v[206:209], 0
	v_mfma_f32_16x16x32_bf16 v[86:89], v[150:153], v[210:213], v[86:89]
	v_mfma_f32_16x16x32_bf16 v[78:81], v[154:157], v[206:209], 0
	v_mfma_f32_16x16x32_bf16 v[78:81], v[158:161], v[210:213], v[78:81]
	v_mfma_f32_16x16x32_bf16 v[66:69], v[154:157], v[214:217], 0
	v_mfma_f32_16x16x32_bf16 v[66:69], v[158:161], v[240:243], v[66:69]
	v_mfma_f32_16x16x32_bf16 v[70:73], v[146:149], v[214:217], 0
	v_mfma_f32_16x16x32_bf16 v[70:73], v[150:153], v[240:243], v[70:73]
	v_mfma_f32_16x16x32_bf16 v[74:77], v[138:141], v[214:217], 0
	v_mfma_f32_16x16x32_bf16 v[74:77], v[142:145], v[240:243], v[74:77]
	v_mfma_f32_16x16x32_bf16 v[82:85], v[130:133], v[214:217], 0
	v_mfma_f32_16x16x32_bf16 v[82:85], v[134:137], v[240:243], v[82:85]
	s_setprio 0
	s_barrier
	ds_read_b128 v[182:185], v180 offset:16384
	ds_read_b128 v[186:189], v180 offset:17408
	ds_read_b128 v[190:193], v180 offset:18432
	ds_read_b128 v[202:205], v180 offset:19456
	ds_read_b128 v[206:209], v180 offset:20480
	ds_read_b128 v[210:213], v180 offset:21504
	ds_read_b128 v[214:217], v180 offset:22528
	ds_read_b128 v[240:243], v180 offset:23552
	s_mov_b32 m0, s42
	s_nop 0
	global_load_lds_dwordx4 v167, s[58:59]
	s_add_u32 s44, s58, s14
	s_mov_b32 m0, s43
	s_nop 0
	global_load_lds_dwordx4 v175, s[58:59]
	s_addc_u32 s45, s59, 0
	s_mov_b32 m0, s46
	s_nop 0
	global_load_lds_dwordx4 v167, s[44:45]
	s_nop 0
	s_mov_b32 m0, s50
	s_nop 0
	global_load_lds_dwordx4 v175, s[44:45]
	s_nop 0
	s_mov_b32 m0, s17
	s_nop 0
	global_load_lds_dwordx4 v165, s[60:61]
	s_nop 0
	s_mov_b32 m0, s53
	s_nop 0
	global_load_lds_dwordx4 v171, s[60:61]
	s_waitcnt vmcnt(8)
	s_waitcnt lgkmcnt(0)
	s_barrier
	s_setprio 1
	s_waitcnt lgkmcnt(0)
	v_mfma_f32_16x16x32_bf16 v[62:65], v[130:133], v[182:185], 0
	v_mfma_f32_16x16x32_bf16 v[62:65], v[134:137], v[186:189], v[62:65]
	v_mfma_f32_16x16x32_bf16 v[58:61], v[138:141], v[182:185], 0
	v_mfma_f32_16x16x32_bf16 v[58:61], v[142:145], v[186:189], v[58:61]
	v_mfma_f32_16x16x32_bf16 v[54:57], v[146:149], v[182:185], 0
	v_mfma_f32_16x16x32_bf16 v[54:57], v[150:153], v[186:189], v[54:57]
	v_mfma_f32_16x16x32_bf16 v[50:53], v[154:157], v[182:185], 0
	v_mfma_f32_16x16x32_bf16 v[50:53], v[158:161], v[186:189], v[50:53]
	v_mfma_f32_16x16x32_bf16 v[30:33], v[154:157], v[190:193], 0
	v_mfma_f32_16x16x32_bf16 v[30:33], v[158:161], v[202:205], v[30:33]
	v_mfma_f32_16x16x32_bf16 v[38:41], v[146:149], v[190:193], 0
	v_mfma_f32_16x16x32_bf16 v[38:41], v[150:153], v[202:205], v[38:41]
	v_mfma_f32_16x16x32_bf16 v[42:45], v[138:141], v[190:193], 0
	v_mfma_f32_16x16x32_bf16 v[42:45], v[142:145], v[202:205], v[42:45]
	v_mfma_f32_16x16x32_bf16 v[46:49], v[130:133], v[190:193], 0
	v_mfma_f32_16x16x32_bf16 v[46:49], v[134:137], v[202:205], v[46:49]
	v_mfma_f32_16x16x32_bf16 v[34:37], v[130:133], v[206:209], 0
	v_mfma_f32_16x16x32_bf16 v[34:37], v[134:137], v[210:213], v[34:37]
	v_mfma_f32_16x16x32_bf16 v[26:29], v[138:141], v[206:209], 0
	v_mfma_f32_16x16x32_bf16 v[26:29], v[142:145], v[210:213], v[26:29]
	v_mfma_f32_16x16x32_bf16 v[22:25], v[146:149], v[206:209], 0
	v_mfma_f32_16x16x32_bf16 v[22:25], v[150:153], v[210:213], v[22:25]
	v_mfma_f32_16x16x32_bf16 v[14:17], v[154:157], v[206:209], 0
	v_mfma_f32_16x16x32_bf16 v[14:17], v[158:161], v[210:213], v[14:17]
	v_mfma_f32_16x16x32_bf16 v[2:5], v[154:157], v[214:217], 0
	v_mfma_f32_16x16x32_bf16 v[2:5], v[158:161], v[240:243], v[2:5]
	v_mfma_f32_16x16x32_bf16 v[6:9], v[146:149], v[214:217], 0
	v_mfma_f32_16x16x32_bf16 v[6:9], v[150:153], v[240:243], v[6:9]
	v_mfma_f32_16x16x32_bf16 v[10:13], v[138:141], v[214:217], 0
	v_mfma_f32_16x16x32_bf16 v[10:13], v[142:145], v[240:243], v[10:13]
	v_mfma_f32_16x16x32_bf16 v[18:21], v[130:133], v[214:217], 0
	v_mfma_f32_16x16x32_bf16 v[18:21], v[134:137], v[240:243], v[18:21]
	s_setprio 0
	s_barrier
; #define PG8_STAGE(bufoff, gbase, voff) do { _Pragma("unroll") for (int _i = 0; _i < 2; ++_i) { \
;         const unsigned _m0 = ldsb + (unsigned)((bufoff) + _i * 8192); const char* _gb = (const char*)(gbase); \
;         asm volatile("s_mov_b32 m0, %0\n\ts_nop 0\n\tglobal_load_lds_dwordx4 %1, %2" :: "s"(_m0), "v"((voff)[_i]), "s"(_gb) : "m0", "memory"); } } while (0)
; #define PG8_LDA(dst, b, h) do { _Pragma("unroll") for (int m = 0; m < 4; ++m) _Pragma("unroll") for (int k = 0; k < 2; ++k) dst[m][k] = *(const LAS bf16x8*)(lds + PG8_SA(b, h) + aoff + m * 2048 + k * 1024); } while (0)
; #define PG8_LDB(dst, b, h) do { _Pragma("unroll") for (int n = 0; n < 2; ++n) _Pragma("unroll") for (int k = 0; k < 2; ++k) dst[n][k] = *(const LAS bf16x8*)(lds + PG8_SB(b, h) + boff + n * 2048 + k * 1024); } while (0)
; #define PG8_MMA(ai, bj, At, Bt) do { __builtin_amdgcn_s_setprio(1); _Pragma("unroll") for (int m = 0; m < 4; ++m) _Pragma("unroll") for (int n = 0; n < 2; ++n) _Pragma("unroll") for (int k = 0; k < 2; ++k) \
;         acc[ai][bj][m][n] = __builtin_amdgcn_mfma_f32_16x16x32_bf16(Bt[n][k], At[m][k], acc[ai][bj][m][n], 0, 0, 0); __builtin_amdgcn_s_setprio(0); } while (0)
; #define PG8_WAIT_V(n) asm volatile("s_waitcnt vmcnt(" #n ")" ::: "memory")
; #define PG8_WAIT_L(n) asm volatile("s_waitcnt lgkmcnt(" #n ")" ::: "memory")
; #define PG8_BAR __builtin_amdgcn_s_barrier()
; #define PG8_SCHED __builtin_amdgcn_sched_barrier(0)
; template <class Epi, bool ALIGN_EPI>
; __device__ __forceinline__ void gemm_phase(LAS unsigned char* lds, const Gemm g, const StaticOrder& S, const Epi& E) {
;     ...
;             PG8_LDB(B0, 1, 0); PG8_LDB(B1, 1, 1); PG8_SCHED; PG8_LDA(At, 1, 0); PG8_STAGE(PG8_SA(0, 1), a2 + hstepA, voffA);
;             PG8_WAIT_V(8); PG8_WAIT_L(0); PG8_BAR; PG8_MMA(0, 0, At, B0); PG8_MMA(0, 1, At, B1); PG8_BAR; PG8_SCHED;
;             PG8_LDA(At, 1, 1); PG8_STAGE(PG8_SB(1, 0), b3, voffB); PG8_STAGE(PG8_SB(1, 1), b3 + hstepB, voffB); PG8_STAGE(PG8_SA(1, 0), a3, voffA);
;             PG8_WAIT_V(8); PG8_WAIT_L(0); PG8_BAR; PG8_MMA(1, 0, At, B0); PG8_MMA(1, 1, At, B1); PG8_BAR; PG8_SCHED;
	v_add_u32_e32 v0, 0x18000, v179
	ds_read_b128 v[130:133], v0
	ds_read_b128 v[134:137], v0 offset:1024
	ds_read_b128 v[138:141], v0 offset:2048
	ds_read_b128 v[142:145], v0 offset:3072
	v_add_u32_e32 v0, 0x1c000, v179
	ds_read_b128 v[146:149], v0
	ds_read_b128 v[150:153], v0 offset:1024
	ds_read_b128 v[154:157], v0 offset:2048
	ds_read_b128 v[158:161], v0 offset:3072
	ds_read_b128 v[182:185], v180 offset:32768
	ds_read_b128 v[186:189], v180 offset:33792
	ds_read_b128 v[190:193], v180 offset:34816
	ds_read_b128 v[202:205], v180 offset:35840
	ds_read_b128 v[206:209], v180 offset:36864
	ds_read_b128 v[210:213], v180 offset:37888
	ds_read_b128 v[214:217], v180 offset:38912
	ds_read_b128 v[240:243], v180 offset:39936
	s_add_u32 s60, s60, 0x40000
	s_addc_u32 s61, s61, 0
	s_mov_b32 m0, s65
	s_nop 0
	global_load_lds_dwordx4 v165, s[60:61]
	s_nop 0
	s_mov_b32 m0, s67
	s_nop 0
	global_load_lds_dwordx4 v171, s[60:61]
	s_waitcnt vmcnt(8)
	s_waitcnt lgkmcnt(0)
	s_nop 0
	s_barrier
	s_setprio 1
	s_waitcnt lgkmcnt(0)
	v_mfma_f32_16x16x32_bf16 v[126:129], v[130:133], v[182:185], v[126:129]
	v_mfma_f32_16x16x32_bf16 v[126:129], v[134:137], v[186:189], v[126:129]
	v_mfma_f32_16x16x32_bf16 v[122:125], v[138:141], v[182:185], v[122:125]
	v_mfma_f32_16x16x32_bf16 v[122:125], v[142:145], v[186:189], v[122:125]
	v_mfma_f32_16x16x32_bf16 v[118:121], v[146:149], v[182:185], v[118:121]
	v_mfma_f32_16x16x32_bf16 v[118:121], v[150:153], v[186:189], v[118:121]
	v_mfma_f32_16x16x32_bf16 v[110:113], v[154:157], v[182:185], v[110:113]
	v_mfma_f32_16x16x32_bf16 v[110:113], v[158:161], v[186:189], v[110:113]
	v_mfma_f32_16x16x32_bf16 v[94:97], v[154:157], v[190:193], v[94:97]
	v_mfma_f32_16x16x32_bf16 v[94:97], v[158:161], v[202:205], v[94:97]
	v_mfma_f32_16x16x32_bf16 v[102:105], v[146:149], v[190:193], v[102:105]
	v_mfma_f32_16x16x32_bf16 v[102:105], v[150:153], v[202:205], v[102:105]
	v_mfma_f32_16x16x32_bf16 v[106:109], v[138:141], v[190:193], v[106:109]
	v_mfma_f32_16x16x32_bf16 v[106:109], v[142:145], v[202:205], v[106:109]
	v_mfma_f32_16x16x32_bf16 v[114:117], v[130:133], v[190:193], v[114:117]
	v_mfma_f32_16x16x32_bf16 v[114:117], v[134:137], v[202:205], v[114:117]
	v_mfma_f32_16x16x32_bf16 v[98:101], v[130:133], v[206:209], v[98:101]
	v_mfma_f32_16x16x32_bf16 v[98:101], v[134:137], v[210:213], v[98:101]
	v_mfma_f32_16x16x32_bf16 v[90:93], v[138:141], v[206:209], v[90:93]
	v_mfma_f32_16x16x32_bf16 v[90:93], v[142:145], v[210:213], v[90:93]
	v_mfma_f32_16x16x32_bf16 v[86:89], v[146:149], v[206:209], v[86:89]
	v_mfma_f32_16x16x32_bf16 v[86:89], v[150:153], v[210:213], v[86:89]
	v_mfma_f32_16x16x32_bf16 v[78:81], v[154:157], v[206:209], v[78:81]
	v_mfma_f32_16x16x32_bf16 v[78:81], v[158:161], v[210:213], v[78:81]
	v_mfma_f32_16x16x32_bf16 v[66:69], v[154:157], v[214:217], v[66:69]
	v_mfma_f32_16x16x32_bf16 v[66:69], v[158:161], v[240:243], v[66:69]
	v_mfma_f32_16x16x32_bf16 v[70:73], v[146:149], v[214:217], v[70:73]
	v_mfma_f32_16x16x32_bf16 v[70:73], v[150:153], v[240:243], v[70:73]
	v_mfma_f32_16x16x32_bf16 v[74:77], v[138:141], v[214:217], v[74:77]
	v_mfma_f32_16x16x32_bf16 v[74:77], v[142:145], v[240:243], v[74:77]
	v_mfma_f32_16x16x32_bf16 v[82:85], v[130:133], v[214:217], v[82:85]
	v_mfma_f32_16x16x32_bf16 v[82:85], v[134:137], v[240:243], v[82:85]
	s_setprio 0
	s_barrier
	ds_read_b128 v[182:185], v180 offset:49152
	ds_read_b128 v[186:189], v180 offset:50176
	ds_read_b128 v[190:193], v180 offset:51200
	ds_read_b128 v[202:205], v180 offset:52224
	ds_read_b128 v[206:209], v180 offset:53248
	ds_read_b128 v[210:213], v180 offset:54272
	ds_read_b128 v[214:217], v180 offset:55296
	ds_read_b128 v[240:243], v180 offset:56320
	s_add_u32 s58, s58, 0x80
	s_addc_u32 s59, s59, 0
	s_mov_b32 m0, s89
	s_nop 0
	global_load_lds_dwordx4 v167, s[58:59]
	s_add_u32 s44, s44, 0x80
	s_mov_b32 m0, s95
	s_nop 0
	global_load_lds_dwordx4 v175, s[58:59]
	s_addc_u32 s45, s45, 0
	s_mov_b32 m0, s26
	s_nop 0
	global_load_lds_dwordx4 v167, s[44:45]
	s_nop 0
	s_mov_b32 m0, s27
	s_nop 0
	global_load_lds_dwordx4 v175, s[44:45]
	s_nop 0
	s_mov_b32 m0, s36
	s_nop 0
	global_load_lds_dwordx4 v165, s[56:57]
	s_nop 0
	s_mov_b32 m0, s37
	s_nop 0
	global_load_lds_dwordx4 v171, s[56:57]
	s_waitcnt vmcnt(8)
	s_waitcnt lgkmcnt(0)
	s_barrier
	s_setprio 1
	s_waitcnt lgkmcnt(0)
	v_mfma_f32_16x16x32_bf16 v[62:65], v[130:133], v[182:185], v[62:65]
	v_mfma_f32_16x16x32_bf16 v[62:65], v[134:137], v[186:189], v[62:65]
	v_mfma_f32_16x16x32_bf16 v[58:61], v[138:141], v[182:185], v[58:61]
	v_mfma_f32_16x16x32_bf16 v[58:61], v[142:145], v[186:189], v[58:61]
	v_mfma_f32_16x16x32_bf16 v[54:57], v[146:149], v[182:185], v[54:57]
	v_mfma_f32_16x16x32_bf16 v[54:57], v[150:153], v[186:189], v[54:57]
	v_mfma_f32_16x16x32_bf16 v[50:53], v[154:157], v[182:185], v[50:53]
	v_mfma_f32_16x16x32_bf16 v[50:53], v[158:161], v[186:189], v[50:53]
	v_mfma_f32_16x16x32_bf16 v[30:33], v[154:157], v[190:193], v[30:33]
	v_mfma_f32_16x16x32_bf16 v[30:33], v[158:161], v[202:205], v[30:33]
	v_mfma_f32_16x16x32_bf16 v[38:41], v[146:149], v[190:193], v[38:41]
	v_mfma_f32_16x16x32_bf16 v[38:41], v[150:153], v[202:205], v[38:41]
	v_mfma_f32_16x16x32_bf16 v[42:45], v[138:141], v[190:193], v[42:45]
	v_mfma_f32_16x16x32_bf16 v[42:45], v[142:145], v[202:205], v[42:45]
	v_mfma_f32_16x16x32_bf16 v[46:49], v[130:133], v[190:193], v[46:49]
	v_mfma_f32_16x16x32_bf16 v[46:49], v[134:137], v[202:205], v[46:49]
	v_mfma_f32_16x16x32_bf16 v[34:37], v[130:133], v[206:209], v[34:37]
	v_mfma_f32_16x16x32_bf16 v[34:37], v[134:137], v[210:213], v[34:37]
	v_mfma_f32_16x16x32_bf16 v[26:29], v[138:141], v[206:209], v[26:29]
	v_mfma_f32_16x16x32_bf16 v[26:29], v[142:145], v[210:213], v[26:29]
	v_mfma_f32_16x16x32_bf16 v[22:25], v[146:149], v[206:209], v[22:25]
	v_mfma_f32_16x16x32_bf16 v[22:25], v[150:153], v[210:213], v[22:25]
	v_mfma_f32_16x16x32_bf16 v[14:17], v[154:157], v[206:209], v[14:17]
	v_mfma_f32_16x16x32_bf16 v[14:17], v[158:161], v[210:213], v[14:17]
	v_mfma_f32_16x16x32_bf16 v[2:5], v[154:157], v[214:217], v[2:5]
	v_mfma_f32_16x16x32_bf16 v[2:5], v[158:161], v[240:243], v[2:5]
	v_mfma_f32_16x16x32_bf16 v[6:9], v[146:149], v[214:217], v[6:9]
	v_mfma_f32_16x16x32_bf16 v[6:9], v[150:153], v[240:243], v[6:9]
	v_mfma_f32_16x16x32_bf16 v[10:13], v[138:141], v[214:217], v[10:13]
	v_mfma_f32_16x16x32_bf16 v[10:13], v[142:145], v[240:243], v[10:13]
	v_mfma_f32_16x16x32_bf16 v[18:21], v[130:133], v[214:217], v[18:21]
	v_mfma_f32_16x16x32_bf16 v[18:21], v[134:137], v[240:243], v[18:21]
	s_setprio 0
	s_barrier
	s_add_u32 s4, s4, 0x100
	s_addc_u32 s5, s5, 0
	s_add_u32 s0, s0, 0x100
	s_addc_u32 s1, s1, 0
	s_cmp_ge_u32 s55, s31
	s_mov_b32 s44, s55
; #define PG8_STAGE(bufoff, gbase, voff) do { _Pragma("unroll") for (int _i = 0; _i < 2; ++_i) { \
;         const unsigned _m0 = ldsb + (unsigned)((bufoff) + _i * 8192); const char* _gb = (const char*)(gbase); \
;         asm volatile("s_mov_b32 m0, %0\n\ts_nop 0\n\tglobal_load_lds_dwordx4 %1, %2" :: "s"(_m0), "v"((voff)[_i]), "s"(_gb) : "m0", "memory"); } } while (0)
; #define PG8_LDA(dst, b, h) do { _Pragma("unroll") for (int m = 0; m < 4; ++m) _Pragma("unroll") for (int k = 0; k < 2; ++k) dst[m][k] = *(const LAS bf16x8*)(lds + PG8_SA(b, h) + aoff + m * 2048 + k * 1024); } while (0)
; #define PG8_LDB(dst, b, h) do { _Pragma("unroll") for (int n = 0; n < 2; ++n) _Pragma("unroll") for (int k = 0; k < 2; ++k) dst[n][k] = *(const LAS bf16x8*)(lds + PG8_SB(b, h) + boff + n * 2048 + k * 1024); } while (0)
; #define PG8_MMA(ai, bj, At, Bt) do { __builtin_amdgcn_s_setprio(1); _Pragma("unroll") for (int m = 0; m < 4; ++m) _Pragma("unroll") for (int n = 0; n < 2; ++n) _Pragma("unroll") for (int k = 0; k < 2; ++k) \
;         acc[ai][bj][m][n] = __builtin_amdgcn_mfma_f32_16x16x32_bf16(Bt[n][k], At[m][k], acc[ai][bj][m][n], 0, 0, 0); __builtin_amdgcn_s_setprio(0); } while (0)
; #define PG8_WAIT_V(n) asm volatile("s_waitcnt vmcnt(" #n ")" ::: "memory")
; #define PG8_WAIT_L(n) asm volatile("s_waitcnt lgkmcnt(" #n ")" ::: "memory")
; template <class Epi, bool ALIGN_EPI>
; __device__ __forceinline__ void gemm_phase(LAS unsigned char* lds, const Gemm g, const StaticOrder& S, const Epi& E) {
;     ...
;         for (int t = 0; t < nt; t += 2) {
;             const bool last = (t == nt - 2);
;             const char* a1 = cA + (size_t)(t + 1) * kstep;
;             const char* a2 = last ? nA : cA + (size_t)(t + 2) * kstep; const char* b2 = last ? nB : cB + (size_t)(t + 2) * kstep;
;             const char* a3 = a2 + kstep; const char* b3 = b2 + kstep;
;             PG8_LDB(B0, 0, 0); PG8_LDB(B1, 0, 1); PG8_SCHED; PG8_LDA(At, 0, 0); PG8_STAGE(PG8_SA(1, 1), a1 + hstepA, voffA);
;             PG8_WAIT_V(8); PG8_WAIT_L(0); PG8_BAR; PG8_MMA(0, 0, At, B0); PG8_MMA(0, 1, At, B1); PG8_BAR; PG8_SCHED;
;             PG8_LDA(At, 0, 1); PG8_STAGE(PG8_SB(0, 0), b2, voffB); PG8_STAGE(PG8_SB(0, 1), b2 + hstepB, voffB); PG8_STAGE(PG8_SA(0, 0), a2, voffA);
;             PG8_WAIT_V(8); PG8_WAIT_L(0); PG8_BAR; PG8_MMA(1, 0, At, B0); PG8_MMA(1, 1, At, B1); PG8_BAR; PG8_SCHED;
.LBB0_271:
	v_add_u32_e32 v0, 0x10000, v179
	ds_read_b128 v[130:133], v0
	ds_read_b128 v[134:137], v0 offset:1024
	ds_read_b128 v[138:141], v0 offset:2048
	ds_read_b128 v[142:145], v0 offset:3072
	v_add_u32_e32 v0, 0x14000, v179
	ds_read_b128 v[146:149], v0
	ds_read_b128 v[150:153], v0 offset:1024
	ds_read_b128 v[154:157], v0 offset:2048
	ds_read_b128 v[158:161], v0 offset:3072
	s_add_i32 s55, s44, 2
	s_add_u32 s45, s0, 0xfffc0080
	s_addc_u32 s56, s1, -1
	s_cmp_eq_u32 s68, s44
	s_cselect_b32 s60, s96, s45
	s_cselect_b32 s61, s97, s56
	s_cselect_b32 s58, s48, s4
	s_cselect_b32 s59, s49, s5
	s_add_u32 s56, s60, 0x80
	s_addc_u32 s57, s61, 0
	ds_read_b128 v[182:185], v180
	ds_read_b128 v[186:189], v180 offset:1024
	ds_read_b128 v[190:193], v180 offset:2048
	ds_read_b128 v[202:205], v180 offset:3072
	ds_read_b128 v[206:209], v180 offset:4096
	ds_read_b128 v[210:213], v180 offset:5120
	ds_read_b128 v[214:217], v180 offset:6144
	ds_read_b128 v[240:243], v180 offset:7168
	s_mov_b32 m0, s41
	s_nop 0
	global_load_lds_dwordx4 v165, s[0:1]
	s_nop 0
	s_mov_b32 m0, s30
	s_nop 0
	global_load_lds_dwordx4 v171, s[0:1]
	s_waitcnt vmcnt(8)
	s_waitcnt lgkmcnt(0)
	s_barrier
	s_setprio 1
	s_waitcnt lgkmcnt(0)
	v_mfma_f32_16x16x32_bf16 v[126:129], v[130:133], v[182:185], v[126:129]
	v_mfma_f32_16x16x32_bf16 v[126:129], v[134:137], v[186:189], v[126:129]
	v_mfma_f32_16x16x32_bf16 v[122:125], v[138:141], v[182:185], v[122:125]
	v_mfma_f32_16x16x32_bf16 v[122:125], v[142:145], v[186:189], v[122:125]
	v_mfma_f32_16x16x32_bf16 v[118:121], v[146:149], v[182:185], v[118:121]
	v_mfma_f32_16x16x32_bf16 v[118:121], v[150:153], v[186:189], v[118:121]
	v_mfma_f32_16x16x32_bf16 v[110:113], v[154:157], v[182:185], v[110:113]
	v_mfma_f32_16x16x32_bf16 v[110:113], v[158:161], v[186:189], v[110:113]
	v_mfma_f32_16x16x32_bf16 v[94:97], v[154:157], v[190:193], v[94:97]
	v_mfma_f32_16x16x32_bf16 v[94:97], v[158:161], v[202:205], v[94:97]
	v_mfma_f32_16x16x32_bf16 v[102:105], v[146:149], v[190:193], v[102:105]
	v_mfma_f32_16x16x32_bf16 v[102:105], v[150:153], v[202:205], v[102:105]
	v_mfma_f32_16x16x32_bf16 v[106:109], v[138:141], v[190:193], v[106:109]
	v_mfma_f32_16x16x32_bf16 v[106:109], v[142:145], v[202:205], v[106:109]
	v_mfma_f32_16x16x32_bf16 v[114:117], v[130:133], v[190:193], v[114:117]
	v_mfma_f32_16x16x32_bf16 v[114:117], v[134:137], v[202:205], v[114:117]
	v_mfma_f32_16x16x32_bf16 v[98:101], v[130:133], v[206:209], v[98:101]
	v_mfma_f32_16x16x32_bf16 v[98:101], v[134:137], v[210:213], v[98:101]
	v_mfma_f32_16x16x32_bf16 v[90:93], v[138:141], v[206:209], v[90:93]
	v_mfma_f32_16x16x32_bf16 v[90:93], v[142:145], v[210:213], v[90:93]
	v_mfma_f32_16x16x32_bf16 v[86:89], v[146:149], v[206:209], v[86:89]
	v_mfma_f32_16x16x32_bf16 v[86:89], v[150:153], v[210:213], v[86:89]
	v_mfma_f32_16x16x32_bf16 v[78:81], v[154:157], v[206:209], v[78:81]
	v_mfma_f32_16x16x32_bf16 v[78:81], v[158:161], v[210:213], v[78:81]
	v_mfma_f32_16x16x32_bf16 v[66:69], v[154:157], v[214:217], v[66:69]
	v_mfma_f32_16x16x32_bf16 v[66:69], v[158:161], v[240:243], v[66:69]
	v_mfma_f32_16x16x32_bf16 v[70:73], v[146:149], v[214:217], v[70:73]
	v_mfma_f32_16x16x32_bf16 v[70:73], v[150:153], v[240:243], v[70:73]
	v_mfma_f32_16x16x32_bf16 v[74:77], v[138:141], v[214:217], v[74:77]
	v_mfma_f32_16x16x32_bf16 v[74:77], v[142:145], v[240:243], v[74:77]
	v_mfma_f32_16x16x32_bf16 v[82:85], v[130:133], v[214:217], v[82:85]
	v_mfma_f32_16x16x32_bf16 v[82:85], v[134:137], v[240:243], v[82:85]
	s_setprio 0
	s_barrier
	ds_read_b128 v[182:185], v180 offset:16384
	ds_read_b128 v[186:189], v180 offset:17408
	ds_read_b128 v[190:193], v180 offset:18432
	ds_read_b128 v[202:205], v180 offset:19456
	ds_read_b128 v[206:209], v180 offset:20480
	ds_read_b128 v[210:213], v180 offset:21504
	ds_read_b128 v[214:217], v180 offset:22528
	ds_read_b128 v[240:243], v180 offset:23552
	s_mov_b32 m0, s42
	s_nop 0
	global_load_lds_dwordx4 v167, s[58:59]
	s_add_u32 s44, s58, s14
	s_mov_b32 m0, s43
	s_nop 0
	global_load_lds_dwordx4 v175, s[58:59]
	s_addc_u32 s45, s59, 0
	s_mov_b32 m0, s46
	s_nop 0
	global_load_lds_dwordx4 v167, s[44:45]
	s_nop 0
	s_mov_b32 m0, s50
	s_nop 0
	global_load_lds_dwordx4 v175, s[44:45]
	s_nop 0
	s_mov_b32 m0, s17
	s_nop 0
	global_load_lds_dwordx4 v165, s[60:61]
	s_nop 0
	s_mov_b32 m0, s53
	s_nop 0
	global_load_lds_dwordx4 v171, s[60:61]
	s_waitcnt vmcnt(8)
	s_waitcnt lgkmcnt(0)
	s_barrier
	s_setprio 1
	s_waitcnt lgkmcnt(0)
	v_mfma_f32_16x16x32_bf16 v[62:65], v[130:133], v[182:185], v[62:65]
	v_mfma_f32_16x16x32_bf16 v[62:65], v[134:137], v[186:189], v[62:65]
	v_mfma_f32_16x16x32_bf16 v[58:61], v[138:141], v[182:185], v[58:61]
	v_mfma_f32_16x16x32_bf16 v[58:61], v[142:145], v[186:189], v[58:61]
	v_mfma_f32_16x16x32_bf16 v[54:57], v[146:149], v[182:185], v[54:57]
	v_mfma_f32_16x16x32_bf16 v[54:57], v[150:153], v[186:189], v[54:57]
	v_mfma_f32_16x16x32_bf16 v[50:53], v[154:157], v[182:185], v[50:53]
	v_mfma_f32_16x16x32_bf16 v[50:53], v[158:161], v[186:189], v[50:53]
	v_mfma_f32_16x16x32_bf16 v[30:33], v[154:157], v[190:193], v[30:33]
	v_mfma_f32_16x16x32_bf16 v[30:33], v[158:161], v[202:205], v[30:33]
	v_mfma_f32_16x16x32_bf16 v[38:41], v[146:149], v[190:193], v[38:41]
	v_mfma_f32_16x16x32_bf16 v[38:41], v[150:153], v[202:205], v[38:41]
	v_mfma_f32_16x16x32_bf16 v[42:45], v[138:141], v[190:193], v[42:45]
	v_mfma_f32_16x16x32_bf16 v[42:45], v[142:145], v[202:205], v[42:45]
	v_mfma_f32_16x16x32_bf16 v[46:49], v[130:133], v[190:193], v[46:49]
	v_mfma_f32_16x16x32_bf16 v[46:49], v[134:137], v[202:205], v[46:49]
	v_mfma_f32_16x16x32_bf16 v[34:37], v[130:133], v[206:209], v[34:37]
	v_mfma_f32_16x16x32_bf16 v[34:37], v[134:137], v[210:213], v[34:37]
	v_mfma_f32_16x16x32_bf16 v[26:29], v[138:141], v[206:209], v[26:29]
	v_mfma_f32_16x16x32_bf16 v[26:29], v[142:145], v[210:213], v[26:29]
	v_mfma_f32_16x16x32_bf16 v[22:25], v[146:149], v[206:209], v[22:25]
	v_mfma_f32_16x16x32_bf16 v[22:25], v[150:153], v[210:213], v[22:25]
	v_mfma_f32_16x16x32_bf16 v[14:17], v[154:157], v[206:209], v[14:17]
	v_mfma_f32_16x16x32_bf16 v[14:17], v[158:161], v[210:213], v[14:17]
	v_mfma_f32_16x16x32_bf16 v[2:5], v[154:157], v[214:217], v[2:5]
	v_mfma_f32_16x16x32_bf16 v[2:5], v[158:161], v[240:243], v[2:5]
	v_mfma_f32_16x16x32_bf16 v[6:9], v[146:149], v[214:217], v[6:9]
	v_mfma_f32_16x16x32_bf16 v[6:9], v[150:153], v[240:243], v[6:9]
	v_mfma_f32_16x16x32_bf16 v[10:13], v[138:141], v[214:217], v[10:13]
	v_mfma_f32_16x16x32_bf16 v[10:13], v[142:145], v[240:243], v[10:13]
	v_mfma_f32_16x16x32_bf16 v[18:21], v[130:133], v[214:217], v[18:21]
	v_mfma_f32_16x16x32_bf16 v[18:21], v[134:137], v[240:243], v[18:21]
	s_setprio 0
	s_barrier
; #define PG8_STAGE(bufoff, gbase, voff) do { _Pragma("unroll") for (int _i = 0; _i < 2; ++_i) { \
;         const unsigned _m0 = ldsb + (unsigned)((bufoff) + _i * 8192); const char* _gb = (const char*)(gbase); \
;         asm volatile("s_mov_b32 m0, %0\n\ts_nop 0\n\tglobal_load_lds_dwordx4 %1, %2" :: "s"(_m0), "v"((voff)[_i]), "s"(_gb) : "m0", "memory"); } } while (0)
; #define PG8_LDA(dst, b, h) do { _Pragma("unroll") for (int m = 0; m < 4; ++m) _Pragma("unroll") for (int k = 0; k < 2; ++k) dst[m][k] = *(const LAS bf16x8*)(lds + PG8_SA(b, h) + aoff + m * 2048 + k * 1024); } while (0)
; #define PG8_LDB(dst, b, h) do { _Pragma("unroll") for (int n = 0; n < 2; ++n) _Pragma("unroll") for (int k = 0; k < 2; ++k) dst[n][k] = *(const LAS bf16x8*)(lds + PG8_SB(b, h) + boff + n * 2048 + k * 1024); } while (0)
; #define PG8_MMA(ai, bj, At, Bt) do { __builtin_amdgcn_s_setprio(1); _Pragma("unroll") for (int m = 0; m < 4; ++m) _Pragma("unroll") for (int n = 0; n < 2; ++n) _Pragma("unroll") for (int k = 0; k < 2; ++k) \
;         acc[ai][bj][m][n] = __builtin_amdgcn_mfma_f32_16x16x32_bf16(Bt[n][k], At[m][k], acc[ai][bj][m][n], 0, 0, 0); __builtin_amdgcn_s_setprio(0); } while (0)
; #define PG8_WAIT_V(n) asm volatile("s_waitcnt vmcnt(" #n ")" ::: "memory")
; #define PG8_WAIT_L(n) asm volatile("s_waitcnt lgkmcnt(" #n ")" ::: "memory")
; #define PG8_BAR __builtin_amdgcn_s_barrier()
; #define PG8_SCHED __builtin_amdgcn_sched_barrier(0)
; template <class Epi, bool ALIGN_EPI>
; __device__ __forceinline__ void gemm_phase(LAS unsigned char* lds, const Gemm g, const StaticOrder& S, const Epi& E) {
;     ...
;             PG8_LDB(B0, 1, 0); PG8_LDB(B1, 1, 1); PG8_SCHED; PG8_LDA(At, 1, 0); PG8_STAGE(PG8_SA(0, 1), a2 + hstepA, voffA);
;             PG8_WAIT_V(8); PG8_WAIT_L(0); PG8_BAR; PG8_MMA(0, 0, At, B0); PG8_MMA(0, 1, At, B1); PG8_BAR; PG8_SCHED;
;             PG8_LDA(At, 1, 1); PG8_STAGE(PG8_SB(1, 0), b3, voffB); PG8_STAGE(PG8_SB(1, 1), b3 + hstepB, voffB); PG8_STAGE(PG8_SA(1, 0), a3, voffA);
;             PG8_WAIT_V(8); PG8_WAIT_L(0); PG8_BAR; PG8_MMA(1, 0, At, B0); PG8_MMA(1, 1, At, B1); PG8_BAR; PG8_SCHED;
;         }
;         if constexpr (ALIGN_EPI) { if (wr == 0) PG8_BAR; }
	v_add_u32_e32 v0, 0x18000, v179
	ds_read_b128 v[130:133], v0
	ds_read_b128 v[134:137], v0 offset:1024
	ds_read_b128 v[138:141], v0 offset:2048
	ds_read_b128 v[142:145], v0 offset:3072
	v_add_u32_e32 v0, 0x1c000, v179
	ds_read_b128 v[146:149], v0
	ds_read_b128 v[150:153], v0 offset:1024
	ds_read_b128 v[154:157], v0 offset:2048
	ds_read_b128 v[158:161], v0 offset:3072
	ds_read_b128 v[182:185], v180 offset:32768
	ds_read_b128 v[186:189], v180 offset:33792
	ds_read_b128 v[190:193], v180 offset:34816
	ds_read_b128 v[202:205], v180 offset:35840
	ds_read_b128 v[206:209], v180 offset:36864
	ds_read_b128 v[210:213], v180 offset:37888
	ds_read_b128 v[214:217], v180 offset:38912
	ds_read_b128 v[240:243], v180 offset:39936
	s_add_u32 s60, s60, 0x40000
	s_addc_u32 s61, s61, 0
	s_mov_b32 m0, s65
	s_nop 0
	global_load_lds_dwordx4 v165, s[60:61]
	s_nop 0
	s_mov_b32 m0, s67
	s_nop 0
	global_load_lds_dwordx4 v171, s[60:61]
	s_waitcnt vmcnt(8)
	s_waitcnt lgkmcnt(0)
	s_nop 0
	s_barrier
	s_setprio 1
	s_waitcnt lgkmcnt(0)
	v_mfma_f32_16x16x32_bf16 v[126:129], v[130:133], v[182:185], v[126:129]
	v_mfma_f32_16x16x32_bf16 v[126:129], v[134:137], v[186:189], v[126:129]
	v_mfma_f32_16x16x32_bf16 v[122:125], v[138:141], v[182:185], v[122:125]
	v_mfma_f32_16x16x32_bf16 v[122:125], v[142:145], v[186:189], v[122:125]
	v_mfma_f32_16x16x32_bf16 v[118:121], v[146:149], v[182:185], v[118:121]
	v_mfma_f32_16x16x32_bf16 v[118:121], v[150:153], v[186:189], v[118:121]
	v_mfma_f32_16x16x32_bf16 v[110:113], v[154:157], v[182:185], v[110:113]
	v_mfma_f32_16x16x32_bf16 v[110:113], v[158:161], v[186:189], v[110:113]
	v_mfma_f32_16x16x32_bf16 v[94:97], v[154:157], v[190:193], v[94:97]
	v_mfma_f32_16x16x32_bf16 v[94:97], v[158:161], v[202:205], v[94:97]
	v_mfma_f32_16x16x32_bf16 v[102:105], v[146:149], v[190:193], v[102:105]
	v_mfma_f32_16x16x32_bf16 v[102:105], v[150:153], v[202:205], v[102:105]
	v_mfma_f32_16x16x32_bf16 v[106:109], v[138:141], v[190:193], v[106:109]
	v_mfma_f32_16x16x32_bf16 v[106:109], v[142:145], v[202:205], v[106:109]
	v_mfma_f32_16x16x32_bf16 v[114:117], v[130:133], v[190:193], v[114:117]
	v_mfma_f32_16x16x32_bf16 v[114:117], v[134:137], v[202:205], v[114:117]
	v_mfma_f32_16x16x32_bf16 v[98:101], v[130:133], v[206:209], v[98:101]
	v_mfma_f32_16x16x32_bf16 v[98:101], v[134:137], v[210:213], v[98:101]
	v_mfma_f32_16x16x32_bf16 v[90:93], v[138:141], v[206:209], v[90:93]
	v_mfma_f32_16x16x32_bf16 v[90:93], v[142:145], v[210:213], v[90:93]
	v_mfma_f32_16x16x32_bf16 v[86:89], v[146:149], v[206:209], v[86:89]
	v_mfma_f32_16x16x32_bf16 v[86:89], v[150:153], v[210:213], v[86:89]
	v_mfma_f32_16x16x32_bf16 v[78:81], v[154:157], v[206:209], v[78:81]
	v_mfma_f32_16x16x32_bf16 v[78:81], v[158:161], v[210:213], v[78:81]
	v_mfma_f32_16x16x32_bf16 v[66:69], v[154:157], v[214:217], v[66:69]
	v_mfma_f32_16x16x32_bf16 v[66:69], v[158:161], v[240:243], v[66:69]
	v_mfma_f32_16x16x32_bf16 v[70:73], v[146:149], v[214:217], v[70:73]
	v_mfma_f32_16x16x32_bf16 v[70:73], v[150:153], v[240:243], v[70:73]
	v_mfma_f32_16x16x32_bf16 v[74:77], v[138:141], v[214:217], v[74:77]
	v_mfma_f32_16x16x32_bf16 v[74:77], v[142:145], v[240:243], v[74:77]
	v_mfma_f32_16x16x32_bf16 v[82:85], v[130:133], v[214:217], v[82:85]
	v_mfma_f32_16x16x32_bf16 v[82:85], v[134:137], v[240:243], v[82:85]
	s_setprio 0
	s_barrier
	ds_read_b128 v[182:185], v180 offset:49152
	ds_read_b128 v[186:189], v180 offset:50176
	ds_read_b128 v[190:193], v180 offset:51200
	ds_read_b128 v[202:205], v180 offset:52224
	ds_read_b128 v[206:209], v180 offset:53248
	ds_read_b128 v[210:213], v180 offset:54272
	ds_read_b128 v[214:217], v180 offset:55296
	ds_read_b128 v[240:243], v180 offset:56320
	s_add_u32 s58, s58, 0x80
	s_addc_u32 s59, s59, 0
	s_mov_b32 m0, s89
	s_nop 0
	global_load_lds_dwordx4 v167, s[58:59]
	s_add_u32 s44, s44, 0x80
	s_mov_b32 m0, s95
	s_nop 0
	global_load_lds_dwordx4 v175, s[58:59]
	s_addc_u32 s45, s45, 0
	s_mov_b32 m0, s26
	s_nop 0
	global_load_lds_dwordx4 v167, s[44:45]
	s_nop 0
	s_mov_b32 m0, s27
	s_nop 0
	global_load_lds_dwordx4 v175, s[44:45]
	s_nop 0
	s_mov_b32 m0, s36
	s_nop 0
	global_load_lds_dwordx4 v165, s[56:57]
	s_nop 0
	s_mov_b32 m0, s37
	s_nop 0
	global_load_lds_dwordx4 v171, s[56:57]
	s_waitcnt vmcnt(8)
	s_waitcnt lgkmcnt(0)
	s_barrier
	s_setprio 1
	s_waitcnt lgkmcnt(0)
	v_mfma_f32_16x16x32_bf16 v[62:65], v[130:133], v[182:185], v[62:65]
	v_mfma_f32_16x16x32_bf16 v[62:65], v[134:137], v[186:189], v[62:65]
	v_mfma_f32_16x16x32_bf16 v[58:61], v[138:141], v[182:185], v[58:61]
	v_mfma_f32_16x16x32_bf16 v[58:61], v[142:145], v[186:189], v[58:61]
	v_mfma_f32_16x16x32_bf16 v[54:57], v[146:149], v[182:185], v[54:57]
	v_mfma_f32_16x16x32_bf16 v[54:57], v[150:153], v[186:189], v[54:57]
	v_mfma_f32_16x16x32_bf16 v[50:53], v[154:157], v[182:185], v[50:53]
	v_mfma_f32_16x16x32_bf16 v[50:53], v[158:161], v[186:189], v[50:53]
	v_mfma_f32_16x16x32_bf16 v[30:33], v[154:157], v[190:193], v[30:33]
	v_mfma_f32_16x16x32_bf16 v[30:33], v[158:161], v[202:205], v[30:33]
	v_mfma_f32_16x16x32_bf16 v[38:41], v[146:149], v[190:193], v[38:41]
	v_mfma_f32_16x16x32_bf16 v[38:41], v[150:153], v[202:205], v[38:41]
	v_mfma_f32_16x16x32_bf16 v[42:45], v[138:141], v[190:193], v[42:45]
	v_mfma_f32_16x16x32_bf16 v[42:45], v[142:145], v[202:205], v[42:45]
	v_mfma_f32_16x16x32_bf16 v[46:49], v[130:133], v[190:193], v[46:49]
	v_mfma_f32_16x16x32_bf16 v[46:49], v[134:137], v[202:205], v[46:49]
	v_mfma_f32_16x16x32_bf16 v[34:37], v[130:133], v[206:209], v[34:37]
	v_mfma_f32_16x16x32_bf16 v[34:37], v[134:137], v[210:213], v[34:37]
	v_mfma_f32_16x16x32_bf16 v[26:29], v[138:141], v[206:209], v[26:29]
	v_mfma_f32_16x16x32_bf16 v[26:29], v[142:145], v[210:213], v[26:29]
	v_mfma_f32_16x16x32_bf16 v[22:25], v[146:149], v[206:209], v[22:25]
	v_mfma_f32_16x16x32_bf16 v[22:25], v[150:153], v[210:213], v[22:25]
	v_mfma_f32_16x16x32_bf16 v[14:17], v[154:157], v[206:209], v[14:17]
	v_mfma_f32_16x16x32_bf16 v[14:17], v[158:161], v[210:213], v[14:17]
	v_mfma_f32_16x16x32_bf16 v[2:5], v[154:157], v[214:217], v[2:5]
	v_mfma_f32_16x16x32_bf16 v[2:5], v[158:161], v[240:243], v[2:5]
	v_mfma_f32_16x16x32_bf16 v[6:9], v[146:149], v[214:217], v[6:9]
	v_mfma_f32_16x16x32_bf16 v[6:9], v[150:153], v[240:243], v[6:9]
	v_mfma_f32_16x16x32_bf16 v[10:13], v[138:141], v[214:217], v[10:13]
	v_mfma_f32_16x16x32_bf16 v[10:13], v[142:145], v[240:243], v[10:13]
	v_mfma_f32_16x16x32_bf16 v[18:21], v[130:133], v[214:217], v[18:21]
	v_mfma_f32_16x16x32_bf16 v[18:21], v[134:137], v[240:243], v[18:21]
	s_setprio 0
	s_barrier
	s_add_u32 s4, s4, 0x100
	s_addc_u32 s5, s5, 0
	s_add_u32 s0, s0, 0x100
	s_addc_u32 s1, s1, 0
	s_cmp_ge_u32 s55, s31
	s_mov_b32 s44, s55
	s_cbranch_scc0 .LBB0_271
	v_readlane_b32 s0, v254, 44
	v_readlane_b32 s1, v254, 45
	s_and_b64 vcc, exec, s[0:1]
	s_cbranch_vccz .LBB0_274
	s_barrier

; #define PG8_STAGE(bufoff, gbase, voff) do { _Pragma("unroll") for (int _i = 0; _i < 2; ++_i) { \
;         const unsigned _m0 = ldsb + (unsigned)((bufoff) + _i * 8192); const char* _gb = (const char*)(gbase); \
;         asm volatile("s_mov_b32 m0, %0\n\ts_nop 0\n\tglobal_load_lds_dwordx4 %1, %2" :: "s"(_m0), "v"((voff)[_i]), "s"(_gb) : "m0", "memory"); } } while (0)
; #define PG8_LDA(dst, b, h) do { _Pragma("unroll") for (int m = 0; m < 4; ++m) _Pragma("unroll") for (int k = 0; k < 2; ++k) dst[m][k] = *(const LAS bf16x8*)(lds + PG8_SA(b, h) + aoff + m * 2048 + k * 1024); } while (0)
; #define PG8_LDB(dst, b, h) do { _Pragma("unroll") for (int n = 0; n < 2; ++n) _Pragma("unroll") for (int k = 0; k < 2; ++k) dst[n][k] = *(const LAS bf16x8*)(lds + PG8_SB(b, h) + boff + n * 2048 + k * 1024); } while (0)
; #define PG8_WAIT_V(n) asm volatile("s_waitcnt vmcnt(" #n ")" ::: "memory")
; #define PG8_WAIT_L(n) asm volatile("s_waitcnt lgkmcnt(" #n ")" ::: "memory")
; #define PG8_BAR __builtin_amdgcn_s_barrier()
; #define PG8_SCHED __builtin_amdgcn_sched_barrier(0)
; template <class Epi, bool ALIGN_EPI>
; __device__ __forceinline__ void gemm_phase(LAS unsigned char* lds, const Gemm g, const StaticOrder& S, const Epi& E) {
;     ...
;         const char* nA = has_next ? (const char*)g.A + (size_t)nxt.pm * tstepA + (size_t)nxt.pn * g.a_pn_off * 2 + (size_t)(nxt.pm >> 4) * g.a_adj : cA; const char* nB = has_next ? (const char*)g.Bt + (size_t)nxt.pn * tstepB : cB;
;         for (int t = 0; t < nt; t += 2) {
;             const bool last = (t == nt - 2);
;             const char* a1 = cA + (size_t)(t + 1) * kstep;
;             const char* a2 = last ? nA : cA + (size_t)(t + 2) * kstep; const char* b2 = last ? nB : cB + (size_t)(t + 2) * kstep;
;             const char* a3 = a2 + kstep; const char* b3 = b2 + kstep;
;             PG8_LDB(B0, 0, 0); PG8_LDB(B1, 0, 1); PG8_SCHED; PG8_LDA(At, 0, 0); PG8_STAGE(PG8_SA(1, 1), a1 + hstepA, voffA);
;             PG8_WAIT_V(8); PG8_WAIT_L(0); PG8_BAR; PG8_MMA(0, 0, At, B0); PG8_MMA(0, 1, At, B1); PG8_BAR; PG8_SCHED;
;             PG8_LDA(At, 0, 1); PG8_STAGE(PG8_SB(0, 0), b2, voffB); PG8_STAGE(PG8_SB(0, 1), b2 + hstepB, voffB); PG8_STAGE(PG8_SA(0, 0), a2, voffA);
;             PG8_WAIT_V(8); PG8_WAIT_L(0); PG8_BAR; PG8_MMA(1, 0, At, B0); PG8_MMA(1, 1, At, B1); PG8_BAR; PG8_SCHED;
.LBB0_305:
	s_ashr_i32 s37, s36, 31
	s_lshl_b64 s[4:5], s[36:37], 19
	s_add_u32 s38, s18, s4
	s_addc_u32 s39, s19, s5
	s_and_b64 s[4:5], s[8:9], exec
	s_cselect_b32 s4, s39, s59
	s_cselect_b32 s5, s38, s58
	s_ashr_i32 s35, s34, 31
	s_lshl_b64 s[50:51], s[34:35], 19
	s_add_u32 s90, s1, s50
	s_addc_u32 s91, s14, s51
	s_and_b64 s[50:51], s[8:9], exec
	s_cselect_b32 s35, s91, s57
	s_cselect_b32 s37, s90, s56
	s_add_u32 s41, s56, 0x100
	s_addc_u32 s49, s57, 0
	s_add_u32 s92, s58, 0x40080
	s_addc_u32 s93, s59, 0
	s_mov_b32 s50, -2
	s_add_u32 s30, s92, 0xfffc0080
	s_addc_u32 s31, s93, -1
	s_cmp_eq_u32 s50, 12
	s_cselect_b32 s60, s5, s30
	s_cselect_b32 s61, s4, s31
	s_cselect_b32 s58, s37, s41
	s_cselect_b32 s59, s35, s49
	s_add_u32 s56, s60, 0x80
	s_addc_u32 s57, s61, 0
	s_mov_b32 m0, s67
	s_nop 0
	global_load_lds_dwordx4 v0, s[92:93]
	s_nop 0
	s_mov_b32 m0, s65
	s_nop 0
	global_load_lds_dwordx4 v181, s[92:93]
	s_waitcnt vmcnt(8)
	s_waitcnt lgkmcnt(0)
	s_barrier
	s_setprio 1
	s_waitcnt lgkmcnt(0)
	v_mfma_f32_16x16x32_bf16 v[142:145], v[74:77], v[162:165], 0
	v_mfma_f32_16x16x32_bf16 v[142:145], v[94:97], v[166:169], v[142:145]
	v_mfma_f32_16x16x32_bf16 v[138:141], v[114:117], v[162:165], 0
	v_mfma_f32_16x16x32_bf16 v[138:141], v[134:137], v[166:169], v[138:141]
	v_mfma_f32_16x16x32_bf16 v[130:133], v[146:149], v[162:165], 0
	v_mfma_f32_16x16x32_bf16 v[130:133], v[150:153], v[166:169], v[130:133]
	v_mfma_f32_16x16x32_bf16 v[126:129], v[154:157], v[162:165], 0
	v_mfma_f32_16x16x32_bf16 v[126:129], v[158:161], v[166:169], v[126:129]
	v_mfma_f32_16x16x32_bf16 v[106:109], v[154:157], v[170:173], 0
	v_mfma_f32_16x16x32_bf16 v[106:109], v[158:161], v[174:177], v[106:109]
	v_mfma_f32_16x16x32_bf16 v[110:113], v[146:149], v[170:173], 0
	v_mfma_f32_16x16x32_bf16 v[110:113], v[150:153], v[174:177], v[110:113]
	v_mfma_f32_16x16x32_bf16 v[118:121], v[114:117], v[170:173], 0
	v_mfma_f32_16x16x32_bf16 v[118:121], v[134:137], v[174:177], v[118:121]
	v_mfma_f32_16x16x32_bf16 v[122:125], v[74:77], v[170:173], 0
	v_mfma_f32_16x16x32_bf16 v[122:125], v[94:97], v[174:177], v[122:125]
	v_mfma_f32_16x16x32_bf16 v[102:105], v[74:77], v[188:191], 0
	v_mfma_f32_16x16x32_bf16 v[102:105], v[94:97], v[202:205], v[102:105]
	v_mfma_f32_16x16x32_bf16 v[98:101], v[114:117], v[188:191], 0
	v_mfma_f32_16x16x32_bf16 v[98:101], v[134:137], v[202:205], v[98:101]
	v_mfma_f32_16x16x32_bf16 v[90:93], v[146:149], v[188:191], 0
	v_mfma_f32_16x16x32_bf16 v[90:93], v[150:153], v[202:205], v[90:93]
	v_mfma_f32_16x16x32_bf16 v[86:89], v[154:157], v[188:191], 0
	v_mfma_f32_16x16x32_bf16 v[86:89], v[158:161], v[202:205], v[86:89]
	v_mfma_f32_16x16x32_bf16 v[66:69], v[154:157], v[206:209], 0
	v_mfma_f32_16x16x32_bf16 v[66:69], v[158:161], v[210:213], v[66:69]
	v_mfma_f32_16x16x32_bf16 v[70:73], v[146:149], v[206:209], 0
	v_mfma_f32_16x16x32_bf16 v[70:73], v[150:153], v[210:213], v[70:73]
	v_mfma_f32_16x16x32_bf16 v[78:81], v[114:117], v[206:209], 0
	v_mfma_f32_16x16x32_bf16 v[78:81], v[134:137], v[210:213], v[78:81]
	v_mfma_f32_16x16x32_bf16 v[82:85], v[74:77], v[206:209], 0
	v_mfma_f32_16x16x32_bf16 v[82:85], v[94:97], v[210:213], v[82:85]
	s_setprio 0
	s_barrier
	ds_read_b128 v[162:165], v186 offset:16384
	ds_read_b128 v[166:169], v186 offset:17408
	ds_read_b128 v[170:173], v186 offset:18432
	ds_read_b128 v[174:177], v186 offset:19456
	ds_read_b128 v[188:191], v186 offset:20480
	ds_read_b128 v[202:205], v186 offset:21504
	ds_read_b128 v[206:209], v186 offset:22528
	ds_read_b128 v[210:213], v186 offset:23552
	s_mov_b32 m0, s29
	s_nop 0
	global_load_lds_dwordx4 v180, s[58:59]
	s_add_u32 s30, s58, 0x40000
	s_mov_b32 m0, s42
	s_nop 0
	global_load_lds_dwordx4 v182, s[58:59]
	s_addc_u32 s31, s59, 0
	s_mov_b32 m0, s43
	s_nop 0
	global_load_lds_dwordx4 v180, s[30:31]
	s_nop 0
	s_mov_b32 m0, s44
	s_nop 0
	global_load_lds_dwordx4 v182, s[30:31]
	s_nop 0
	s_mov_b32 m0, s15
	s_nop 0
	global_load_lds_dwordx4 v0, s[60:61]
	s_nop 0
	s_mov_b32 m0, s45
	s_nop 0
	global_load_lds_dwordx4 v181, s[60:61]
	s_waitcnt vmcnt(8)
	s_waitcnt lgkmcnt(0)
	s_nop 0
	s_barrier
	s_setprio 1
	s_waitcnt lgkmcnt(0)
	v_mfma_f32_16x16x32_bf16 v[62:65], v[74:77], v[162:165], 0
	v_mfma_f32_16x16x32_bf16 v[62:65], v[94:97], v[166:169], v[62:65]
	v_mfma_f32_16x16x32_bf16 v[58:61], v[114:117], v[162:165], 0
	v_mfma_f32_16x16x32_bf16 v[58:61], v[134:137], v[166:169], v[58:61]
	v_mfma_f32_16x16x32_bf16 v[54:57], v[146:149], v[162:165], 0
	v_mfma_f32_16x16x32_bf16 v[54:57], v[150:153], v[166:169], v[54:57]
	v_mfma_f32_16x16x32_bf16 v[50:53], v[154:157], v[162:165], 0
	v_mfma_f32_16x16x32_bf16 v[50:53], v[158:161], v[166:169], v[50:53]
	v_mfma_f32_16x16x32_bf16 v[34:37], v[154:157], v[170:173], 0
	v_mfma_f32_16x16x32_bf16 v[34:37], v[158:161], v[174:177], v[34:37]
	v_mfma_f32_16x16x32_bf16 v[38:41], v[146:149], v[170:173], 0
	v_mfma_f32_16x16x32_bf16 v[38:41], v[150:153], v[174:177], v[38:41]
	v_mfma_f32_16x16x32_bf16 v[42:45], v[114:117], v[170:173], 0
	v_mfma_f32_16x16x32_bf16 v[42:45], v[134:137], v[174:177], v[42:45]
	v_mfma_f32_16x16x32_bf16 v[46:49], v[74:77], v[170:173], 0
	v_mfma_f32_16x16x32_bf16 v[46:49], v[94:97], v[174:177], v[46:49]
	v_mfma_f32_16x16x32_bf16 v[30:33], v[74:77], v[188:191], 0
	v_mfma_f32_16x16x32_bf16 v[30:33], v[94:97], v[202:205], v[30:33]
	v_mfma_f32_16x16x32_bf16 v[26:29], v[114:117], v[188:191], 0
	v_mfma_f32_16x16x32_bf16 v[26:29], v[134:137], v[202:205], v[26:29]
	v_mfma_f32_16x16x32_bf16 v[22:25], v[146:149], v[188:191], 0
	v_mfma_f32_16x16x32_bf16 v[22:25], v[150:153], v[202:205], v[22:25]
	v_mfma_f32_16x16x32_bf16 v[18:21], v[154:157], v[188:191], 0
	v_mfma_f32_16x16x32_bf16 v[18:21], v[158:161], v[202:205], v[18:21]
	v_mfma_f32_16x16x32_bf16 v[2:5], v[154:157], v[206:209], 0
	v_mfma_f32_16x16x32_bf16 v[2:5], v[158:161], v[210:213], v[2:5]
	v_mfma_f32_16x16x32_bf16 v[6:9], v[146:149], v[206:209], 0
	v_mfma_f32_16x16x32_bf16 v[6:9], v[150:153], v[210:213], v[6:9]
	v_mfma_f32_16x16x32_bf16 v[10:13], v[114:117], v[206:209], 0
	v_mfma_f32_16x16x32_bf16 v[10:13], v[134:137], v[210:213], v[10:13]
	v_mfma_f32_16x16x32_bf16 v[14:17], v[74:77], v[206:209], 0
	v_mfma_f32_16x16x32_bf16 v[14:17], v[94:97], v[210:213], v[14:17]
	s_setprio 0
	s_barrier
; #define PG8_STAGE(bufoff, gbase, voff) do { _Pragma("unroll") for (int _i = 0; _i < 2; ++_i) { \
;         const unsigned _m0 = ldsb + (unsigned)((bufoff) + _i * 8192); const char* _gb = (const char*)(gbase); \
;         asm volatile("s_mov_b32 m0, %0\n\ts_nop 0\n\tglobal_load_lds_dwordx4 %1, %2" :: "s"(_m0), "v"((voff)[_i]), "s"(_gb) : "m0", "memory"); } } while (0)
; #define PG8_LDA(dst, b, h) do { _Pragma("unroll") for (int m = 0; m < 4; ++m) _Pragma("unroll") for (int k = 0; k < 2; ++k) dst[m][k] = *(const LAS bf16x8*)(lds + PG8_SA(b, h) + aoff + m * 2048 + k * 1024); } while (0)
; #define PG8_LDB(dst, b, h) do { _Pragma("unroll") for (int n = 0; n < 2; ++n) _Pragma("unroll") for (int k = 0; k < 2; ++k) dst[n][k] = *(const LAS bf16x8*)(lds + PG8_SB(b, h) + boff + n * 2048 + k * 1024); } while (0)
; #define PG8_MMA(ai, bj, At, Bt) do { __builtin_amdgcn_s_setprio(1); _Pragma("unroll") for (int m = 0; m < 4; ++m) _Pragma("unroll") for (int n = 0; n < 2; ++n) _Pragma("unroll") for (int k = 0; k < 2; ++k) \
;         acc[ai][bj][m][n] = __builtin_amdgcn_mfma_f32_16x16x32_bf16(Bt[n][k], At[m][k], acc[ai][bj][m][n], 0, 0, 0); __builtin_amdgcn_s_setprio(0); } while (0)
; #define PG8_WAIT_V(n) asm volatile("s_waitcnt vmcnt(" #n ")" ::: "memory")
; #define PG8_WAIT_L(n) asm volatile("s_waitcnt lgkmcnt(" #n ")" ::: "memory")
; #define PG8_BAR __builtin_amdgcn_s_barrier()
; #define PG8_SCHED __builtin_amdgcn_sched_barrier(0)
; template <class Epi, bool ALIGN_EPI>
; __device__ __forceinline__ void gemm_phase(LAS unsigned char* lds, const Gemm g, const StaticOrder& S, const Epi& E) {
;     ...
;             PG8_LDB(B0, 1, 0); PG8_LDB(B1, 1, 1); PG8_SCHED; PG8_LDA(At, 1, 0); PG8_STAGE(PG8_SA(0, 1), a2 + hstepA, voffA);
;             PG8_WAIT_V(8); PG8_WAIT_L(0); PG8_BAR; PG8_MMA(0, 0, At, B0); PG8_MMA(0, 1, At, B1); PG8_BAR; PG8_SCHED;
;             PG8_LDA(At, 1, 1); PG8_STAGE(PG8_SB(1, 0), b3, voffB); PG8_STAGE(PG8_SB(1, 1), b3 + hstepB, voffB); PG8_STAGE(PG8_SA(1, 0), a3, voffA);
;             PG8_WAIT_V(8); PG8_WAIT_L(0); PG8_BAR; PG8_MMA(1, 0, At, B0); PG8_MMA(1, 1, At, B1); PG8_BAR; PG8_SCHED;
	v_add_u32_e32 v134, 0x18000, v185
	v_add_u32_e32 v158, 0x1c000, v185
	ds_read_b128 v[74:77], v134
	ds_read_b128 v[94:97], v134 offset:1024
	ds_read_b128 v[114:117], v134 offset:2048
	ds_read_b128 v[134:137], v134 offset:3072
	ds_read_b128 v[146:149], v158
	ds_read_b128 v[150:153], v158 offset:1024
	ds_read_b128 v[154:157], v158 offset:2048
	ds_read_b128 v[158:161], v158 offset:3072
	ds_read_b128 v[162:165], v186 offset:32768
	ds_read_b128 v[166:169], v186 offset:33792
	ds_read_b128 v[170:173], v186 offset:34816
	ds_read_b128 v[174:177], v186 offset:35840
	ds_read_b128 v[188:191], v186 offset:36864
	ds_read_b128 v[202:205], v186 offset:37888
	ds_read_b128 v[206:209], v186 offset:38912
	ds_read_b128 v[210:213], v186 offset:39936
	s_add_u32 s30, s60, 0x40000
	s_addc_u32 s31, s61, 0
	s_mov_b32 m0, s55
	s_nop 0
	global_load_lds_dwordx4 v0, s[30:31]
	s_nop 0
	s_mov_b32 m0, s88
	s_nop 0
	global_load_lds_dwordx4 v181, s[30:31]
	s_waitcnt vmcnt(8)
	s_waitcnt lgkmcnt(0)
	s_nop 0
	s_barrier
	s_setprio 1
	s_waitcnt lgkmcnt(0)
	v_mfma_f32_16x16x32_bf16 v[142:145], v[74:77], v[162:165], v[142:145]
	v_mfma_f32_16x16x32_bf16 v[142:145], v[94:97], v[166:169], v[142:145]
	v_mfma_f32_16x16x32_bf16 v[138:141], v[114:117], v[162:165], v[138:141]
	v_mfma_f32_16x16x32_bf16 v[138:141], v[134:137], v[166:169], v[138:141]
	v_mfma_f32_16x16x32_bf16 v[130:133], v[146:149], v[162:165], v[130:133]
	v_mfma_f32_16x16x32_bf16 v[130:133], v[150:153], v[166:169], v[130:133]
	v_mfma_f32_16x16x32_bf16 v[126:129], v[154:157], v[162:165], v[126:129]
	v_mfma_f32_16x16x32_bf16 v[126:129], v[158:161], v[166:169], v[126:129]
	v_mfma_f32_16x16x32_bf16 v[106:109], v[154:157], v[170:173], v[106:109]
	v_mfma_f32_16x16x32_bf16 v[106:109], v[158:161], v[174:177], v[106:109]
	v_mfma_f32_16x16x32_bf16 v[110:113], v[146:149], v[170:173], v[110:113]
	v_mfma_f32_16x16x32_bf16 v[110:113], v[150:153], v[174:177], v[110:113]
	v_mfma_f32_16x16x32_bf16 v[118:121], v[114:117], v[170:173], v[118:121]
	v_mfma_f32_16x16x32_bf16 v[118:121], v[134:137], v[174:177], v[118:121]
	v_mfma_f32_16x16x32_bf16 v[122:125], v[74:77], v[170:173], v[122:125]
	v_mfma_f32_16x16x32_bf16 v[122:125], v[94:97], v[174:177], v[122:125]
	v_mfma_f32_16x16x32_bf16 v[102:105], v[74:77], v[188:191], v[102:105]
	v_mfma_f32_16x16x32_bf16 v[102:105], v[94:97], v[202:205], v[102:105]
	v_mfma_f32_16x16x32_bf16 v[98:101], v[114:117], v[188:191], v[98:101]
	v_mfma_f32_16x16x32_bf16 v[98:101], v[134:137], v[202:205], v[98:101]
	v_mfma_f32_16x16x32_bf16 v[90:93], v[146:149], v[188:191], v[90:93]
	v_mfma_f32_16x16x32_bf16 v[90:93], v[150:153], v[202:205], v[90:93]
	v_mfma_f32_16x16x32_bf16 v[86:89], v[154:157], v[188:191], v[86:89]
	v_mfma_f32_16x16x32_bf16 v[86:89], v[158:161], v[202:205], v[86:89]
	v_mfma_f32_16x16x32_bf16 v[66:69], v[154:157], v[206:209], v[66:69]
	v_mfma_f32_16x16x32_bf16 v[66:69], v[158:161], v[210:213], v[66:69]
	v_mfma_f32_16x16x32_bf16 v[70:73], v[146:149], v[206:209], v[70:73]
	v_mfma_f32_16x16x32_bf16 v[70:73], v[150:153], v[210:213], v[70:73]
	v_mfma_f32_16x16x32_bf16 v[78:81], v[114:117], v[206:209], v[78:81]
	v_mfma_f32_16x16x32_bf16 v[78:81], v[134:137], v[210:213], v[78:81]
	v_mfma_f32_16x16x32_bf16 v[82:85], v[74:77], v[206:209], v[82:85]
	v_mfma_f32_16x16x32_bf16 v[82:85], v[94:97], v[210:213], v[82:85]
	s_setprio 0
	s_barrier
	ds_read_b128 v[162:165], v186 offset:49152
	ds_read_b128 v[166:169], v186 offset:50176
	ds_read_b128 v[170:173], v186 offset:51200
	ds_read_b128 v[174:177], v186 offset:52224
	ds_read_b128 v[188:191], v186 offset:53248
	ds_read_b128 v[202:205], v186 offset:54272
	ds_read_b128 v[206:209], v186 offset:55296
	ds_read_b128 v[210:213], v186 offset:56320
	s_add_u32 s30, s58, 0x80
	s_addc_u32 s31, s59, 0
	s_mov_b32 m0, s94
	s_nop 0
	global_load_lds_dwordx4 v180, s[30:31]
	s_nop 0
	s_mov_b32 m0, s95
	s_nop 0
	global_load_lds_dwordx4 v182, s[30:31]
	s_add_u32 s30, s58, 0x40080
	s_addc_u32 s31, s59, 0
	s_mov_b32 m0, s17
	s_nop 0
	global_load_lds_dwordx4 v180, s[30:31]
	s_nop 0
	s_mov_b32 m0, s53
	s_nop 0
	global_load_lds_dwordx4 v182, s[30:31]
	s_nop 0
	s_mov_b32 m0, s96
	s_nop 0
	global_load_lds_dwordx4 v0, s[56:57]
	s_nop 0
	s_mov_b32 m0, s97
	s_nop 0
	global_load_lds_dwordx4 v181, s[56:57]
	s_waitcnt vmcnt(8)
	s_waitcnt lgkmcnt(0)
	s_nop 0
	s_barrier
	s_setprio 1
	s_waitcnt lgkmcnt(0)
	v_mfma_f32_16x16x32_bf16 v[62:65], v[74:77], v[162:165], v[62:65]
	v_mfma_f32_16x16x32_bf16 v[62:65], v[94:97], v[166:169], v[62:65]
	v_mfma_f32_16x16x32_bf16 v[58:61], v[114:117], v[162:165], v[58:61]
	v_mfma_f32_16x16x32_bf16 v[58:61], v[134:137], v[166:169], v[58:61]
	v_mfma_f32_16x16x32_bf16 v[54:57], v[146:149], v[162:165], v[54:57]
	v_mfma_f32_16x16x32_bf16 v[54:57], v[150:153], v[166:169], v[54:57]
	v_mfma_f32_16x16x32_bf16 v[50:53], v[154:157], v[162:165], v[50:53]
	v_mfma_f32_16x16x32_bf16 v[50:53], v[158:161], v[166:169], v[50:53]
	v_mfma_f32_16x16x32_bf16 v[34:37], v[154:157], v[170:173], v[34:37]
	v_mfma_f32_16x16x32_bf16 v[34:37], v[158:161], v[174:177], v[34:37]
	v_mfma_f32_16x16x32_bf16 v[38:41], v[146:149], v[170:173], v[38:41]
	v_mfma_f32_16x16x32_bf16 v[38:41], v[150:153], v[174:177], v[38:41]
	v_mfma_f32_16x16x32_bf16 v[42:45], v[114:117], v[170:173], v[42:45]
	v_mfma_f32_16x16x32_bf16 v[42:45], v[134:137], v[174:177], v[42:45]
	v_mfma_f32_16x16x32_bf16 v[46:49], v[74:77], v[170:173], v[46:49]
	v_mfma_f32_16x16x32_bf16 v[46:49], v[94:97], v[174:177], v[46:49]
	v_mfma_f32_16x16x32_bf16 v[30:33], v[74:77], v[188:191], v[30:33]
	v_mfma_f32_16x16x32_bf16 v[30:33], v[94:97], v[202:205], v[30:33]
	v_mfma_f32_16x16x32_bf16 v[26:29], v[114:117], v[188:191], v[26:29]
	v_mfma_f32_16x16x32_bf16 v[26:29], v[134:137], v[202:205], v[26:29]
	v_mfma_f32_16x16x32_bf16 v[22:25], v[146:149], v[188:191], v[22:25]
	v_mfma_f32_16x16x32_bf16 v[22:25], v[150:153], v[202:205], v[22:25]
	v_mfma_f32_16x16x32_bf16 v[18:21], v[154:157], v[188:191], v[18:21]
	v_mfma_f32_16x16x32_bf16 v[18:21], v[158:161], v[202:205], v[18:21]
	v_mfma_f32_16x16x32_bf16 v[2:5], v[154:157], v[206:209], v[2:5]
	v_mfma_f32_16x16x32_bf16 v[2:5], v[158:161], v[210:213], v[2:5]
	v_mfma_f32_16x16x32_bf16 v[6:9], v[146:149], v[206:209], v[6:9]
	v_mfma_f32_16x16x32_bf16 v[6:9], v[150:153], v[210:213], v[6:9]
	v_mfma_f32_16x16x32_bf16 v[10:13], v[114:117], v[206:209], v[10:13]
	v_mfma_f32_16x16x32_bf16 v[10:13], v[134:137], v[210:213], v[10:13]
	v_mfma_f32_16x16x32_bf16 v[14:17], v[74:77], v[206:209], v[14:17]
	v_mfma_f32_16x16x32_bf16 v[14:17], v[94:97], v[210:213], v[14:17]
	s_setprio 0
	s_barrier
	s_add_i32 s50, s50, 2
	s_add_u32 s41, s41, 0x100
	s_addc_u32 s49, s49, 0
	s_add_u32 s92, s92, 0x100
	s_addc_u32 s93, s93, 0
	s_cmp_gt_u32 s50, 13
; #define PG8_STAGE(bufoff, gbase, voff) do { _Pragma("unroll") for (int _i = 0; _i < 2; ++_i) { \
;         const unsigned _m0 = ldsb + (unsigned)((bufoff) + _i * 8192); const char* _gb = (const char*)(gbase); \
;         asm volatile("s_mov_b32 m0, %0\n\ts_nop 0\n\tglobal_load_lds_dwordx4 %1, %2" :: "s"(_m0), "v"((voff)[_i]), "s"(_gb) : "m0", "memory"); } } while (0)
; #define PG8_LDA(dst, b, h) do { _Pragma("unroll") for (int m = 0; m < 4; ++m) _Pragma("unroll") for (int k = 0; k < 2; ++k) dst[m][k] = *(const LAS bf16x8*)(lds + PG8_SA(b, h) + aoff + m * 2048 + k * 1024); } while (0)
; #define PG8_LDB(dst, b, h) do { _Pragma("unroll") for (int n = 0; n < 2; ++n) _Pragma("unroll") for (int k = 0; k < 2; ++k) dst[n][k] = *(const LAS bf16x8*)(lds + PG8_SB(b, h) + boff + n * 2048 + k * 1024); } while (0)
; #define PG8_MMA(ai, bj, At, Bt) do { __builtin_amdgcn_s_setprio(1); _Pragma("unroll") for (int m = 0; m < 4; ++m) _Pragma("unroll") for (int n = 0; n < 2; ++n) _Pragma("unroll") for (int k = 0; k < 2; ++k) \
;         acc[ai][bj][m][n] = __builtin_amdgcn_mfma_f32_16x16x32_bf16(Bt[n][k], At[m][k], acc[ai][bj][m][n], 0, 0, 0); __builtin_amdgcn_s_setprio(0); } while (0)
; #define PG8_WAIT_V(n) asm volatile("s_waitcnt vmcnt(" #n ")" ::: "memory")
; #define PG8_WAIT_L(n) asm volatile("s_waitcnt lgkmcnt(" #n ")" ::: "memory")
; template <class Epi, bool ALIGN_EPI>
; __device__ __forceinline__ void gemm_phase(LAS unsigned char* lds, const Gemm g, const StaticOrder& S, const Epi& E) {
;     ...
;         for (int t = 0; t < nt; t += 2) {
;             const bool last = (t == nt - 2);
;             const char* a1 = cA + (size_t)(t + 1) * kstep;
;             const char* a2 = last ? nA : cA + (size_t)(t + 2) * kstep; const char* b2 = last ? nB : cB + (size_t)(t + 2) * kstep;
;             const char* a3 = a2 + kstep; const char* b3 = b2 + kstep;
;             PG8_LDB(B0, 0, 0); PG8_LDB(B1, 0, 1); PG8_SCHED; PG8_LDA(At, 0, 0); PG8_STAGE(PG8_SA(1, 1), a1 + hstepA, voffA);
;             PG8_WAIT_V(8); PG8_WAIT_L(0); PG8_BAR; PG8_MMA(0, 0, At, B0); PG8_MMA(0, 1, At, B1); PG8_BAR; PG8_SCHED;
;             PG8_LDA(At, 0, 1); PG8_STAGE(PG8_SB(0, 0), b2, voffB); PG8_STAGE(PG8_SB(0, 1), b2 + hstepB, voffB); PG8_STAGE(PG8_SA(0, 0), a2, voffA);
;             PG8_WAIT_V(8); PG8_WAIT_L(0); PG8_BAR; PG8_MMA(1, 0, At, B0); PG8_MMA(1, 1, At, B1); PG8_BAR; PG8_SCHED;
.LBB0_306:
	v_add_u32_e32 v134, 0x10000, v185
	v_add_u32_e32 v158, 0x14000, v185
	ds_read_b128 v[74:77], v134
	ds_read_b128 v[94:97], v134 offset:1024
	ds_read_b128 v[114:117], v134 offset:2048
	ds_read_b128 v[134:137], v134 offset:3072
	ds_read_b128 v[146:149], v158
	ds_read_b128 v[150:153], v158 offset:1024
	ds_read_b128 v[154:157], v158 offset:2048
	ds_read_b128 v[158:161], v158 offset:3072
	s_add_u32 s30, s92, 0xfffc0080
	s_addc_u32 s31, s93, -1
	s_cmp_eq_u32 s50, 12
	s_cselect_b32 s60, s5, s30
	s_cselect_b32 s61, s4, s31
	s_cselect_b32 s58, s37, s41
	s_cselect_b32 s59, s35, s49
	s_add_u32 s56, s60, 0x80
	s_addc_u32 s57, s61, 0
	ds_read_b128 v[162:165], v186
	ds_read_b128 v[166:169], v186 offset:1024
	ds_read_b128 v[170:173], v186 offset:2048
	ds_read_b128 v[174:177], v186 offset:3072
	ds_read_b128 v[188:191], v186 offset:4096
	ds_read_b128 v[202:205], v186 offset:5120
	ds_read_b128 v[206:209], v186 offset:6144
	ds_read_b128 v[210:213], v186 offset:7168
	s_mov_b32 m0, s67
	s_nop 0
	global_load_lds_dwordx4 v0, s[92:93]
	s_nop 0
	s_mov_b32 m0, s65
	s_nop 0
	global_load_lds_dwordx4 v181, s[92:93]
	s_waitcnt vmcnt(8)
	s_waitcnt lgkmcnt(0)
	s_nop 0
	s_barrier
	s_setprio 1
	s_waitcnt lgkmcnt(0)
	v_mfma_f32_16x16x32_bf16 v[142:145], v[74:77], v[162:165], v[142:145]
	v_mfma_f32_16x16x32_bf16 v[142:145], v[94:97], v[166:169], v[142:145]
	v_mfma_f32_16x16x32_bf16 v[138:141], v[114:117], v[162:165], v[138:141]
	v_mfma_f32_16x16x32_bf16 v[138:141], v[134:137], v[166:169], v[138:141]
	v_mfma_f32_16x16x32_bf16 v[130:133], v[146:149], v[162:165], v[130:133]
	v_mfma_f32_16x16x32_bf16 v[130:133], v[150:153], v[166:169], v[130:133]
	v_mfma_f32_16x16x32_bf16 v[126:129], v[154:157], v[162:165], v[126:129]
	v_mfma_f32_16x16x32_bf16 v[126:129], v[158:161], v[166:169], v[126:129]
	v_mfma_f32_16x16x32_bf16 v[106:109], v[154:157], v[170:173], v[106:109]
	v_mfma_f32_16x16x32_bf16 v[106:109], v[158:161], v[174:177], v[106:109]
	v_mfma_f32_16x16x32_bf16 v[110:113], v[146:149], v[170:173], v[110:113]
	v_mfma_f32_16x16x32_bf16 v[110:113], v[150:153], v[174:177], v[110:113]
	v_mfma_f32_16x16x32_bf16 v[118:121], v[114:117], v[170:173], v[118:121]
	v_mfma_f32_16x16x32_bf16 v[118:121], v[134:137], v[174:177], v[118:121]
	v_mfma_f32_16x16x32_bf16 v[122:125], v[74:77], v[170:173], v[122:125]
	v_mfma_f32_16x16x32_bf16 v[122:125], v[94:97], v[174:177], v[122:125]
	v_mfma_f32_16x16x32_bf16 v[102:105], v[74:77], v[188:191], v[102:105]
	v_mfma_f32_16x16x32_bf16 v[102:105], v[94:97], v[202:205], v[102:105]
	v_mfma_f32_16x16x32_bf16 v[98:101], v[114:117], v[188:191], v[98:101]
	v_mfma_f32_16x16x32_bf16 v[98:101], v[134:137], v[202:205], v[98:101]
	v_mfma_f32_16x16x32_bf16 v[90:93], v[146:149], v[188:191], v[90:93]
	v_mfma_f32_16x16x32_bf16 v[90:93], v[150:153], v[202:205], v[90:93]
	v_mfma_f32_16x16x32_bf16 v[86:89], v[154:157], v[188:191], v[86:89]
	v_mfma_f32_16x16x32_bf16 v[86:89], v[158:161], v[202:205], v[86:89]
	v_mfma_f32_16x16x32_bf16 v[66:69], v[154:157], v[206:209], v[66:69]
	v_mfma_f32_16x16x32_bf16 v[66:69], v[158:161], v[210:213], v[66:69]
	v_mfma_f32_16x16x32_bf16 v[70:73], v[146:149], v[206:209], v[70:73]
	v_mfma_f32_16x16x32_bf16 v[70:73], v[150:153], v[210:213], v[70:73]
	v_mfma_f32_16x16x32_bf16 v[78:81], v[114:117], v[206:209], v[78:81]
	v_mfma_f32_16x16x32_bf16 v[78:81], v[134:137], v[210:213], v[78:81]
	v_mfma_f32_16x16x32_bf16 v[82:85], v[74:77], v[206:209], v[82:85]
	v_mfma_f32_16x16x32_bf16 v[82:85], v[94:97], v[210:213], v[82:85]
	s_setprio 0
	s_barrier
	ds_read_b128 v[162:165], v186 offset:16384
	ds_read_b128 v[166:169], v186 offset:17408
	ds_read_b128 v[170:173], v186 offset:18432
	ds_read_b128 v[174:177], v186 offset:19456
	ds_read_b128 v[188:191], v186 offset:20480
	ds_read_b128 v[202:205], v186 offset:21504
	ds_read_b128 v[206:209], v186 offset:22528
	ds_read_b128 v[210:213], v186 offset:23552
	s_mov_b32 m0, s29
	s_nop 0
	global_load_lds_dwordx4 v180, s[58:59]
	s_add_u32 s30, s58, 0x40000
	s_mov_b32 m0, s42
	s_nop 0
	global_load_lds_dwordx4 v182, s[58:59]
	s_addc_u32 s31, s59, 0
	s_mov_b32 m0, s43
	s_nop 0
	global_load_lds_dwordx4 v180, s[30:31]
	s_nop 0
	s_mov_b32 m0, s44
	s_nop 0
	global_load_lds_dwordx4 v182, s[30:31]
	s_nop 0
	s_mov_b32 m0, s15
	s_nop 0
	global_load_lds_dwordx4 v0, s[60:61]
	s_nop 0
	s_mov_b32 m0, s45
	s_nop 0
	global_load_lds_dwordx4 v181, s[60:61]
	s_waitcnt vmcnt(8)
	s_waitcnt lgkmcnt(0)
	s_nop 0
	s_barrier
	s_setprio 1
	s_waitcnt lgkmcnt(0)
	v_mfma_f32_16x16x32_bf16 v[62:65], v[74:77], v[162:165], v[62:65]
	v_mfma_f32_16x16x32_bf16 v[62:65], v[94:97], v[166:169], v[62:65]
	v_mfma_f32_16x16x32_bf16 v[58:61], v[114:117], v[162:165], v[58:61]
	v_mfma_f32_16x16x32_bf16 v[58:61], v[134:137], v[166:169], v[58:61]
	v_mfma_f32_16x16x32_bf16 v[54:57], v[146:149], v[162:165], v[54:57]
	v_mfma_f32_16x16x32_bf16 v[54:57], v[150:153], v[166:169], v[54:57]
	v_mfma_f32_16x16x32_bf16 v[50:53], v[154:157], v[162:165], v[50:53]
	v_mfma_f32_16x16x32_bf16 v[50:53], v[158:161], v[166:169], v[50:53]
	v_mfma_f32_16x16x32_bf16 v[34:37], v[154:157], v[170:173], v[34:37]
	v_mfma_f32_16x16x32_bf16 v[34:37], v[158:161], v[174:177], v[34:37]
	v_mfma_f32_16x16x32_bf16 v[38:41], v[146:149], v[170:173], v[38:41]
	v_mfma_f32_16x16x32_bf16 v[38:41], v[150:153], v[174:177], v[38:41]
	v_mfma_f32_16x16x32_bf16 v[42:45], v[114:117], v[170:173], v[42:45]
	v_mfma_f32_16x16x32_bf16 v[42:45], v[134:137], v[174:177], v[42:45]
	v_mfma_f32_16x16x32_bf16 v[46:49], v[74:77], v[170:173], v[46:49]
	v_mfma_f32_16x16x32_bf16 v[46:49], v[94:97], v[174:177], v[46:49]
	v_mfma_f32_16x16x32_bf16 v[30:33], v[74:77], v[188:191], v[30:33]
	v_mfma_f32_16x16x32_bf16 v[30:33], v[94:97], v[202:205], v[30:33]
	v_mfma_f32_16x16x32_bf16 v[26:29], v[114:117], v[188:191], v[26:29]
	v_mfma_f32_16x16x32_bf16 v[26:29], v[134:137], v[202:205], v[26:29]
	v_mfma_f32_16x16x32_bf16 v[22:25], v[146:149], v[188:191], v[22:25]
	v_mfma_f32_16x16x32_bf16 v[22:25], v[150:153], v[202:205], v[22:25]
	v_mfma_f32_16x16x32_bf16 v[18:21], v[154:157], v[188:191], v[18:21]
	v_mfma_f32_16x16x32_bf16 v[18:21], v[158:161], v[202:205], v[18:21]
	v_mfma_f32_16x16x32_bf16 v[2:5], v[154:157], v[206:209], v[2:5]
	v_mfma_f32_16x16x32_bf16 v[2:5], v[158:161], v[210:213], v[2:5]
	v_mfma_f32_16x16x32_bf16 v[6:9], v[146:149], v[206:209], v[6:9]
	v_mfma_f32_16x16x32_bf16 v[6:9], v[150:153], v[210:213], v[6:9]
	v_mfma_f32_16x16x32_bf16 v[10:13], v[114:117], v[206:209], v[10:13]
	v_mfma_f32_16x16x32_bf16 v[10:13], v[134:137], v[210:213], v[10:13]
	v_mfma_f32_16x16x32_bf16 v[14:17], v[74:77], v[206:209], v[14:17]
	v_mfma_f32_16x16x32_bf16 v[14:17], v[94:97], v[210:213], v[14:17]
	s_setprio 0
	s_barrier
; #define PG8_STAGE(bufoff, gbase, voff) do { _Pragma("unroll") for (int _i = 0; _i < 2; ++_i) { \
;         const unsigned _m0 = ldsb + (unsigned)((bufoff) + _i * 8192); const char* _gb = (const char*)(gbase); \
;         asm volatile("s_mov_b32 m0, %0\n\ts_nop 0\n\tglobal_load_lds_dwordx4 %1, %2" :: "s"(_m0), "v"((voff)[_i]), "s"(_gb) : "m0", "memory"); } } while (0)
; #define PG8_LDA(dst, b, h) do { _Pragma("unroll") for (int m = 0; m < 4; ++m) _Pragma("unroll") for (int k = 0; k < 2; ++k) dst[m][k] = *(const LAS bf16x8*)(lds + PG8_SA(b, h) + aoff + m * 2048 + k * 1024); } while (0)
; #define PG8_LDB(dst, b, h) do { _Pragma("unroll") for (int n = 0; n < 2; ++n) _Pragma("unroll") for (int k = 0; k < 2; ++k) dst[n][k] = *(const LAS bf16x8*)(lds + PG8_SB(b, h) + boff + n * 2048 + k * 1024); } while (0)
; #define PG8_MMA(ai, bj, At, Bt) do { __builtin_amdgcn_s_setprio(1); _Pragma("unroll") for (int m = 0; m < 4; ++m) _Pragma("unroll") for (int n = 0; n < 2; ++n) _Pragma("unroll") for (int k = 0; k < 2; ++k) \
;         acc[ai][bj][m][n] = __builtin_amdgcn_mfma_f32_16x16x32_bf16(Bt[n][k], At[m][k], acc[ai][bj][m][n], 0, 0, 0); __builtin_amdgcn_s_setprio(0); } while (0)
; #define PG8_WAIT_V(n) asm volatile("s_waitcnt vmcnt(" #n ")" ::: "memory")
; #define PG8_WAIT_L(n) asm volatile("s_waitcnt lgkmcnt(" #n ")" ::: "memory")
; #define PG8_BAR __builtin_amdgcn_s_barrier()
; #define PG8_SCHED __builtin_amdgcn_sched_barrier(0)
; template <class Epi, bool ALIGN_EPI>
; __device__ __forceinline__ void gemm_phase(LAS unsigned char* lds, const Gemm g, const StaticOrder& S, const Epi& E) {
;     ...
;             PG8_LDB(B0, 1, 0); PG8_LDB(B1, 1, 1); PG8_SCHED; PG8_LDA(At, 1, 0); PG8_STAGE(PG8_SA(0, 1), a2 + hstepA, voffA);
;             PG8_WAIT_V(8); PG8_WAIT_L(0); PG8_BAR; PG8_MMA(0, 0, At, B0); PG8_MMA(0, 1, At, B1); PG8_BAR; PG8_SCHED;
;             PG8_LDA(At, 1, 1); PG8_STAGE(PG8_SB(1, 0), b3, voffB); PG8_STAGE(PG8_SB(1, 1), b3 + hstepB, voffB); PG8_STAGE(PG8_SA(1, 0), a3, voffA);
;             PG8_WAIT_V(8); PG8_WAIT_L(0); PG8_BAR; PG8_MMA(1, 0, At, B0); PG8_MMA(1, 1, At, B1); PG8_BAR; PG8_SCHED;
;         }
;         if constexpr (ALIGN_EPI) { if (wr == 0) PG8_BAR; }
	v_add_u32_e32 v134, 0x18000, v185
	v_add_u32_e32 v158, 0x1c000, v185
	ds_read_b128 v[74:77], v134
	ds_read_b128 v[94:97], v134 offset:1024
	ds_read_b128 v[114:117], v134 offset:2048
	ds_read_b128 v[134:137], v134 offset:3072
	ds_read_b128 v[146:149], v158
	ds_read_b128 v[150:153], v158 offset:1024
	ds_read_b128 v[154:157], v158 offset:2048
	ds_read_b128 v[158:161], v158 offset:3072
	ds_read_b128 v[162:165], v186 offset:32768
	ds_read_b128 v[166:169], v186 offset:33792
	ds_read_b128 v[170:173], v186 offset:34816
	ds_read_b128 v[174:177], v186 offset:35840
	ds_read_b128 v[188:191], v186 offset:36864
	ds_read_b128 v[202:205], v186 offset:37888
	ds_read_b128 v[206:209], v186 offset:38912
	ds_read_b128 v[210:213], v186 offset:39936
	s_add_u32 s30, s60, 0x40000
	s_addc_u32 s31, s61, 0
	s_mov_b32 m0, s55
	s_nop 0
	global_load_lds_dwordx4 v0, s[30:31]
	s_nop 0
	s_mov_b32 m0, s88
	s_nop 0
	global_load_lds_dwordx4 v181, s[30:31]
	s_waitcnt vmcnt(8)
	s_waitcnt lgkmcnt(0)
	s_nop 0
	s_barrier
	s_setprio 1
	s_waitcnt lgkmcnt(0)
	v_mfma_f32_16x16x32_bf16 v[142:145], v[74:77], v[162:165], v[142:145]
	v_mfma_f32_16x16x32_bf16 v[142:145], v[94:97], v[166:169], v[142:145]
	v_mfma_f32_16x16x32_bf16 v[138:141], v[114:117], v[162:165], v[138:141]
	v_mfma_f32_16x16x32_bf16 v[138:141], v[134:137], v[166:169], v[138:141]
	v_mfma_f32_16x16x32_bf16 v[130:133], v[146:149], v[162:165], v[130:133]
	v_mfma_f32_16x16x32_bf16 v[130:133], v[150:153], v[166:169], v[130:133]
	v_mfma_f32_16x16x32_bf16 v[126:129], v[154:157], v[162:165], v[126:129]
	v_mfma_f32_16x16x32_bf16 v[126:129], v[158:161], v[166:169], v[126:129]
	v_mfma_f32_16x16x32_bf16 v[106:109], v[154:157], v[170:173], v[106:109]
	v_mfma_f32_16x16x32_bf16 v[106:109], v[158:161], v[174:177], v[106:109]
	v_mfma_f32_16x16x32_bf16 v[110:113], v[146:149], v[170:173], v[110:113]
	v_mfma_f32_16x16x32_bf16 v[110:113], v[150:153], v[174:177], v[110:113]
	v_mfma_f32_16x16x32_bf16 v[118:121], v[114:117], v[170:173], v[118:121]
	v_mfma_f32_16x16x32_bf16 v[118:121], v[134:137], v[174:177], v[118:121]
	v_mfma_f32_16x16x32_bf16 v[122:125], v[74:77], v[170:173], v[122:125]
	v_mfma_f32_16x16x32_bf16 v[122:125], v[94:97], v[174:177], v[122:125]
	v_mfma_f32_16x16x32_bf16 v[102:105], v[74:77], v[188:191], v[102:105]
	v_mfma_f32_16x16x32_bf16 v[102:105], v[94:97], v[202:205], v[102:105]
	v_mfma_f32_16x16x32_bf16 v[98:101], v[114:117], v[188:191], v[98:101]
	v_mfma_f32_16x16x32_bf16 v[98:101], v[134:137], v[202:205], v[98:101]
	v_mfma_f32_16x16x32_bf16 v[90:93], v[146:149], v[188:191], v[90:93]
	v_mfma_f32_16x16x32_bf16 v[90:93], v[150:153], v[202:205], v[90:93]
	v_mfma_f32_16x16x32_bf16 v[86:89], v[154:157], v[188:191], v[86:89]
	v_mfma_f32_16x16x32_bf16 v[86:89], v[158:161], v[202:205], v[86:89]
	v_mfma_f32_16x16x32_bf16 v[66:69], v[154:157], v[206:209], v[66:69]
	v_mfma_f32_16x16x32_bf16 v[66:69], v[158:161], v[210:213], v[66:69]
	v_mfma_f32_16x16x32_bf16 v[70:73], v[146:149], v[206:209], v[70:73]
	v_mfma_f32_16x16x32_bf16 v[70:73], v[150:153], v[210:213], v[70:73]
	v_mfma_f32_16x16x32_bf16 v[78:81], v[114:117], v[206:209], v[78:81]
	v_mfma_f32_16x16x32_bf16 v[78:81], v[134:137], v[210:213], v[78:81]
	v_mfma_f32_16x16x32_bf16 v[82:85], v[74:77], v[206:209], v[82:85]
	v_mfma_f32_16x16x32_bf16 v[82:85], v[94:97], v[210:213], v[82:85]
	s_setprio 0
	s_barrier
	ds_read_b128 v[162:165], v186 offset:49152
	ds_read_b128 v[166:169], v186 offset:50176
	ds_read_b128 v[170:173], v186 offset:51200
	ds_read_b128 v[174:177], v186 offset:52224
	ds_read_b128 v[188:191], v186 offset:53248
	ds_read_b128 v[202:205], v186 offset:54272
	ds_read_b128 v[206:209], v186 offset:55296
	ds_read_b128 v[210:213], v186 offset:56320
	s_add_u32 s30, s58, 0x80
	s_addc_u32 s31, s59, 0
	s_mov_b32 m0, s94
	s_nop 0
	global_load_lds_dwordx4 v180, s[30:31]
	s_nop 0
	s_mov_b32 m0, s95
	s_nop 0
	global_load_lds_dwordx4 v182, s[30:31]
	s_add_u32 s30, s58, 0x40080
	s_addc_u32 s31, s59, 0
	s_mov_b32 m0, s17
	s_nop 0
	global_load_lds_dwordx4 v180, s[30:31]
	s_nop 0
	s_mov_b32 m0, s53
	s_nop 0
	global_load_lds_dwordx4 v182, s[30:31]
	s_nop 0
	s_mov_b32 m0, s96
	s_nop 0
	global_load_lds_dwordx4 v0, s[56:57]
	s_nop 0
	s_mov_b32 m0, s97
	s_nop 0
	global_load_lds_dwordx4 v181, s[56:57]
	s_waitcnt vmcnt(8)
	s_waitcnt lgkmcnt(0)
	s_nop 0
	s_barrier
	s_setprio 1
	s_waitcnt lgkmcnt(0)
	v_mfma_f32_16x16x32_bf16 v[62:65], v[74:77], v[162:165], v[62:65]
	v_mfma_f32_16x16x32_bf16 v[62:65], v[94:97], v[166:169], v[62:65]
	v_mfma_f32_16x16x32_bf16 v[58:61], v[114:117], v[162:165], v[58:61]
	v_mfma_f32_16x16x32_bf16 v[58:61], v[134:137], v[166:169], v[58:61]
	v_mfma_f32_16x16x32_bf16 v[54:57], v[146:149], v[162:165], v[54:57]
	v_mfma_f32_16x16x32_bf16 v[54:57], v[150:153], v[166:169], v[54:57]
	v_mfma_f32_16x16x32_bf16 v[50:53], v[154:157], v[162:165], v[50:53]
	v_mfma_f32_16x16x32_bf16 v[50:53], v[158:161], v[166:169], v[50:53]
	v_mfma_f32_16x16x32_bf16 v[34:37], v[154:157], v[170:173], v[34:37]
	v_mfma_f32_16x16x32_bf16 v[34:37], v[158:161], v[174:177], v[34:37]
	v_mfma_f32_16x16x32_bf16 v[38:41], v[146:149], v[170:173], v[38:41]
	v_mfma_f32_16x16x32_bf16 v[38:41], v[150:153], v[174:177], v[38:41]
	v_mfma_f32_16x16x32_bf16 v[42:45], v[114:117], v[170:173], v[42:45]
	v_mfma_f32_16x16x32_bf16 v[42:45], v[134:137], v[174:177], v[42:45]
	v_mfma_f32_16x16x32_bf16 v[46:49], v[74:77], v[170:173], v[46:49]
	v_mfma_f32_16x16x32_bf16 v[46:49], v[94:97], v[174:177], v[46:49]
	v_mfma_f32_16x16x32_bf16 v[30:33], v[74:77], v[188:191], v[30:33]
	v_mfma_f32_16x16x32_bf16 v[30:33], v[94:97], v[202:205], v[30:33]
	v_mfma_f32_16x16x32_bf16 v[26:29], v[114:117], v[188:191], v[26:29]
	v_mfma_f32_16x16x32_bf16 v[26:29], v[134:137], v[202:205], v[26:29]
	v_mfma_f32_16x16x32_bf16 v[22:25], v[146:149], v[188:191], v[22:25]
	v_mfma_f32_16x16x32_bf16 v[22:25], v[150:153], v[202:205], v[22:25]
	v_mfma_f32_16x16x32_bf16 v[18:21], v[154:157], v[188:191], v[18:21]
	v_mfma_f32_16x16x32_bf16 v[18:21], v[158:161], v[202:205], v[18:21]
	v_mfma_f32_16x16x32_bf16 v[2:5], v[154:157], v[206:209], v[2:5]
	v_mfma_f32_16x16x32_bf16 v[2:5], v[158:161], v[210:213], v[2:5]
	v_mfma_f32_16x16x32_bf16 v[6:9], v[146:149], v[206:209], v[6:9]
	v_mfma_f32_16x16x32_bf16 v[6:9], v[150:153], v[210:213], v[6:9]
	v_mfma_f32_16x16x32_bf16 v[10:13], v[114:117], v[206:209], v[10:13]
	v_mfma_f32_16x16x32_bf16 v[10:13], v[134:137], v[210:213], v[10:13]
	v_mfma_f32_16x16x32_bf16 v[14:17], v[74:77], v[206:209], v[14:17]
	v_mfma_f32_16x16x32_bf16 v[14:17], v[94:97], v[210:213], v[14:17]
	s_setprio 0
	s_barrier
	s_add_i32 s50, s50, 2
	s_add_u32 s41, s41, 0x100
	s_addc_u32 s49, s49, 0
	s_add_u32 s92, s92, 0x100
	s_addc_u32 s93, s93, 0
	s_cmp_gt_u32 s50, 13
	s_cbranch_scc0 .LBB0_306
	v_readlane_b32 s4, v254, 46
	v_readlane_b32 s5, v254, 47
	s_and_b64 vcc, exec, s[4:5]
	s_cbranch_vccz .LBB0_309
	s_barrier

; #define PG8_STAGE(bufoff, gbase, voff) do { _Pragma("unroll") for (int _i = 0; _i < 2; ++_i) { \
;         const unsigned _m0 = ldsb + (unsigned)((bufoff) + _i * 8192); const char* _gb = (const char*)(gbase); \
;         asm volatile("s_mov_b32 m0, %0\n\ts_nop 0\n\tglobal_load_lds_dwordx4 %1, %2" :: "s"(_m0), "v"((voff)[_i]), "s"(_gb) : "m0", "memory"); } } while (0)
; #define PG8_LDA(dst, b, h) do { _Pragma("unroll") for (int m = 0; m < 4; ++m) _Pragma("unroll") for (int k = 0; k < 2; ++k) dst[m][k] = *(const LAS bf16x8*)(lds + PG8_SA(b, h) + aoff + m * 2048 + k * 1024); } while (0)
; #define PG8_LDB(dst, b, h) do { _Pragma("unroll") for (int n = 0; n < 2; ++n) _Pragma("unroll") for (int k = 0; k < 2; ++k) dst[n][k] = *(const LAS bf16x8*)(lds + PG8_SB(b, h) + boff + n * 2048 + k * 1024); } while (0)
; #define PG8_MMA(ai, bj, At, Bt) do { __builtin_amdgcn_s_setprio(1); _Pragma("unroll") for (int m = 0; m < 4; ++m) _Pragma("unroll") for (int n = 0; n < 2; ++n) _Pragma("unroll") for (int k = 0; k < 2; ++k) \
;         acc[ai][bj][m][n] = __builtin_amdgcn_mfma_f32_16x16x32_bf16(Bt[n][k], At[m][k], acc[ai][bj][m][n], 0, 0, 0); __builtin_amdgcn_s_setprio(0); } while (0)
; #define PG8_WAIT_V(n) asm volatile("s_waitcnt vmcnt(" #n ")" ::: "memory")
; #define PG8_WAIT_L(n) asm volatile("s_waitcnt lgkmcnt(" #n ")" ::: "memory")
; template <class Epi, bool ALIGN_EPI>
; __device__ __forceinline__ void gemm_phase(LAS unsigned char* lds, const Gemm g, const StaticOrder& S, const Epi& E) {
;     ...
;         for (int t = 0; t < nt; t += 2) {
;             const bool last = (t == nt - 2);
;             const char* a1 = cA + (size_t)(t + 1) * kstep;
;             const char* a2 = last ? nA : cA + (size_t)(t + 2) * kstep; const char* b2 = last ? nB : cB + (size_t)(t + 2) * kstep;
;             const char* a3 = a2 + kstep; const char* b3 = b2 + kstep;
;             PG8_LDB(B0, 0, 0); PG8_LDB(B1, 0, 1); PG8_SCHED; PG8_LDA(At, 0, 0); PG8_STAGE(PG8_SA(1, 1), a1 + hstepA, voffA);
;             PG8_WAIT_V(8); PG8_WAIT_L(0); PG8_BAR; PG8_MMA(0, 0, At, B0); PG8_MMA(0, 1, At, B1); PG8_BAR; PG8_SCHED;
;             PG8_LDA(At, 0, 1); PG8_STAGE(PG8_SB(0, 0), b2, voffB); PG8_STAGE(PG8_SB(0, 1), b2 + hstepB, voffB); PG8_STAGE(PG8_SA(0, 0), a2, voffA);
;             PG8_WAIT_V(8); PG8_WAIT_L(0); PG8_BAR; PG8_MMA(1, 0, At, B0); PG8_MMA(1, 1, At, B1); PG8_BAR; PG8_SCHED;
.LBB0_349:
	v_add_u32_e32 v0, 0x10000, v187
	ds_read_b128 v[34:37], v0
	ds_read_b128 v[54:57], v0 offset:1024
	ds_read_b128 v[74:77], v0 offset:2048
	ds_read_b128 v[94:97], v0 offset:3072
	v_add_u32_e32 v0, 0x14000, v187
	ds_read_b128 v[110:113], v0
	ds_read_b128 v[126:129], v0 offset:1024
	ds_read_b128 v[146:149], v0 offset:2048
	ds_read_b128 v[160:163], v0 offset:3072
	s_add_u32 s38, s36, 0xfffc0080
	s_addc_u32 s39, s37, -1
	s_cmp_eq_u32 s50, 12
	s_cselect_b32 s54, s5, s38
	s_cselect_b32 s55, s4, s39
	s_cselect_b32 s48, s27, s29
	s_cselect_b32 s49, s11, s41
	s_add_u32 s38, s54, 0x80
	s_addc_u32 s39, s55, 0
	ds_read_b128 v[164:167], v188
	ds_read_b128 v[168:171], v188 offset:1024
	ds_read_b128 v[172:175], v188 offset:2048
	ds_read_b128 v[176:179], v188 offset:3072
	ds_read_b128 v[190:193], v188 offset:4096
	ds_read_b128 v[202:205], v188 offset:5120
	ds_read_b128 v[206:209], v188 offset:6144
	ds_read_b128 v[210:213], v188 offset:7168
	s_mov_b32 m0, s91
	s_nop 0
	global_load_lds_dwordx4 v180, s[36:37]
	s_nop 0
	s_mov_b32 m0, s93
	s_nop 0
	global_load_lds_dwordx4 v182, s[36:37]
	s_waitcnt vmcnt(8)
	s_waitcnt lgkmcnt(0)
	s_nop 0
	s_barrier
	s_setprio 1
	s_waitcnt lgkmcnt(0)
	v_mfma_f32_16x16x32_bf16 v[154:157], v[34:37], v[164:167], v[154:157]
	v_mfma_f32_16x16x32_bf16 v[154:157], v[54:57], v[168:171], v[154:157]
	v_mfma_f32_16x16x32_bf16 v[150:153], v[74:77], v[164:167], v[150:153]
	v_mfma_f32_16x16x32_bf16 v[150:153], v[94:97], v[168:171], v[150:153]
	v_mfma_f32_16x16x32_bf16 v[142:145], v[110:113], v[164:167], v[142:145]
	v_mfma_f32_16x16x32_bf16 v[142:145], v[126:129], v[168:171], v[142:145]
	v_mfma_f32_16x16x32_bf16 v[138:141], v[146:149], v[164:167], v[138:141]
	v_mfma_f32_16x16x32_bf16 v[138:141], v[160:163], v[168:171], v[138:141]
	v_mfma_f32_16x16x32_bf16 v[118:121], v[146:149], v[172:175], v[118:121]
	v_mfma_f32_16x16x32_bf16 v[118:121], v[160:163], v[176:179], v[118:121]
	v_mfma_f32_16x16x32_bf16 v[122:125], v[110:113], v[172:175], v[122:125]
	v_mfma_f32_16x16x32_bf16 v[122:125], v[126:129], v[176:179], v[122:125]
	v_mfma_f32_16x16x32_bf16 v[130:133], v[74:77], v[172:175], v[130:133]
	v_mfma_f32_16x16x32_bf16 v[130:133], v[94:97], v[176:179], v[130:133]
	v_mfma_f32_16x16x32_bf16 v[134:137], v[34:37], v[172:175], v[134:137]
	v_mfma_f32_16x16x32_bf16 v[134:137], v[54:57], v[176:179], v[134:137]
	v_mfma_f32_16x16x32_bf16 v[114:117], v[34:37], v[190:193], v[114:117]
	v_mfma_f32_16x16x32_bf16 v[114:117], v[54:57], v[202:205], v[114:117]
	v_mfma_f32_16x16x32_bf16 v[106:109], v[74:77], v[190:193], v[106:109]
	v_mfma_f32_16x16x32_bf16 v[106:109], v[94:97], v[202:205], v[106:109]
	v_mfma_f32_16x16x32_bf16 v[102:105], v[110:113], v[190:193], v[102:105]
	v_mfma_f32_16x16x32_bf16 v[102:105], v[126:129], v[202:205], v[102:105]
	v_mfma_f32_16x16x32_bf16 v[98:101], v[146:149], v[190:193], v[98:101]
	v_mfma_f32_16x16x32_bf16 v[98:101], v[160:163], v[202:205], v[98:101]
	v_mfma_f32_16x16x32_bf16 v[78:81], v[146:149], v[206:209], v[78:81]
	v_mfma_f32_16x16x32_bf16 v[78:81], v[160:163], v[210:213], v[78:81]
	v_mfma_f32_16x16x32_bf16 v[82:85], v[110:113], v[206:209], v[82:85]
	v_mfma_f32_16x16x32_bf16 v[82:85], v[126:129], v[210:213], v[82:85]
	v_mfma_f32_16x16x32_bf16 v[86:89], v[74:77], v[206:209], v[86:89]
	v_mfma_f32_16x16x32_bf16 v[86:89], v[94:97], v[210:213], v[86:89]
	v_mfma_f32_16x16x32_bf16 v[90:93], v[34:37], v[206:209], v[90:93]
	v_mfma_f32_16x16x32_bf16 v[90:93], v[54:57], v[210:213], v[90:93]
	s_setprio 0
	s_barrier
	ds_read_b128 v[164:167], v188 offset:16384
	ds_read_b128 v[168:171], v188 offset:17408
	ds_read_b128 v[172:175], v188 offset:18432
	ds_read_b128 v[176:179], v188 offset:19456
	ds_read_b128 v[190:193], v188 offset:20480
	ds_read_b128 v[202:205], v188 offset:21504
	ds_read_b128 v[206:209], v188 offset:22528
	ds_read_b128 v[210:213], v188 offset:23552
	s_mov_b32 m0, s43
	s_nop 0
	global_load_lds_dwordx4 v181, s[48:49]
	s_add_u32 s96, s48, 0x40000
	s_mov_b32 m0, s44
	s_nop 0
	global_load_lds_dwordx4 v183, s[48:49]
	s_addc_u32 s97, s49, 0
	s_mov_b32 m0, s45
	s_nop 0
	global_load_lds_dwordx4 v181, s[96:97]
	s_nop 0
	s_mov_b32 m0, s56
	s_nop 0
	global_load_lds_dwordx4 v183, s[96:97]
	s_nop 0
	s_mov_b32 m0, s42
	s_nop 0
	global_load_lds_dwordx4 v180, s[54:55]
	s_nop 0
	s_mov_b32 m0, s57
	s_nop 0
	global_load_lds_dwordx4 v182, s[54:55]
	s_waitcnt vmcnt(8)
	s_waitcnt lgkmcnt(0)
	s_nop 0
	s_barrier
	s_setprio 1
	s_waitcnt lgkmcnt(0)
	v_mfma_f32_16x16x32_bf16 v[70:73], v[34:37], v[164:167], v[70:73]
	v_mfma_f32_16x16x32_bf16 v[66:69], v[74:77], v[164:167], v[66:69]
	v_mfma_f32_16x16x32_bf16 v[50:53], v[34:37], v[172:175], v[50:53]
	v_mfma_f32_16x16x32_bf16 v[46:49], v[74:77], v[172:175], v[46:49]
	v_mfma_f32_16x16x32_bf16 v[30:33], v[34:37], v[190:193], v[30:33]
	v_mfma_f32_16x16x32_bf16 v[26:29], v[74:77], v[190:193], v[26:29]
	v_mfma_f32_16x16x32_bf16 v[14:17], v[34:37], v[206:209], v[14:17]
	v_mfma_f32_16x16x32_bf16 v[10:13], v[74:77], v[206:209], v[10:13]
	v_mfma_f32_16x16x32_bf16 v[70:73], v[54:57], v[168:171], v[70:73]
	v_mfma_f32_16x16x32_bf16 v[66:69], v[94:97], v[168:171], v[66:69]
	v_mfma_f32_16x16x32_bf16 v[50:53], v[54:57], v[176:179], v[50:53]
	v_mfma_f32_16x16x32_bf16 v[46:49], v[94:97], v[176:179], v[46:49]
	v_mfma_f32_16x16x32_bf16 v[30:33], v[54:57], v[202:205], v[30:33]
	v_mfma_f32_16x16x32_bf16 v[26:29], v[94:97], v[202:205], v[26:29]
	v_mfma_f32_16x16x32_bf16 v[14:17], v[54:57], v[210:213], v[14:17]
	v_mfma_f32_16x16x32_bf16 v[10:13], v[94:97], v[210:213], v[10:13]
	s_setprio 0
	s_setprio 1
	v_mfma_f32_16x16x32_bf16 v[42:45], v[110:113], v[172:175], v[42:45]
	v_mfma_f32_16x16x32_bf16 v[38:41], v[146:149], v[172:175], v[38:41]
	v_mfma_f32_16x16x32_bf16 v[22:25], v[110:113], v[190:193], v[22:25]
	v_mfma_f32_16x16x32_bf16 v[18:21], v[146:149], v[190:193], v[18:21]
	v_mfma_f32_16x16x32_bf16 v[6:9], v[110:113], v[206:209], v[6:9]
	v_mfma_f32_16x16x32_bf16 v[2:5], v[146:149], v[206:209], v[2:5]
	v_mfma_f32_16x16x32_bf16 v[34:37], v[110:113], v[164:167], v[62:65]
	v_mfma_f32_16x16x32_bf16 v[54:57], v[146:149], v[164:167], v[58:61]
	v_mfma_f32_16x16x32_bf16 v[42:45], v[126:129], v[176:179], v[42:45]
	v_mfma_f32_16x16x32_bf16 v[38:41], v[160:163], v[176:179], v[38:41]
	v_mfma_f32_16x16x32_bf16 v[22:25], v[126:129], v[202:205], v[22:25]
	v_mfma_f32_16x16x32_bf16 v[18:21], v[160:163], v[202:205], v[18:21]
	v_mfma_f32_16x16x32_bf16 v[6:9], v[126:129], v[210:213], v[6:9]
	v_mfma_f32_16x16x32_bf16 v[2:5], v[160:163], v[210:213], v[2:5]
	v_mfma_f32_16x16x32_bf16 v[34:37], v[126:129], v[168:171], v[34:37]
	v_mfma_f32_16x16x32_bf16 v[54:57], v[160:163], v[168:171], v[54:57]
	s_setprio 0
	s_barrier
; #define PG8_STAGE(bufoff, gbase, voff) do { _Pragma("unroll") for (int _i = 0; _i < 2; ++_i) { \
;         const unsigned _m0 = ldsb + (unsigned)((bufoff) + _i * 8192); const char* _gb = (const char*)(gbase); \
;         asm volatile("s_mov_b32 m0, %0\n\ts_nop 0\n\tglobal_load_lds_dwordx4 %1, %2" :: "s"(_m0), "v"((voff)[_i]), "s"(_gb) : "m0", "memory"); } } while (0)
; #define PG8_LDA(dst, b, h) do { _Pragma("unroll") for (int m = 0; m < 4; ++m) _Pragma("unroll") for (int k = 0; k < 2; ++k) dst[m][k] = *(const LAS bf16x8*)(lds + PG8_SA(b, h) + aoff + m * 2048 + k * 1024); } while (0)
; #define PG8_LDB(dst, b, h) do { _Pragma("unroll") for (int n = 0; n < 2; ++n) _Pragma("unroll") for (int k = 0; k < 2; ++k) dst[n][k] = *(const LAS bf16x8*)(lds + PG8_SB(b, h) + boff + n * 2048 + k * 1024); } while (0)
; #define PG8_MMA(ai, bj, At, Bt) do { __builtin_amdgcn_s_setprio(1); _Pragma("unroll") for (int m = 0; m < 4; ++m) _Pragma("unroll") for (int n = 0; n < 2; ++n) _Pragma("unroll") for (int k = 0; k < 2; ++k) \
;         acc[ai][bj][m][n] = __builtin_amdgcn_mfma_f32_16x16x32_bf16(Bt[n][k], At[m][k], acc[ai][bj][m][n], 0, 0, 0); __builtin_amdgcn_s_setprio(0); } while (0)
; #define PG8_WAIT_V(n) asm volatile("s_waitcnt vmcnt(" #n ")" ::: "memory")
; #define PG8_WAIT_L(n) asm volatile("s_waitcnt lgkmcnt(" #n ")" ::: "memory")
; #define PG8_BAR __builtin_amdgcn_s_barrier()
; #define PG8_SCHED __builtin_amdgcn_sched_barrier(0)
; template <class Epi, bool ALIGN_EPI>
; __device__ __forceinline__ void gemm_phase(LAS unsigned char* lds, const Gemm g, const StaticOrder& S, const Epi& E) {
;     ...
;             PG8_LDB(B0, 1, 0); PG8_LDB(B1, 1, 1); PG8_SCHED; PG8_LDA(At, 1, 0); PG8_STAGE(PG8_SA(0, 1), a2 + hstepA, voffA);
;             PG8_WAIT_V(8); PG8_WAIT_L(0); PG8_BAR; PG8_MMA(0, 0, At, B0); PG8_MMA(0, 1, At, B1); PG8_BAR; PG8_SCHED;
;             PG8_LDA(At, 1, 1); PG8_STAGE(PG8_SB(1, 0), b3, voffB); PG8_STAGE(PG8_SB(1, 1), b3 + hstepB, voffB); PG8_STAGE(PG8_SA(1, 0), a3, voffA);
;             PG8_WAIT_V(8); PG8_WAIT_L(0); PG8_BAR; PG8_MMA(1, 0, At, B0); PG8_MMA(1, 1, At, B1); PG8_BAR; PG8_SCHED;
;         }
;         if constexpr (ALIGN_EPI) { if (wr == 0) PG8_BAR; }
	v_add_u32_e32 v0, 0x18000, v187
	ds_read_b128 v[58:61], v0
	ds_read_b128 v[62:65], v0 offset:1024
	ds_read_b128 v[74:77], v0 offset:2048
	ds_read_b128 v[94:97], v0 offset:3072
	v_add_u32_e32 v0, 0x1c000, v187
	ds_read_b128 v[110:113], v0
	ds_read_b128 v[126:129], v0 offset:1024
	ds_read_b128 v[146:149], v0 offset:2048
	ds_read_b128 v[160:163], v0 offset:3072
	ds_read_b128 v[164:167], v188 offset:32768
	ds_read_b128 v[168:171], v188 offset:33792
	ds_read_b128 v[172:175], v188 offset:34816
	ds_read_b128 v[176:179], v188 offset:35840
	ds_read_b128 v[190:193], v188 offset:36864
	ds_read_b128 v[202:205], v188 offset:37888
	ds_read_b128 v[206:209], v188 offset:38912
	ds_read_b128 v[210:213], v188 offset:39936
	s_add_u32 s54, s54, 0x40000
	s_addc_u32 s55, s55, 0
	s_mov_b32 m0, s58
	s_nop 0
	global_load_lds_dwordx4 v180, s[54:55]
	s_nop 0
	s_mov_b32 m0, s59
	s_nop 0
	global_load_lds_dwordx4 v182, s[54:55]
	s_waitcnt vmcnt(8)
	s_waitcnt lgkmcnt(0)
	s_nop 0
	s_barrier
	s_setprio 1
	s_waitcnt lgkmcnt(0)
	v_mfma_f32_16x16x32_bf16 v[154:157], v[58:61], v[164:167], v[154:157]
	v_mfma_f32_16x16x32_bf16 v[154:157], v[62:65], v[168:171], v[154:157]
	v_mfma_f32_16x16x32_bf16 v[150:153], v[74:77], v[164:167], v[150:153]
	v_mfma_f32_16x16x32_bf16 v[150:153], v[94:97], v[168:171], v[150:153]
	v_mfma_f32_16x16x32_bf16 v[142:145], v[110:113], v[164:167], v[142:145]
	v_mfma_f32_16x16x32_bf16 v[142:145], v[126:129], v[168:171], v[142:145]
	v_mfma_f32_16x16x32_bf16 v[138:141], v[146:149], v[164:167], v[138:141]
	v_mfma_f32_16x16x32_bf16 v[138:141], v[160:163], v[168:171], v[138:141]
	v_mfma_f32_16x16x32_bf16 v[118:121], v[146:149], v[172:175], v[118:121]
	v_mfma_f32_16x16x32_bf16 v[118:121], v[160:163], v[176:179], v[118:121]
	v_mfma_f32_16x16x32_bf16 v[122:125], v[110:113], v[172:175], v[122:125]
	v_mfma_f32_16x16x32_bf16 v[122:125], v[126:129], v[176:179], v[122:125]
	v_mfma_f32_16x16x32_bf16 v[130:133], v[74:77], v[172:175], v[130:133]
	v_mfma_f32_16x16x32_bf16 v[130:133], v[94:97], v[176:179], v[130:133]
	v_mfma_f32_16x16x32_bf16 v[134:137], v[58:61], v[172:175], v[134:137]
	v_mfma_f32_16x16x32_bf16 v[134:137], v[62:65], v[176:179], v[134:137]
	v_mfma_f32_16x16x32_bf16 v[114:117], v[58:61], v[190:193], v[114:117]
	v_mfma_f32_16x16x32_bf16 v[114:117], v[62:65], v[202:205], v[114:117]
	v_mfma_f32_16x16x32_bf16 v[106:109], v[74:77], v[190:193], v[106:109]
	v_mfma_f32_16x16x32_bf16 v[106:109], v[94:97], v[202:205], v[106:109]
	v_mfma_f32_16x16x32_bf16 v[102:105], v[110:113], v[190:193], v[102:105]
	v_mfma_f32_16x16x32_bf16 v[102:105], v[126:129], v[202:205], v[102:105]
	v_mfma_f32_16x16x32_bf16 v[98:101], v[146:149], v[190:193], v[98:101]
	v_mfma_f32_16x16x32_bf16 v[98:101], v[160:163], v[202:205], v[98:101]
	v_mfma_f32_16x16x32_bf16 v[78:81], v[146:149], v[206:209], v[78:81]
	v_mfma_f32_16x16x32_bf16 v[78:81], v[160:163], v[210:213], v[78:81]
	v_mfma_f32_16x16x32_bf16 v[82:85], v[110:113], v[206:209], v[82:85]
	v_mfma_f32_16x16x32_bf16 v[82:85], v[126:129], v[210:213], v[82:85]
	v_mfma_f32_16x16x32_bf16 v[86:89], v[74:77], v[206:209], v[86:89]
	v_mfma_f32_16x16x32_bf16 v[86:89], v[94:97], v[210:213], v[86:89]
	v_mfma_f32_16x16x32_bf16 v[90:93], v[58:61], v[206:209], v[90:93]
	v_mfma_f32_16x16x32_bf16 v[90:93], v[62:65], v[210:213], v[90:93]
	s_setprio 0
	s_barrier
	ds_read_b128 v[164:167], v188 offset:49152
	ds_read_b128 v[168:171], v188 offset:50176
	ds_read_b128 v[172:175], v188 offset:51200
	ds_read_b128 v[176:179], v188 offset:52224
	ds_read_b128 v[190:193], v188 offset:53248
	ds_read_b128 v[202:205], v188 offset:54272
	ds_read_b128 v[206:209], v188 offset:55296
	ds_read_b128 v[210:213], v188 offset:56320
	s_add_u32 s54, s48, 0x80
	s_addc_u32 s55, s49, 0
	s_mov_b32 m0, s17
	s_nop 0
	global_load_lds_dwordx4 v181, s[54:55]
	s_add_u32 s48, s48, 0x40080
	s_mov_b32 m0, s60
	s_nop 0
	global_load_lds_dwordx4 v183, s[54:55]
	s_addc_u32 s49, s49, 0
	s_mov_b32 m0, s89
	s_nop 0
	global_load_lds_dwordx4 v181, s[48:49]
	s_nop 0
	s_mov_b32 m0, s90
	s_nop 0
	global_load_lds_dwordx4 v183, s[48:49]
	s_nop 0
	s_mov_b32 m0, s61
	s_nop 0
	global_load_lds_dwordx4 v180, s[38:39]
	s_nop 0
	s_mov_b32 m0, s88
	s_nop 0
	global_load_lds_dwordx4 v182, s[38:39]
	s_waitcnt vmcnt(8)
	s_waitcnt lgkmcnt(0)
	s_barrier
	s_setprio 1
	s_waitcnt lgkmcnt(0)
	v_mfma_f32_16x16x32_bf16 v[70:73], v[58:61], v[164:167], v[70:73]
	v_mfma_f32_16x16x32_bf16 v[66:69], v[74:77], v[164:167], v[66:69]
	v_mfma_f32_16x16x32_bf16 v[50:53], v[58:61], v[172:175], v[50:53]
	v_mfma_f32_16x16x32_bf16 v[46:49], v[74:77], v[172:175], v[46:49]
	v_mfma_f32_16x16x32_bf16 v[30:33], v[58:61], v[190:193], v[30:33]
	v_mfma_f32_16x16x32_bf16 v[26:29], v[74:77], v[190:193], v[26:29]
	v_mfma_f32_16x16x32_bf16 v[14:17], v[58:61], v[206:209], v[14:17]
	v_mfma_f32_16x16x32_bf16 v[10:13], v[74:77], v[206:209], v[10:13]
	v_mfma_f32_16x16x32_bf16 v[70:73], v[62:65], v[168:171], v[70:73]
	v_mfma_f32_16x16x32_bf16 v[66:69], v[94:97], v[168:171], v[66:69]
	v_mfma_f32_16x16x32_bf16 v[50:53], v[62:65], v[176:179], v[50:53]
	v_mfma_f32_16x16x32_bf16 v[46:49], v[94:97], v[176:179], v[46:49]
	v_mfma_f32_16x16x32_bf16 v[30:33], v[62:65], v[202:205], v[30:33]
	v_mfma_f32_16x16x32_bf16 v[26:29], v[94:97], v[202:205], v[26:29]
	v_mfma_f32_16x16x32_bf16 v[14:17], v[62:65], v[210:213], v[14:17]
	v_mfma_f32_16x16x32_bf16 v[10:13], v[94:97], v[210:213], v[10:13]
	s_setprio 0
	s_setprio 1
	v_mfma_f32_16x16x32_bf16 v[34:37], v[110:113], v[164:167], v[34:37]
	v_mfma_f32_16x16x32_bf16 v[62:65], v[126:129], v[168:171], v[34:37]
	v_mfma_f32_16x16x32_bf16 v[34:37], v[146:149], v[164:167], v[54:57]
	v_mfma_f32_16x16x32_bf16 v[58:61], v[160:163], v[168:171], v[34:37]
	v_mfma_f32_16x16x32_bf16 v[34:37], v[110:113], v[172:175], v[42:45]
	v_mfma_f32_16x16x32_bf16 v[42:45], v[126:129], v[176:179], v[34:37]
	v_mfma_f32_16x16x32_bf16 v[34:37], v[146:149], v[172:175], v[38:41]
	v_mfma_f32_16x16x32_bf16 v[22:25], v[110:113], v[190:193], v[22:25]
	v_mfma_f32_16x16x32_bf16 v[18:21], v[146:149], v[190:193], v[18:21]
	v_mfma_f32_16x16x32_bf16 v[6:9], v[110:113], v[206:209], v[6:9]
	v_mfma_f32_16x16x32_bf16 v[2:5], v[146:149], v[206:209], v[2:5]
	v_mfma_f32_16x16x32_bf16 v[38:41], v[160:163], v[176:179], v[34:37]
	v_mfma_f32_16x16x32_bf16 v[22:25], v[126:129], v[202:205], v[22:25]
	v_mfma_f32_16x16x32_bf16 v[18:21], v[160:163], v[202:205], v[18:21]
	v_mfma_f32_16x16x32_bf16 v[6:9], v[126:129], v[210:213], v[6:9]
	v_mfma_f32_16x16x32_bf16 v[2:5], v[160:163], v[210:213], v[2:5]
	s_setprio 0
	s_barrier
	s_add_i32 s50, s50, 2
	s_add_u32 s29, s29, 0x100
	s_addc_u32 s41, s41, 0
	s_add_u32 s36, s36, 0x100
	s_addc_u32 s37, s37, 0
	s_cmp_gt_u32 s50, 13
	s_cbranch_scc0 .LBB0_349
	s_and_b64 vcc, exec, s[24:25]
	s_cbranch_vccz .LBB0_352
	s_barrier
